# plus EpiResid epilogue load ladder de-serialised (4 base loads per row group issued together, counted vmcnt)
# speedup vs baseline: 1.0055x; 1.0055x over previous
; __device__ __forceinline__ unsigned cvt_pk_bf16(float lo, float hi) { unsigned r; asm volatile("v_cvt_pk_bf16_f32 %0, %1, %2" : "=v"(r) : "v"(lo), "v"(hi)); return r; }
;     __device__ __forceinline__ void operator()(const f32x4 (&acc)[2][2][4][2], const Unit& u, int wr, int wc, int fr, int fq) const {
;     ...
;             for (int m = 0; m < 4; ++m) { const int row = row0 + ai * HALF + m * 16; const size_t off = (size_t)row * D + col0;
;                 float ssq = 0.f;
; #pragma unroll
;                 for (int bj = 0; bj < 2; ++bj)
; #pragma unroll
;                     for (int n = 0; n < 2; ++n) { const f32x4 bs = *(const f32x4*)(base + off + bj * HALF + n * 16);
;                         const f32x4 o = bs + gv[bj][n] * acc[ai][bj][m][n];
;                         *(f32x4*)(out + off + bj * HALF + n * 16) = o;
;                         if (FOLD) { ssq += (o.x * o.x + o.y * o.y) + (o.z * o.z + o.w * o.w); const f32x4 q = o * sv[bj][n];
;                             u32x2 w; w.x = cvt_pk_bf16(q.x, q.y); w.y = cvt_pk_bf16(q.z, q.w); *(u32x2*)(U2 + off + bj * HALF + n * 16) = w; } }
;                 if (FOLD) { ssq += __shfl_xor(ssq, 16); ssq += __shfl_xor(ssq, 32);
;                     if (fq == 0) part[(size_t)row * 16 + (u.pn & 3) * 4 + wc] = ssq; } }
.LBB0_429:
	s_or_b64 exec, exec, s[36:37]
	v_or_b32_e32 v164, 16, v146
	s_waitcnt lgkmcnt(0)
	v_ashrrev_i32_e32 v165, 31, v164
	v_lshlrev_b64 v[176:177], 10, v[164:165]
	v_lshl_add_u64 v[180:181], v[176:177], 0, v[144:145]
	v_readlane_b32 s72, v248, 11
	v_lshlrev_b64 v[182:183], 2, v[180:181]
	v_readlane_b32 s73, v248, 12
	v_readlane_b32 s74, v248, 13
	v_readlane_b32 s75, v248, 14
	v_lshl_add_u64 v[184:185], s[72:73], 0, v[182:183]
	global_load_dwordx4 v[236:239], v[184:185], off
	global_load_dwordx4 v[240:243], v[184:185], off offset:64
	global_load_dwordx4 v[244:247], v[184:185], off offset:512
	global_load_dwordx4 v[176:179], v[184:185], off offset:576
	v_readlane_b32 s76, v248, 15
	v_readlane_b32 s77, v248, 16
	v_readlane_b32 s78, v248, 17
	v_readlane_b32 s79, v248, 18
	v_readlane_b32 s36, v249, 43
	v_readlane_b32 s72, v248, 0
	v_readlane_b32 s37, v249, 44
	v_readlane_b32 s78, v248, 6
	v_readlane_b32 s79, v248, 7
	v_lshl_add_u64 v[180:181], v[180:181], 1, s[36:37]
	v_readlane_b32 s80, v248, 19
	v_lshl_add_u64 v[182:183], s[78:79], 0, v[182:183]
	v_readlane_b32 s81, v248, 20
	v_readlane_b32 s82, v248, 21
	v_readlane_b32 s83, v248, 22
	v_readlane_b32 s84, v248, 23
	v_readlane_b32 s85, v248, 24
	v_readlane_b32 s86, v248, 25
	v_readlane_b32 s87, v248, 26
	v_readlane_b32 s73, v248, 1
	v_readlane_b32 s74, v248, 2
	v_readlane_b32 s75, v248, 3
	v_readlane_b32 s76, v248, 4
	v_readlane_b32 s77, v248, 5
	s_waitcnt vmcnt(3)
	v_pk_fma_f32 v[108:109], v[108:109], v[158:159], v[236:237]
	v_pk_fma_f32 v[110:111], v[110:111], v[156:157], v[238:239]
	v_pk_mul_f32 v[238:239], v[162:163], v[108:109]
	global_store_dwordx4 v[182:183], v[108:111], off
	v_pk_mul_f32 v[236:237], v[160:161], v[110:111]
	v_cvt_pk_bf16_f32 v238, v238, v239
	s_nop 0
	v_cvt_pk_bf16_f32 v239, v236, v237
	global_store_dwordx2 v[180:181], v[238:239], off
	v_mul_f32_e32 v109, v109, v109
	v_mul_f32_e32 v111, v111, v111
	v_fmac_f32_e32 v109, v108, v108
	v_fmac_f32_e32 v111, v110, v110
	v_add_f32_e32 v108, v109, v111
	s_waitcnt vmcnt(4)
	v_pk_fma_f32 v[104:105], v[104:105], v[150:151], v[240:241]
	v_pk_fma_f32 v[106:107], v[106:107], v[154:155], v[242:243]
	v_pk_mul_f32 v[242:243], v[126:127], v[104:105]
	global_store_dwordx4 v[182:183], v[104:107], off offset:64
	v_pk_mul_f32 v[240:241], v[124:125], v[106:107]
	v_cvt_pk_bf16_f32 v242, v242, v243
	s_nop 0
	v_cvt_pk_bf16_f32 v243, v240, v241
	global_store_dwordx2 v[180:181], v[242:243], off offset:32
	v_mul_f32_e32 v105, v105, v105
	v_mul_f32_e32 v107, v107, v107
	v_fmac_f32_e32 v105, v104, v104
	v_fmac_f32_e32 v107, v106, v106
	v_add_f32_e32 v104, v105, v107
	v_add_f32_e32 v104, v108, v104
	s_waitcnt vmcnt(5)
	v_pk_fma_f32 v[100:101], v[100:101], v[148:149], v[244:245]
	v_pk_fma_f32 v[102:103], v[102:103], v[152:153], v[246:247]
	v_pk_mul_f32 v[246:247], v[122:123], v[100:101]
	global_store_dwordx4 v[182:183], v[100:103], off offset:512
	v_pk_mul_f32 v[244:245], v[120:121], v[102:103]
	v_cvt_pk_bf16_f32 v246, v246, v247
	s_nop 0
	v_cvt_pk_bf16_f32 v247, v244, v245
	global_store_dwordx2 v[180:181], v[246:247], off offset:256
	v_mul_f32_e32 v101, v101, v101
	v_mul_f32_e32 v103, v103, v103
	v_fmac_f32_e32 v101, v100, v100
	v_fmac_f32_e32 v103, v102, v102
	v_add_f32_e32 v100, v101, v103
	v_add_f32_e32 v102, v104, v100
	s_waitcnt vmcnt(6)
	v_pk_fma_f32 v[100:101], v[98:99], v[118:119], v[178:179]
	v_pk_fma_f32 v[98:99], v[96:97], v[116:117], v[176:177]
	v_mul_f32_e32 v97, v101, v101
	v_mul_f32_e32 v96, v99, v99
	v_fmac_f32_e32 v96, v98, v98
	v_fmac_f32_e32 v97, v100, v100
	v_add_f32_e32 v96, v96, v97
	v_add_f32_e32 v96, v102, v96
	ds_bpermute_b32 v97, v174, v96
	global_store_dwordx4 v[182:183], v[98:101], off offset:576
	s_waitcnt lgkmcnt(0)
	v_add_f32_e32 v96, v96, v97
	ds_bpermute_b32 v97, v175, v96
	v_pk_mul_f32 v[98:99], v[112:113], v[98:99]
	v_pk_mul_f32 v[100:101], v[114:115], v[100:101]
	v_cvt_pk_bf16_f32 v98, v98, v99
	s_nop 0
	v_cvt_pk_bf16_f32 v99, v100, v101
	global_store_dwordx2 v[180:181], v[98:99], off offset:288
	s_and_saveexec_b64 s[36:37], s[0:1]
	s_cbranch_execz .LBB0_431
	v_readlane_b32 s40, v249, 31
	s_waitcnt lgkmcnt(0)
	v_add_f32_e32 v98, v96, v97
	v_lshlrev_b64 v[96:97], 6, v[164:165]
	v_readlane_b32 s41, v249, 32
	s_lshl_b32 s22, s38, 2
	s_nop 0
	v_lshl_add_u64 v[96:97], s[40:41], 0, v[96:97]
	v_lshl_add_u64 v[96:97], v[96:97], 0, s[22:23]
	s_lshl_b32 s22, s50, 2
	v_lshl_add_u64 v[96:97], v[96:97], 0, s[22:23]
	global_store_dword v[96:97], v98, off
; __device__ __forceinline__ unsigned cvt_pk_bf16(float lo, float hi) { unsigned r; asm volatile("v_cvt_pk_bf16_f32 %0, %1, %2" : "=v"(r) : "v"(lo), "v"(hi)); return r; }
;     __device__ __forceinline__ void operator()(const f32x4 (&acc)[2][2][4][2], const Unit& u, int wr, int wc, int fr, int fq) const {
;     ...
;             for (int m = 0; m < 4; ++m) { const int row = row0 + ai * HALF + m * 16; const size_t off = (size_t)row * D + col0;
;                 float ssq = 0.f;
; #pragma unroll
;                 for (int bj = 0; bj < 2; ++bj)
; #pragma unroll
;                     for (int n = 0; n < 2; ++n) { const f32x4 bs = *(const f32x4*)(base + off + bj * HALF + n * 16);
;                         const f32x4 o = bs + gv[bj][n] * acc[ai][bj][m][n];
;                         *(f32x4*)(out + off + bj * HALF + n * 16) = o;
;                         if (FOLD) { ssq += (o.x * o.x + o.y * o.y) + (o.z * o.z + o.w * o.w); const f32x4 q = o * sv[bj][n];
;                             u32x2 w; w.x = cvt_pk_bf16(q.x, q.y); w.y = cvt_pk_bf16(q.z, q.w); *(u32x2*)(U2 + off + bj * HALF + n * 16) = w; } }
;                 if (FOLD) { ssq += __shfl_xor(ssq, 16); ssq += __shfl_xor(ssq, 32);
;                     if (fq == 0) part[(size_t)row * 16 + (u.pn & 3) * 4 + wc] = ssq; } }
.LBB0_431:
	s_or_b64 exec, exec, s[36:37]
	v_or_b32_e32 v96, 32, v146
	s_waitcnt lgkmcnt(0)
	v_ashrrev_i32_e32 v97, 31, v96
	v_lshlrev_b64 v[98:99], 10, v[96:97]
	v_lshl_add_u64 v[102:103], v[98:99], 0, v[144:145]
	v_readlane_b32 s72, v248, 11
	v_lshlrev_b64 v[104:105], 2, v[102:103]
	v_readlane_b32 s73, v248, 12
	v_readlane_b32 s74, v248, 13
	v_readlane_b32 s75, v248, 14
	v_lshl_add_u64 v[106:107], s[72:73], 0, v[104:105]
	global_load_dwordx4 v[236:239], v[106:107], off
	global_load_dwordx4 v[240:243], v[106:107], off offset:64
	global_load_dwordx4 v[244:247], v[106:107], off offset:512
	global_load_dwordx4 v[98:101], v[106:107], off offset:576
	v_readlane_b32 s76, v248, 15
	v_readlane_b32 s77, v248, 16
	v_readlane_b32 s78, v248, 17
	v_readlane_b32 s79, v248, 18
	v_readlane_b32 s36, v249, 43
	v_readlane_b32 s72, v248, 0
	v_readlane_b32 s37, v249, 44
	v_readlane_b32 s78, v248, 6
	v_readlane_b32 s79, v248, 7
	v_lshl_add_u64 v[102:103], v[102:103], 1, s[36:37]
	v_readlane_b32 s80, v248, 19
	v_lshl_add_u64 v[104:105], s[78:79], 0, v[104:105]
	v_readlane_b32 s81, v248, 20
	v_readlane_b32 s82, v248, 21
	v_readlane_b32 s83, v248, 22
	v_readlane_b32 s84, v248, 23
	v_readlane_b32 s85, v248, 24
	v_readlane_b32 s86, v248, 25
	v_readlane_b32 s87, v248, 26
	v_readlane_b32 s73, v248, 1
	v_readlane_b32 s74, v248, 2
	v_readlane_b32 s75, v248, 3
	v_readlane_b32 s76, v248, 4
	v_readlane_b32 s77, v248, 5
	s_waitcnt vmcnt(3)
	v_pk_fma_f32 v[92:93], v[92:93], v[158:159], v[236:237]
	v_pk_fma_f32 v[94:95], v[94:95], v[156:157], v[238:239]
	v_pk_mul_f32 v[238:239], v[162:163], v[92:93]
	global_store_dwordx4 v[104:105], v[92:95], off
	v_pk_mul_f32 v[236:237], v[160:161], v[94:95]
	v_cvt_pk_bf16_f32 v238, v238, v239
	s_nop 0
	v_cvt_pk_bf16_f32 v239, v236, v237
	global_store_dwordx2 v[102:103], v[238:239], off
	v_mul_f32_e32 v93, v93, v93
	v_mul_f32_e32 v95, v95, v95
	v_fmac_f32_e32 v93, v92, v92
	v_fmac_f32_e32 v95, v94, v94
	v_add_f32_e32 v92, v93, v95
	s_waitcnt vmcnt(4)
	v_pk_fma_f32 v[88:89], v[88:89], v[150:151], v[240:241]
	v_pk_fma_f32 v[90:91], v[90:91], v[154:155], v[242:243]
	v_pk_mul_f32 v[242:243], v[126:127], v[88:89]
	global_store_dwordx4 v[104:105], v[88:91], off offset:64
	v_pk_mul_f32 v[240:241], v[124:125], v[90:91]
	v_cvt_pk_bf16_f32 v242, v242, v243
	s_nop 0
	v_cvt_pk_bf16_f32 v243, v240, v241
	global_store_dwordx2 v[102:103], v[242:243], off offset:32
	v_mul_f32_e32 v89, v89, v89
	v_mul_f32_e32 v91, v91, v91
	v_fmac_f32_e32 v89, v88, v88
	v_fmac_f32_e32 v91, v90, v90
	v_add_f32_e32 v88, v89, v91
	v_add_f32_e32 v88, v92, v88
	s_waitcnt vmcnt(5)
	v_pk_fma_f32 v[84:85], v[84:85], v[148:149], v[244:245]
	v_pk_fma_f32 v[86:87], v[86:87], v[152:153], v[246:247]
	v_pk_mul_f32 v[246:247], v[122:123], v[84:85]
	global_store_dwordx4 v[104:105], v[84:87], off offset:512
	v_pk_mul_f32 v[244:245], v[120:121], v[86:87]
	v_cvt_pk_bf16_f32 v246, v246, v247
	s_nop 0
	v_cvt_pk_bf16_f32 v247, v244, v245
	global_store_dwordx2 v[102:103], v[246:247], off offset:256
	v_mul_f32_e32 v85, v85, v85
	v_mul_f32_e32 v87, v87, v87
	v_fmac_f32_e32 v85, v84, v84
	v_fmac_f32_e32 v87, v86, v86
	v_add_f32_e32 v84, v85, v87
	v_add_f32_e32 v86, v88, v84
	s_waitcnt vmcnt(6)
	v_pk_fma_f32 v[84:85], v[82:83], v[118:119], v[100:101]
	v_pk_fma_f32 v[82:83], v[80:81], v[116:117], v[98:99]
	v_mul_f32_e32 v81, v85, v85
	v_mul_f32_e32 v80, v83, v83
	v_fmac_f32_e32 v80, v82, v82
	v_fmac_f32_e32 v81, v84, v84
	v_add_f32_e32 v80, v80, v81
	v_add_f32_e32 v80, v86, v80
	ds_bpermute_b32 v81, v174, v80
	global_store_dwordx4 v[104:105], v[82:85], off offset:576
	s_waitcnt lgkmcnt(0)
	v_add_f32_e32 v80, v80, v81
	ds_bpermute_b32 v81, v175, v80
	v_pk_mul_f32 v[82:83], v[112:113], v[82:83]
	v_pk_mul_f32 v[84:85], v[114:115], v[84:85]
	v_cvt_pk_bf16_f32 v82, v82, v83
	s_nop 0
	v_cvt_pk_bf16_f32 v83, v84, v85
	global_store_dwordx2 v[102:103], v[82:83], off offset:288
	s_and_saveexec_b64 s[36:37], s[0:1]
	s_cbranch_execz .LBB0_433
	v_readlane_b32 s40, v249, 31
	s_waitcnt lgkmcnt(0)
	v_add_f32_e32 v82, v80, v81
	v_lshlrev_b64 v[80:81], 6, v[96:97]
	v_readlane_b32 s41, v249, 32
	s_lshl_b32 s22, s38, 2
	s_nop 0
	v_lshl_add_u64 v[80:81], s[40:41], 0, v[80:81]
	v_lshl_add_u64 v[80:81], v[80:81], 0, s[22:23]
	s_lshl_b32 s22, s50, 2
	v_lshl_add_u64 v[80:81], v[80:81], 0, s[22:23]
	global_store_dword v[80:81], v82, off
; __device__ __forceinline__ unsigned cvt_pk_bf16(float lo, float hi) { unsigned r; asm volatile("v_cvt_pk_bf16_f32 %0, %1, %2" : "=v"(r) : "v"(lo), "v"(hi)); return r; }
;     __device__ __forceinline__ void operator()(const f32x4 (&acc)[2][2][4][2], const Unit& u, int wr, int wc, int fr, int fq) const {
;     ...
;             for (int m = 0; m < 4; ++m) { const int row = row0 + ai * HALF + m * 16; const size_t off = (size_t)row * D + col0;
;                 float ssq = 0.f;
; #pragma unroll
;                 for (int bj = 0; bj < 2; ++bj)
; #pragma unroll
;                     for (int n = 0; n < 2; ++n) { const f32x4 bs = *(const f32x4*)(base + off + bj * HALF + n * 16);
;                         const f32x4 o = bs + gv[bj][n] * acc[ai][bj][m][n];
;                         *(f32x4*)(out + off + bj * HALF + n * 16) = o;
;                         if (FOLD) { ssq += (o.x * o.x + o.y * o.y) + (o.z * o.z + o.w * o.w); const f32x4 q = o * sv[bj][n];
;                             u32x2 w; w.x = cvt_pk_bf16(q.x, q.y); w.y = cvt_pk_bf16(q.z, q.w); *(u32x2*)(U2 + off + bj * HALF + n * 16) = w; } }
;                 if (FOLD) { ssq += __shfl_xor(ssq, 16); ssq += __shfl_xor(ssq, 32);
;                     if (fq == 0) part[(size_t)row * 16 + (u.pn & 3) * 4 + wc] = ssq; } }
.LBB0_433:
	s_or_b64 exec, exec, s[36:37]
	v_or_b32_e32 v80, 48, v146
	s_waitcnt lgkmcnt(0)
	v_ashrrev_i32_e32 v81, 31, v80
	v_lshlrev_b64 v[82:83], 10, v[80:81]
	v_lshl_add_u64 v[86:87], v[82:83], 0, v[144:145]
	v_readlane_b32 s72, v248, 11
	v_lshlrev_b64 v[88:89], 2, v[86:87]
	v_readlane_b32 s73, v248, 12
	v_readlane_b32 s74, v248, 13
	v_readlane_b32 s75, v248, 14
	v_lshl_add_u64 v[90:91], s[72:73], 0, v[88:89]
	global_load_dwordx4 v[236:239], v[90:91], off
	global_load_dwordx4 v[240:243], v[90:91], off offset:64
	global_load_dwordx4 v[244:247], v[90:91], off offset:512
	global_load_dwordx4 v[82:85], v[90:91], off offset:576
	v_readlane_b32 s76, v248, 15
	v_readlane_b32 s77, v248, 16
	v_readlane_b32 s78, v248, 17
	v_readlane_b32 s79, v248, 18
	v_readlane_b32 s36, v249, 43
	v_readlane_b32 s72, v248, 0
	v_readlane_b32 s37, v249, 44
	v_readlane_b32 s78, v248, 6
	v_readlane_b32 s79, v248, 7
	v_lshl_add_u64 v[86:87], v[86:87], 1, s[36:37]
	v_readlane_b32 s80, v248, 19
	v_lshl_add_u64 v[88:89], s[78:79], 0, v[88:89]
	v_readlane_b32 s81, v248, 20
	v_readlane_b32 s82, v248, 21
	v_readlane_b32 s83, v248, 22
	v_readlane_b32 s84, v248, 23
	v_readlane_b32 s85, v248, 24
	v_readlane_b32 s86, v248, 25
	v_readlane_b32 s87, v248, 26
	v_readlane_b32 s73, v248, 1
	v_readlane_b32 s74, v248, 2
	v_readlane_b32 s75, v248, 3
	v_readlane_b32 s76, v248, 4
	v_readlane_b32 s77, v248, 5
	s_waitcnt vmcnt(3)
	v_pk_fma_f32 v[76:77], v[76:77], v[158:159], v[236:237]
	v_pk_fma_f32 v[78:79], v[78:79], v[156:157], v[238:239]
	v_pk_mul_f32 v[238:239], v[162:163], v[76:77]
	global_store_dwordx4 v[88:89], v[76:79], off
	v_pk_mul_f32 v[236:237], v[160:161], v[78:79]
	v_cvt_pk_bf16_f32 v238, v238, v239
	s_nop 0
	v_cvt_pk_bf16_f32 v239, v236, v237
	global_store_dwordx2 v[86:87], v[238:239], off
	v_mul_f32_e32 v77, v77, v77
	v_mul_f32_e32 v79, v79, v79
	v_fmac_f32_e32 v77, v76, v76
	v_fmac_f32_e32 v79, v78, v78
	v_add_f32_e32 v76, v77, v79
	s_waitcnt vmcnt(4)
	v_pk_fma_f32 v[72:73], v[72:73], v[150:151], v[240:241]
	v_pk_fma_f32 v[74:75], v[74:75], v[154:155], v[242:243]
	v_pk_mul_f32 v[242:243], v[126:127], v[72:73]
	global_store_dwordx4 v[88:89], v[72:75], off offset:64
	v_pk_mul_f32 v[240:241], v[124:125], v[74:75]
	v_cvt_pk_bf16_f32 v242, v242, v243
	s_nop 0
	v_cvt_pk_bf16_f32 v243, v240, v241
	global_store_dwordx2 v[86:87], v[242:243], off offset:32
	v_mul_f32_e32 v73, v73, v73
	v_mul_f32_e32 v75, v75, v75
	v_fmac_f32_e32 v73, v72, v72
	v_fmac_f32_e32 v75, v74, v74
	v_add_f32_e32 v72, v73, v75
	v_add_f32_e32 v72, v76, v72
	s_waitcnt vmcnt(5)
	v_pk_fma_f32 v[68:69], v[68:69], v[148:149], v[244:245]
	v_pk_fma_f32 v[70:71], v[70:71], v[152:153], v[246:247]
	v_pk_mul_f32 v[246:247], v[122:123], v[68:69]
	global_store_dwordx4 v[88:89], v[68:71], off offset:512
	v_pk_mul_f32 v[244:245], v[120:121], v[70:71]
	v_cvt_pk_bf16_f32 v246, v246, v247
	s_nop 0
	v_cvt_pk_bf16_f32 v247, v244, v245
	global_store_dwordx2 v[86:87], v[246:247], off offset:256
	v_mul_f32_e32 v69, v69, v69
	v_mul_f32_e32 v71, v71, v71
	v_fmac_f32_e32 v69, v68, v68
	v_fmac_f32_e32 v71, v70, v70
	v_add_f32_e32 v68, v69, v71
	v_add_f32_e32 v70, v72, v68
	s_waitcnt vmcnt(6)
	v_pk_fma_f32 v[68:69], v[66:67], v[118:119], v[84:85]
	v_pk_fma_f32 v[66:67], v[64:65], v[116:117], v[82:83]
	v_mul_f32_e32 v65, v69, v69
	v_mul_f32_e32 v64, v67, v67
	v_fmac_f32_e32 v64, v66, v66
	v_fmac_f32_e32 v65, v68, v68
	v_add_f32_e32 v64, v64, v65
	v_add_f32_e32 v64, v70, v64
	ds_bpermute_b32 v65, v174, v64
	global_store_dwordx4 v[88:89], v[66:69], off offset:576
	s_waitcnt lgkmcnt(0)
	v_add_f32_e32 v64, v64, v65
	ds_bpermute_b32 v65, v175, v64
	v_pk_mul_f32 v[66:67], v[112:113], v[66:67]
	v_pk_mul_f32 v[68:69], v[114:115], v[68:69]
	v_cvt_pk_bf16_f32 v66, v66, v67
	s_nop 0
	v_cvt_pk_bf16_f32 v67, v68, v69
	global_store_dwordx2 v[86:87], v[66:67], off offset:288
	s_and_saveexec_b64 s[36:37], s[0:1]
	s_cbranch_execz .LBB0_435
	v_readlane_b32 s40, v249, 31
	s_waitcnt lgkmcnt(0)
	v_add_f32_e32 v66, v64, v65
	v_lshlrev_b64 v[64:65], 6, v[80:81]
	v_readlane_b32 s41, v249, 32
	s_lshl_b32 s22, s38, 2
	s_nop 0
	v_lshl_add_u64 v[64:65], s[40:41], 0, v[64:65]
	v_lshl_add_u64 v[64:65], v[64:65], 0, s[22:23]
	s_lshl_b32 s22, s50, 2
	v_lshl_add_u64 v[64:65], v[64:65], 0, s[22:23]
	global_store_dword v[64:65], v66, off
; __device__ __forceinline__ unsigned cvt_pk_bf16(float lo, float hi) { unsigned r; asm volatile("v_cvt_pk_bf16_f32 %0, %1, %2" : "=v"(r) : "v"(lo), "v"(hi)); return r; }
;     __device__ __forceinline__ void operator()(const f32x4 (&acc)[2][2][4][2], const Unit& u, int wr, int wc, int fr, int fq) const {
;     ...
;             for (int m = 0; m < 4; ++m) { const int row = row0 + ai * HALF + m * 16; const size_t off = (size_t)row * D + col0;
;                 float ssq = 0.f;
; #pragma unroll
;                 for (int bj = 0; bj < 2; ++bj)
; #pragma unroll
;                     for (int n = 0; n < 2; ++n) { const f32x4 bs = *(const f32x4*)(base + off + bj * HALF + n * 16);
;                         const f32x4 o = bs + gv[bj][n] * acc[ai][bj][m][n];
;                         *(f32x4*)(out + off + bj * HALF + n * 16) = o;
;                         if (FOLD) { ssq += (o.x * o.x + o.y * o.y) + (o.z * o.z + o.w * o.w); const f32x4 q = o * sv[bj][n];
;                             u32x2 w; w.x = cvt_pk_bf16(q.x, q.y); w.y = cvt_pk_bf16(q.z, q.w); *(u32x2*)(U2 + off + bj * HALF + n * 16) = w; } }
;                 if (FOLD) { ssq += __shfl_xor(ssq, 16); ssq += __shfl_xor(ssq, 32);
;                     if (fq == 0) part[(size_t)row * 16 + (u.pn & 3) * 4 + wc] = ssq; } }
.LBB0_435:
	s_or_b64 exec, exec, s[36:37]
	v_add_u32_e32 v64, 0x80, v146
	s_waitcnt lgkmcnt(0)
	v_ashrrev_i32_e32 v65, 31, v64
	v_lshlrev_b64 v[66:67], 10, v[64:65]
	v_lshl_add_u64 v[70:71], v[66:67], 0, v[144:145]
	v_readlane_b32 s72, v248, 11
	v_lshlrev_b64 v[72:73], 2, v[70:71]
	v_readlane_b32 s73, v248, 12
	v_readlane_b32 s74, v248, 13
	v_readlane_b32 s75, v248, 14
	v_lshl_add_u64 v[74:75], s[72:73], 0, v[72:73]
	global_load_dwordx4 v[236:239], v[74:75], off
	global_load_dwordx4 v[240:243], v[74:75], off offset:64
	global_load_dwordx4 v[244:247], v[74:75], off offset:512
	global_load_dwordx4 v[66:69], v[74:75], off offset:576
	v_readlane_b32 s76, v248, 15
	v_readlane_b32 s77, v248, 16
	v_readlane_b32 s78, v248, 17
	v_readlane_b32 s79, v248, 18
	v_readlane_b32 s36, v249, 43
	v_readlane_b32 s72, v248, 0
	v_readlane_b32 s37, v249, 44
	v_readlane_b32 s78, v248, 6
	v_readlane_b32 s79, v248, 7
	v_lshl_add_u64 v[70:71], v[70:71], 1, s[36:37]
	v_readlane_b32 s80, v248, 19
	v_lshl_add_u64 v[72:73], s[78:79], 0, v[72:73]
	v_readlane_b32 s81, v248, 20
	v_readlane_b32 s82, v248, 21
	v_readlane_b32 s83, v248, 22
	v_readlane_b32 s84, v248, 23
	v_readlane_b32 s85, v248, 24
	v_readlane_b32 s86, v248, 25
	v_readlane_b32 s87, v248, 26
	v_readlane_b32 s73, v248, 1
	v_readlane_b32 s74, v248, 2
	v_readlane_b32 s75, v248, 3
	v_readlane_b32 s76, v248, 4
	v_readlane_b32 s77, v248, 5
	s_waitcnt vmcnt(3)
	v_pk_fma_f32 v[60:61], v[60:61], v[158:159], v[236:237]
	v_pk_fma_f32 v[62:63], v[62:63], v[156:157], v[238:239]
	v_pk_mul_f32 v[238:239], v[162:163], v[60:61]
	global_store_dwordx4 v[72:73], v[60:63], off
	v_pk_mul_f32 v[236:237], v[160:161], v[62:63]
	v_cvt_pk_bf16_f32 v238, v238, v239
	s_nop 0
	v_cvt_pk_bf16_f32 v239, v236, v237
	global_store_dwordx2 v[70:71], v[238:239], off
	v_mul_f32_e32 v61, v61, v61
	v_mul_f32_e32 v63, v63, v63
	v_fmac_f32_e32 v61, v60, v60
	v_fmac_f32_e32 v63, v62, v62
	v_add_f32_e32 v60, v61, v63
	s_waitcnt vmcnt(4)
	v_pk_fma_f32 v[56:57], v[56:57], v[150:151], v[240:241]
	v_pk_fma_f32 v[58:59], v[58:59], v[154:155], v[242:243]
	v_pk_mul_f32 v[242:243], v[126:127], v[56:57]
	global_store_dwordx4 v[72:73], v[56:59], off offset:64
	v_pk_mul_f32 v[240:241], v[124:125], v[58:59]
	v_cvt_pk_bf16_f32 v242, v242, v243
	s_nop 0
	v_cvt_pk_bf16_f32 v243, v240, v241
	global_store_dwordx2 v[70:71], v[242:243], off offset:32
	v_mul_f32_e32 v57, v57, v57
	v_mul_f32_e32 v59, v59, v59
	v_fmac_f32_e32 v57, v56, v56
	v_fmac_f32_e32 v59, v58, v58
	v_add_f32_e32 v56, v57, v59
	v_add_f32_e32 v56, v60, v56
	s_waitcnt vmcnt(5)
	v_pk_fma_f32 v[52:53], v[52:53], v[148:149], v[244:245]
	v_pk_fma_f32 v[54:55], v[54:55], v[152:153], v[246:247]
	v_pk_mul_f32 v[246:247], v[122:123], v[52:53]
	global_store_dwordx4 v[72:73], v[52:55], off offset:512
	v_pk_mul_f32 v[244:245], v[120:121], v[54:55]
	v_cvt_pk_bf16_f32 v246, v246, v247
	s_nop 0
	v_cvt_pk_bf16_f32 v247, v244, v245
	global_store_dwordx2 v[70:71], v[246:247], off offset:256
	v_mul_f32_e32 v53, v53, v53
	v_mul_f32_e32 v55, v55, v55
	v_fmac_f32_e32 v53, v52, v52
	v_fmac_f32_e32 v55, v54, v54
	v_add_f32_e32 v52, v53, v55
	v_add_f32_e32 v54, v56, v52
	s_waitcnt vmcnt(6)
	v_pk_fma_f32 v[52:53], v[50:51], v[118:119], v[68:69]
	v_pk_fma_f32 v[50:51], v[48:49], v[116:117], v[66:67]
	v_mul_f32_e32 v49, v53, v53
	v_mul_f32_e32 v48, v51, v51
	v_fmac_f32_e32 v48, v50, v50
	v_fmac_f32_e32 v49, v52, v52
	v_add_f32_e32 v48, v48, v49
	v_add_f32_e32 v48, v54, v48
	ds_bpermute_b32 v49, v174, v48
	global_store_dwordx4 v[72:73], v[50:53], off offset:576
	s_waitcnt lgkmcnt(0)
	v_add_f32_e32 v48, v48, v49
	ds_bpermute_b32 v49, v175, v48
	v_pk_mul_f32 v[50:51], v[112:113], v[50:51]
	v_pk_mul_f32 v[52:53], v[114:115], v[52:53]
	v_cvt_pk_bf16_f32 v50, v50, v51
	s_nop 0
	v_cvt_pk_bf16_f32 v51, v52, v53
	global_store_dwordx2 v[70:71], v[50:51], off offset:288
	s_and_saveexec_b64 s[36:37], s[0:1]
	s_cbranch_execz .LBB0_437
	v_readlane_b32 s40, v249, 31
	s_waitcnt lgkmcnt(0)
	v_add_f32_e32 v50, v48, v49
	v_lshlrev_b64 v[48:49], 6, v[64:65]
	v_readlane_b32 s41, v249, 32
	s_lshl_b32 s22, s38, 2
	s_nop 0
	v_lshl_add_u64 v[48:49], s[40:41], 0, v[48:49]
	v_lshl_add_u64 v[48:49], v[48:49], 0, s[22:23]
	s_lshl_b32 s22, s50, 2
	v_lshl_add_u64 v[48:49], v[48:49], 0, s[22:23]
	global_store_dword v[48:49], v50, off
; __device__ __forceinline__ unsigned cvt_pk_bf16(float lo, float hi) { unsigned r; asm volatile("v_cvt_pk_bf16_f32 %0, %1, %2" : "=v"(r) : "v"(lo), "v"(hi)); return r; }
;     __device__ __forceinline__ void operator()(const f32x4 (&acc)[2][2][4][2], const Unit& u, int wr, int wc, int fr, int fq) const {
;     ...
;             for (int m = 0; m < 4; ++m) { const int row = row0 + ai * HALF + m * 16; const size_t off = (size_t)row * D + col0;
;                 float ssq = 0.f;
; #pragma unroll
;                 for (int bj = 0; bj < 2; ++bj)
; #pragma unroll
;                     for (int n = 0; n < 2; ++n) { const f32x4 bs = *(const f32x4*)(base + off + bj * HALF + n * 16);
;                         const f32x4 o = bs + gv[bj][n] * acc[ai][bj][m][n];
;                         *(f32x4*)(out + off + bj * HALF + n * 16) = o;
;                         if (FOLD) { ssq += (o.x * o.x + o.y * o.y) + (o.z * o.z + o.w * o.w); const f32x4 q = o * sv[bj][n];
;                             u32x2 w; w.x = cvt_pk_bf16(q.x, q.y); w.y = cvt_pk_bf16(q.z, q.w); *(u32x2*)(U2 + off + bj * HALF + n * 16) = w; } }
;                 if (FOLD) { ssq += __shfl_xor(ssq, 16); ssq += __shfl_xor(ssq, 32);
;                     if (fq == 0) part[(size_t)row * 16 + (u.pn & 3) * 4 + wc] = ssq; } }
.LBB0_437:
	s_or_b64 exec, exec, s[36:37]
	v_add_u32_e32 v48, 0x90, v146
	s_waitcnt lgkmcnt(0)
	v_ashrrev_i32_e32 v49, 31, v48
	v_lshlrev_b64 v[50:51], 10, v[48:49]
	v_lshl_add_u64 v[54:55], v[50:51], 0, v[144:145]
	v_readlane_b32 s72, v248, 11
	v_lshlrev_b64 v[56:57], 2, v[54:55]
	v_readlane_b32 s73, v248, 12
	v_readlane_b32 s74, v248, 13
	v_readlane_b32 s75, v248, 14
	v_lshl_add_u64 v[58:59], s[72:73], 0, v[56:57]
	global_load_dwordx4 v[236:239], v[58:59], off
	global_load_dwordx4 v[240:243], v[58:59], off offset:64
	global_load_dwordx4 v[244:247], v[58:59], off offset:512
	global_load_dwordx4 v[50:53], v[58:59], off offset:576
	v_readlane_b32 s76, v248, 15
	v_readlane_b32 s77, v248, 16
	v_readlane_b32 s78, v248, 17
	v_readlane_b32 s79, v248, 18
	v_readlane_b32 s36, v249, 43
	v_readlane_b32 s72, v248, 0
	v_readlane_b32 s37, v249, 44
	v_readlane_b32 s78, v248, 6
	v_readlane_b32 s79, v248, 7
	v_lshl_add_u64 v[54:55], v[54:55], 1, s[36:37]
	v_readlane_b32 s80, v248, 19
	v_lshl_add_u64 v[56:57], s[78:79], 0, v[56:57]
	v_readlane_b32 s81, v248, 20
	v_readlane_b32 s82, v248, 21
	v_readlane_b32 s83, v248, 22
	v_readlane_b32 s84, v248, 23
	v_readlane_b32 s85, v248, 24
	v_readlane_b32 s86, v248, 25
	v_readlane_b32 s87, v248, 26
	v_readlane_b32 s73, v248, 1
	v_readlane_b32 s74, v248, 2
	v_readlane_b32 s75, v248, 3
	v_readlane_b32 s76, v248, 4
	v_readlane_b32 s77, v248, 5
	s_waitcnt vmcnt(3)
	v_pk_fma_f32 v[44:45], v[44:45], v[158:159], v[236:237]
	v_pk_fma_f32 v[46:47], v[46:47], v[156:157], v[238:239]
	v_pk_mul_f32 v[238:239], v[162:163], v[44:45]
	global_store_dwordx4 v[56:57], v[44:47], off
	v_pk_mul_f32 v[236:237], v[160:161], v[46:47]
	v_cvt_pk_bf16_f32 v238, v238, v239
	s_nop 0
	v_cvt_pk_bf16_f32 v239, v236, v237
	global_store_dwordx2 v[54:55], v[238:239], off
	v_mul_f32_e32 v45, v45, v45
	v_mul_f32_e32 v47, v47, v47
	v_fmac_f32_e32 v45, v44, v44
	v_fmac_f32_e32 v47, v46, v46
	v_add_f32_e32 v44, v45, v47
	s_waitcnt vmcnt(4)
	v_pk_fma_f32 v[40:41], v[40:41], v[150:151], v[240:241]
	v_pk_fma_f32 v[42:43], v[42:43], v[154:155], v[242:243]
	v_pk_mul_f32 v[242:243], v[126:127], v[40:41]
	global_store_dwordx4 v[56:57], v[40:43], off offset:64
	v_pk_mul_f32 v[240:241], v[124:125], v[42:43]
	v_cvt_pk_bf16_f32 v242, v242, v243
	s_nop 0
	v_cvt_pk_bf16_f32 v243, v240, v241
	global_store_dwordx2 v[54:55], v[242:243], off offset:32
	v_mul_f32_e32 v41, v41, v41
	v_mul_f32_e32 v43, v43, v43
	v_fmac_f32_e32 v41, v40, v40
	v_fmac_f32_e32 v43, v42, v42
	v_add_f32_e32 v40, v41, v43
	v_add_f32_e32 v40, v44, v40
	s_waitcnt vmcnt(5)
	v_pk_fma_f32 v[36:37], v[36:37], v[148:149], v[244:245]
	v_pk_fma_f32 v[38:39], v[38:39], v[152:153], v[246:247]
	v_pk_mul_f32 v[246:247], v[122:123], v[36:37]
	global_store_dwordx4 v[56:57], v[36:39], off offset:512
	v_pk_mul_f32 v[244:245], v[120:121], v[38:39]
	v_cvt_pk_bf16_f32 v246, v246, v247
	s_nop 0
	v_cvt_pk_bf16_f32 v247, v244, v245
	global_store_dwordx2 v[54:55], v[246:247], off offset:256
	v_mul_f32_e32 v37, v37, v37
	v_mul_f32_e32 v39, v39, v39
	v_fmac_f32_e32 v37, v36, v36
	v_fmac_f32_e32 v39, v38, v38
	v_add_f32_e32 v36, v37, v39
	v_add_f32_e32 v38, v40, v36
	s_waitcnt vmcnt(6)
	v_pk_fma_f32 v[36:37], v[34:35], v[118:119], v[52:53]
	v_pk_fma_f32 v[34:35], v[32:33], v[116:117], v[50:51]
	v_mul_f32_e32 v33, v37, v37
	v_mul_f32_e32 v32, v35, v35
	v_fmac_f32_e32 v32, v34, v34
	v_fmac_f32_e32 v33, v36, v36
	v_add_f32_e32 v32, v32, v33
	v_add_f32_e32 v32, v38, v32
	ds_bpermute_b32 v33, v174, v32
	global_store_dwordx4 v[56:57], v[34:37], off offset:576
	s_waitcnt lgkmcnt(0)
	v_add_f32_e32 v32, v32, v33
	ds_bpermute_b32 v33, v175, v32
	v_pk_mul_f32 v[34:35], v[112:113], v[34:35]
	v_pk_mul_f32 v[36:37], v[114:115], v[36:37]
	v_cvt_pk_bf16_f32 v34, v34, v35
	s_nop 0
	v_cvt_pk_bf16_f32 v35, v36, v37
	global_store_dwordx2 v[54:55], v[34:35], off offset:288
	s_and_saveexec_b64 s[36:37], s[0:1]
	s_cbranch_execz .LBB0_439
	v_readlane_b32 s40, v249, 31
	s_waitcnt lgkmcnt(0)
	v_add_f32_e32 v34, v32, v33
	v_lshlrev_b64 v[32:33], 6, v[48:49]
	v_readlane_b32 s41, v249, 32
	s_lshl_b32 s22, s38, 2
	s_nop 0
	v_lshl_add_u64 v[32:33], s[40:41], 0, v[32:33]
	v_lshl_add_u64 v[32:33], v[32:33], 0, s[22:23]
	s_lshl_b32 s22, s50, 2
	v_lshl_add_u64 v[32:33], v[32:33], 0, s[22:23]
	global_store_dword v[32:33], v34, off
; __device__ __forceinline__ unsigned cvt_pk_bf16(float lo, float hi) { unsigned r; asm volatile("v_cvt_pk_bf16_f32 %0, %1, %2" : "=v"(r) : "v"(lo), "v"(hi)); return r; }
;     __device__ __forceinline__ void operator()(const f32x4 (&acc)[2][2][4][2], const Unit& u, int wr, int wc, int fr, int fq) const {
;     ...
;             for (int m = 0; m < 4; ++m) { const int row = row0 + ai * HALF + m * 16; const size_t off = (size_t)row * D + col0;
;                 float ssq = 0.f;
; #pragma unroll
;                 for (int bj = 0; bj < 2; ++bj)
; #pragma unroll
;                     for (int n = 0; n < 2; ++n) { const f32x4 bs = *(const f32x4*)(base + off + bj * HALF + n * 16);
;                         const f32x4 o = bs + gv[bj][n] * acc[ai][bj][m][n];
;                         *(f32x4*)(out + off + bj * HALF + n * 16) = o;
;                         if (FOLD) { ssq += (o.x * o.x + o.y * o.y) + (o.z * o.z + o.w * o.w); const f32x4 q = o * sv[bj][n];
;                             u32x2 w; w.x = cvt_pk_bf16(q.x, q.y); w.y = cvt_pk_bf16(q.z, q.w); *(u32x2*)(U2 + off + bj * HALF + n * 16) = w; } }
;                 if (FOLD) { ssq += __shfl_xor(ssq, 16); ssq += __shfl_xor(ssq, 32);
;                     if (fq == 0) part[(size_t)row * 16 + (u.pn & 3) * 4 + wc] = ssq; } }
.LBB0_439:
	s_or_b64 exec, exec, s[36:37]
	v_add_u32_e32 v32, 0xa0, v146
	s_waitcnt lgkmcnt(0)
	v_ashrrev_i32_e32 v33, 31, v32
	v_lshlrev_b64 v[34:35], 10, v[32:33]
	v_lshl_add_u64 v[38:39], v[34:35], 0, v[144:145]
	v_readlane_b32 s72, v248, 11
	v_lshlrev_b64 v[40:41], 2, v[38:39]
	v_readlane_b32 s73, v248, 12
	v_readlane_b32 s74, v248, 13
	v_readlane_b32 s75, v248, 14
	v_lshl_add_u64 v[42:43], s[72:73], 0, v[40:41]
	global_load_dwordx4 v[236:239], v[42:43], off
	global_load_dwordx4 v[240:243], v[42:43], off offset:64
	global_load_dwordx4 v[244:247], v[42:43], off offset:512
	global_load_dwordx4 v[34:37], v[42:43], off offset:576
	v_readlane_b32 s76, v248, 15
	v_readlane_b32 s77, v248, 16
	v_readlane_b32 s78, v248, 17
	v_readlane_b32 s79, v248, 18
	v_readlane_b32 s36, v249, 43
	v_readlane_b32 s72, v248, 0
	v_readlane_b32 s37, v249, 44
	v_readlane_b32 s78, v248, 6
	v_readlane_b32 s79, v248, 7
	v_lshl_add_u64 v[38:39], v[38:39], 1, s[36:37]
	v_readlane_b32 s80, v248, 19
	v_lshl_add_u64 v[40:41], s[78:79], 0, v[40:41]
	v_readlane_b32 s81, v248, 20
	v_readlane_b32 s82, v248, 21
	v_readlane_b32 s83, v248, 22
	v_readlane_b32 s84, v248, 23
	v_readlane_b32 s85, v248, 24
	v_readlane_b32 s86, v248, 25
	v_readlane_b32 s87, v248, 26
	v_readlane_b32 s73, v248, 1
	v_readlane_b32 s74, v248, 2
	v_readlane_b32 s75, v248, 3
	v_readlane_b32 s76, v248, 4
	v_readlane_b32 s77, v248, 5
	s_waitcnt vmcnt(3)
	v_pk_fma_f32 v[28:29], v[28:29], v[158:159], v[236:237]
	v_pk_fma_f32 v[30:31], v[30:31], v[156:157], v[238:239]
	v_pk_mul_f32 v[238:239], v[162:163], v[28:29]
	global_store_dwordx4 v[40:41], v[28:31], off
	v_pk_mul_f32 v[236:237], v[160:161], v[30:31]
	v_cvt_pk_bf16_f32 v238, v238, v239
	s_nop 0
	v_cvt_pk_bf16_f32 v239, v236, v237
	global_store_dwordx2 v[38:39], v[238:239], off
	v_mul_f32_e32 v29, v29, v29
	v_mul_f32_e32 v31, v31, v31
	v_fmac_f32_e32 v29, v28, v28
	v_fmac_f32_e32 v31, v30, v30
	v_add_f32_e32 v28, v29, v31
	s_waitcnt vmcnt(4)
	v_pk_fma_f32 v[24:25], v[24:25], v[150:151], v[240:241]
	v_pk_fma_f32 v[26:27], v[26:27], v[154:155], v[242:243]
	v_pk_mul_f32 v[242:243], v[126:127], v[24:25]
	global_store_dwordx4 v[40:41], v[24:27], off offset:64
	v_pk_mul_f32 v[240:241], v[124:125], v[26:27]
	v_cvt_pk_bf16_f32 v242, v242, v243
	s_nop 0
	v_cvt_pk_bf16_f32 v243, v240, v241
	global_store_dwordx2 v[38:39], v[242:243], off offset:32
	v_mul_f32_e32 v25, v25, v25
	v_mul_f32_e32 v27, v27, v27
	v_fmac_f32_e32 v25, v24, v24
	v_fmac_f32_e32 v27, v26, v26
	v_add_f32_e32 v24, v25, v27
	v_add_f32_e32 v24, v28, v24
	s_waitcnt vmcnt(5)
	v_pk_fma_f32 v[20:21], v[20:21], v[148:149], v[244:245]
	v_pk_fma_f32 v[22:23], v[22:23], v[152:153], v[246:247]
	v_pk_mul_f32 v[246:247], v[122:123], v[20:21]
	global_store_dwordx4 v[40:41], v[20:23], off offset:512
	v_pk_mul_f32 v[244:245], v[120:121], v[22:23]
	v_cvt_pk_bf16_f32 v246, v246, v247
	s_nop 0
	v_cvt_pk_bf16_f32 v247, v244, v245
	global_store_dwordx2 v[38:39], v[246:247], off offset:256
	v_mul_f32_e32 v21, v21, v21
	v_mul_f32_e32 v23, v23, v23
	v_fmac_f32_e32 v21, v20, v20
	v_fmac_f32_e32 v23, v22, v22
	v_add_f32_e32 v20, v21, v23
	v_add_f32_e32 v22, v24, v20
	s_waitcnt vmcnt(6)
	v_pk_fma_f32 v[20:21], v[18:19], v[118:119], v[36:37]
	v_pk_fma_f32 v[18:19], v[16:17], v[116:117], v[34:35]
	v_mul_f32_e32 v17, v21, v21
	v_mul_f32_e32 v16, v19, v19
	v_fmac_f32_e32 v16, v18, v18
	v_fmac_f32_e32 v17, v20, v20
	v_add_f32_e32 v16, v16, v17
	v_add_f32_e32 v16, v22, v16
	ds_bpermute_b32 v17, v174, v16
	global_store_dwordx4 v[40:41], v[18:21], off offset:576
	s_waitcnt lgkmcnt(0)
	v_add_f32_e32 v16, v16, v17
	ds_bpermute_b32 v17, v175, v16
	v_pk_mul_f32 v[18:19], v[112:113], v[18:19]
	v_pk_mul_f32 v[20:21], v[114:115], v[20:21]
	v_cvt_pk_bf16_f32 v18, v18, v19
	s_nop 0
	v_cvt_pk_bf16_f32 v19, v20, v21
	global_store_dwordx2 v[38:39], v[18:19], off offset:288
	s_and_saveexec_b64 s[36:37], s[0:1]
	s_cbranch_execz .LBB0_441
	v_readlane_b32 s40, v249, 31
	s_waitcnt lgkmcnt(0)
	v_add_f32_e32 v18, v16, v17
	v_lshlrev_b64 v[16:17], 6, v[32:33]
	v_readlane_b32 s41, v249, 32
	s_lshl_b32 s22, s38, 2
	s_nop 0
	v_lshl_add_u64 v[16:17], s[40:41], 0, v[16:17]
	v_lshl_add_u64 v[16:17], v[16:17], 0, s[22:23]
	s_lshl_b32 s22, s50, 2
	v_lshl_add_u64 v[16:17], v[16:17], 0, s[22:23]
	global_store_dword v[16:17], v18, off
; __device__ __forceinline__ unsigned cvt_pk_bf16(float lo, float hi) { unsigned r; asm volatile("v_cvt_pk_bf16_f32 %0, %1, %2" : "=v"(r) : "v"(lo), "v"(hi)); return r; }
;     __device__ __forceinline__ void operator()(const f32x4 (&acc)[2][2][4][2], const Unit& u, int wr, int wc, int fr, int fq) const {
;     ...
;             for (int m = 0; m < 4; ++m) { const int row = row0 + ai * HALF + m * 16; const size_t off = (size_t)row * D + col0;
;                 float ssq = 0.f;
; #pragma unroll
;                 for (int bj = 0; bj < 2; ++bj)
; #pragma unroll
;                     for (int n = 0; n < 2; ++n) { const f32x4 bs = *(const f32x4*)(base + off + bj * HALF + n * 16);
;                         const f32x4 o = bs + gv[bj][n] * acc[ai][bj][m][n];
;                         *(f32x4*)(out + off + bj * HALF + n * 16) = o;
;                         if (FOLD) { ssq += (o.x * o.x + o.y * o.y) + (o.z * o.z + o.w * o.w); const f32x4 q = o * sv[bj][n];
;                             u32x2 w; w.x = cvt_pk_bf16(q.x, q.y); w.y = cvt_pk_bf16(q.z, q.w); *(u32x2*)(U2 + off + bj * HALF + n * 16) = w; } }
;                 if (FOLD) { ssq += __shfl_xor(ssq, 16); ssq += __shfl_xor(ssq, 32);
;                     if (fq == 0) part[(size_t)row * 16 + (u.pn & 3) * 4 + wc] = ssq; } }
.LBB0_441:
	s_or_b64 exec, exec, s[36:37]
	v_add_u32_e32 v16, 0xb0, v146
	s_waitcnt lgkmcnt(0)
	v_ashrrev_i32_e32 v17, 31, v16
	v_lshlrev_b64 v[18:19], 10, v[16:17]
	v_lshl_add_u64 v[22:23], v[18:19], 0, v[144:145]
	v_readlane_b32 s72, v248, 11
	v_lshlrev_b64 v[24:25], 2, v[22:23]
	v_readlane_b32 s73, v248, 12
	v_readlane_b32 s74, v248, 13
	v_readlane_b32 s75, v248, 14
	v_lshl_add_u64 v[26:27], s[72:73], 0, v[24:25]
	global_load_dwordx4 v[236:239], v[26:27], off
	global_load_dwordx4 v[240:243], v[26:27], off offset:64
	global_load_dwordx4 v[244:247], v[26:27], off offset:512
	global_load_dwordx4 v[18:21], v[26:27], off offset:576
	v_readlane_b32 s76, v248, 15
	v_readlane_b32 s77, v248, 16
	v_readlane_b32 s78, v248, 17
	v_readlane_b32 s79, v248, 18
	v_readlane_b32 s36, v249, 43
	v_readlane_b32 s72, v248, 0
	v_readlane_b32 s37, v249, 44
	v_readlane_b32 s78, v248, 6
	v_readlane_b32 s79, v248, 7
	v_lshl_add_u64 v[22:23], v[22:23], 1, s[36:37]
	v_readlane_b32 s80, v248, 19
	v_lshl_add_u64 v[24:25], s[78:79], 0, v[24:25]
	v_readlane_b32 s81, v248, 20
	v_readlane_b32 s82, v248, 21
	v_readlane_b32 s83, v248, 22
	v_readlane_b32 s84, v248, 23
	v_readlane_b32 s85, v248, 24
	v_readlane_b32 s86, v248, 25
	v_readlane_b32 s87, v248, 26
	v_readlane_b32 s73, v248, 1
	v_readlane_b32 s74, v248, 2
	v_readlane_b32 s75, v248, 3
	v_readlane_b32 s76, v248, 4
	v_readlane_b32 s77, v248, 5
	s_waitcnt vmcnt(3)
	v_pk_fma_f32 v[12:13], v[12:13], v[158:159], v[236:237]
	v_pk_fma_f32 v[14:15], v[14:15], v[156:157], v[238:239]
	v_pk_mul_f32 v[238:239], v[162:163], v[12:13]
	global_store_dwordx4 v[24:25], v[12:15], off
	v_pk_mul_f32 v[236:237], v[160:161], v[14:15]
	v_cvt_pk_bf16_f32 v238, v238, v239
	s_nop 0
	v_cvt_pk_bf16_f32 v239, v236, v237
	global_store_dwordx2 v[22:23], v[238:239], off
	v_mul_f32_e32 v13, v13, v13
	v_mul_f32_e32 v15, v15, v15
	v_fmac_f32_e32 v13, v12, v12
	v_fmac_f32_e32 v15, v14, v14
	v_add_f32_e32 v12, v13, v15
	s_waitcnt vmcnt(4)
	v_pk_fma_f32 v[8:9], v[8:9], v[150:151], v[240:241]
	v_pk_fma_f32 v[10:11], v[10:11], v[154:155], v[242:243]
	v_pk_mul_f32 v[242:243], v[126:127], v[8:9]
	global_store_dwordx4 v[24:25], v[8:11], off offset:64
	v_pk_mul_f32 v[240:241], v[124:125], v[10:11]
	v_cvt_pk_bf16_f32 v242, v242, v243
	s_nop 0
	v_cvt_pk_bf16_f32 v243, v240, v241
	global_store_dwordx2 v[22:23], v[242:243], off offset:32
	v_mul_f32_e32 v9, v9, v9
	v_mul_f32_e32 v11, v11, v11
	v_fmac_f32_e32 v9, v8, v8
	v_fmac_f32_e32 v11, v10, v10
	v_add_f32_e32 v8, v9, v11
	v_add_f32_e32 v8, v12, v8
	s_waitcnt vmcnt(5)
	v_pk_fma_f32 v[4:5], v[4:5], v[148:149], v[244:245]
	v_pk_fma_f32 v[6:7], v[6:7], v[152:153], v[246:247]
	v_pk_mul_f32 v[246:247], v[122:123], v[4:5]
	global_store_dwordx4 v[24:25], v[4:7], off offset:512
	v_pk_mul_f32 v[244:245], v[120:121], v[6:7]
	v_cvt_pk_bf16_f32 v246, v246, v247
	s_nop 0
	v_cvt_pk_bf16_f32 v247, v244, v245
	global_store_dwordx2 v[22:23], v[246:247], off offset:256
	v_mul_f32_e32 v5, v5, v5
	v_mul_f32_e32 v7, v7, v7
	v_fmac_f32_e32 v5, v4, v4
	v_fmac_f32_e32 v7, v6, v6
	v_add_f32_e32 v4, v5, v7
	v_add_f32_e32 v6, v8, v4
	s_waitcnt vmcnt(6)
	v_pk_fma_f32 v[4:5], v[2:3], v[118:119], v[20:21]
	v_pk_fma_f32 v[2:3], v[0:1], v[116:117], v[18:19]
	v_mul_f32_e32 v1, v5, v5
	v_mul_f32_e32 v0, v3, v3
	v_fmac_f32_e32 v0, v2, v2
	v_fmac_f32_e32 v1, v4, v4
	v_add_f32_e32 v0, v0, v1
	v_add_f32_e32 v0, v6, v0
	ds_bpermute_b32 v1, v174, v0
	global_store_dwordx4 v[24:25], v[2:5], off offset:576
	s_waitcnt lgkmcnt(0)
	v_add_f32_e32 v0, v0, v1
	ds_bpermute_b32 v1, v175, v0
	v_pk_mul_f32 v[2:3], v[112:113], v[2:3]
	v_pk_mul_f32 v[4:5], v[114:115], v[4:5]
	v_cvt_pk_bf16_f32 v2, v2, v3
	s_nop 0
	v_cvt_pk_bf16_f32 v3, v4, v5
	global_store_dwordx2 v[22:23], v[2:3], off offset:288
	s_and_saveexec_b64 s[36:37], s[0:1]
	s_cbranch_execz .LBB0_443
	v_readlane_b32 s40, v249, 31
	s_waitcnt lgkmcnt(0)
	v_add_f32_e32 v2, v0, v1
	v_lshlrev_b64 v[0:1], 6, v[16:17]
	v_readlane_b32 s41, v249, 32
	s_lshl_b32 s22, s38, 2
	s_nop 0
	v_lshl_add_u64 v[0:1], s[40:41], 0, v[0:1]
	v_lshl_add_u64 v[0:1], v[0:1], 0, s[22:23]
	s_lshl_b32 s22, s50, 2
	v_lshl_add_u64 v[0:1], v[0:1], 0, s[22:23]
	global_store_dword v[0:1], v2, off

; __device__ __forceinline__ unsigned cvt_pk_bf16(float lo, float hi) { unsigned r; asm volatile("v_cvt_pk_bf16_f32 %0, %1, %2" : "=v"(r) : "v"(lo), "v"(hi)); return r; }
;     __device__ __forceinline__ void operator()(const f32x4 (&acc)[2][2][4][2], const Unit& u, int wr, int wc, int fr, int fq) const {
;     ...
;             for (int m = 0; m < 4; ++m) { const int row = row0 + ai * HALF + m * 16; const size_t off = (size_t)row * D + col0;
;                 float ssq = 0.f;
; #pragma unroll
;                 for (int bj = 0; bj < 2; ++bj)
; #pragma unroll
;                     for (int n = 0; n < 2; ++n) { const f32x4 bs = *(const f32x4*)(base + off + bj * HALF + n * 16);
;                         const f32x4 o = bs + gv[bj][n] * acc[ai][bj][m][n];
;                         *(f32x4*)(out + off + bj * HALF + n * 16) = o;
;                         if (FOLD) { ssq += (o.x * o.x + o.y * o.y) + (o.z * o.z + o.w * o.w); const f32x4 q = o * sv[bj][n];
;                             u32x2 w; w.x = cvt_pk_bf16(q.x, q.y); w.y = cvt_pk_bf16(q.z, q.w); *(u32x2*)(U2 + off + bj * HALF + n * 16) = w; } }
;                 if (FOLD) { ssq += __shfl_xor(ssq, 16); ssq += __shfl_xor(ssq, 32);
;                     if (fq == 0) part[(size_t)row * 16 + (u.pn & 3) * 4 + wc] = ssq; } }
.LBB0_1104:
	s_or_b64 exec, exec, s[4:5]
	v_or_b32_e32 v128, 16, v162
	s_waitcnt lgkmcnt(0)
	v_ashrrev_i32_e32 v129, 31, v128
	v_lshlrev_b64 v[130:131], 10, v[128:129]
	v_readlane_b32 s56, v248, 0
	v_lshl_add_u64 v[130:131], v[130:131], 0, v[160:161]
	v_readlane_b32 s62, v248, 6
	v_readlane_b32 s63, v248, 7
	v_readlane_b32 s4, v249, 43
	v_readlane_b32 s5, v249, 44
	v_lshl_add_u64 v[178:179], v[130:131], 2, s[62:63]
	global_load_dwordx4 v[236:239], v[178:179], off
	global_load_dwordx4 v[240:243], v[178:179], off offset:64
	global_load_dwordx4 v[244:247], v[178:179], off offset:512
	global_load_dwordx4 v[174:177], v[178:179], off offset:576
	v_lshl_add_u64 v[130:131], v[130:131], 1, s[4:5]
	v_readlane_b32 s57, v248, 1
	v_readlane_b32 s58, v248, 2
	v_readlane_b32 s59, v248, 3
	v_readlane_b32 s60, v248, 4
	v_readlane_b32 s61, v248, 5
	s_waitcnt vmcnt(3)
	v_pk_fma_f32 v[124:125], v[124:125], v[100:101], v[236:237]
	v_pk_fma_f32 v[126:127], v[126:127], v[102:103], v[238:239]
	v_pk_mul_f32 v[238:239], v[166:167], v[124:125]
	global_store_dwordx4 v[178:179], v[124:127], off
	v_pk_mul_f32 v[236:237], v[164:165], v[126:127]
	v_cvt_pk_bf16_f32 v238, v238, v239
	s_nop 0
	v_cvt_pk_bf16_f32 v239, v236, v237
	global_store_dwordx2 v[130:131], v[238:239], off
	v_mul_f32_e32 v125, v125, v125
	v_mul_f32_e32 v127, v127, v127
	v_fmac_f32_e32 v125, v124, v124
	v_fmac_f32_e32 v127, v126, v126
	v_add_f32_e32 v124, v125, v127
	s_waitcnt vmcnt(4)
	v_pk_fma_f32 v[120:121], v[120:121], v[108:109], v[240:241]
	v_pk_fma_f32 v[122:123], v[122:123], v[110:111], v[242:243]
	v_pk_mul_f32 v[242:243], v[142:143], v[120:121]
	global_store_dwordx4 v[178:179], v[120:123], off offset:64
	v_pk_mul_f32 v[240:241], v[140:141], v[122:123]
	v_cvt_pk_bf16_f32 v242, v242, v243
	s_nop 0
	v_cvt_pk_bf16_f32 v243, v240, v241
	global_store_dwordx2 v[130:131], v[242:243], off offset:32
	v_mul_f32_e32 v121, v121, v121
	v_mul_f32_e32 v123, v123, v123
	v_fmac_f32_e32 v121, v120, v120
	v_fmac_f32_e32 v123, v122, v122
	v_add_f32_e32 v120, v121, v123
	v_add_f32_e32 v120, v124, v120
	s_waitcnt vmcnt(5)
	v_pk_fma_f32 v[116:117], v[116:117], v[104:105], v[244:245]
	v_pk_fma_f32 v[118:119], v[118:119], v[106:107], v[246:247]
	v_pk_mul_f32 v[246:247], v[138:139], v[116:117]
	global_store_dwordx4 v[178:179], v[116:119], off offset:512
	v_pk_mul_f32 v[244:245], v[136:137], v[118:119]
	v_cvt_pk_bf16_f32 v246, v246, v247
	s_nop 0
	v_cvt_pk_bf16_f32 v247, v244, v245
	global_store_dwordx2 v[130:131], v[246:247], off offset:256
	v_mul_f32_e32 v117, v117, v117
	v_mul_f32_e32 v119, v119, v119
	v_fmac_f32_e32 v117, v116, v116
	v_fmac_f32_e32 v119, v118, v118
	v_add_f32_e32 v116, v117, v119
	v_add_f32_e32 v118, v120, v116
	s_waitcnt vmcnt(6)
	v_pk_fma_f32 v[116:117], v[114:115], v[98:99], v[176:177]
	v_pk_fma_f32 v[114:115], v[112:113], v[96:97], v[174:175]
	v_mul_f32_e32 v113, v117, v117
	v_mul_f32_e32 v112, v115, v115
	v_fmac_f32_e32 v112, v114, v114
	v_fmac_f32_e32 v113, v116, v116
	v_add_f32_e32 v112, v112, v113
	v_add_f32_e32 v112, v118, v112
	ds_bpermute_b32 v113, v207, v112
	global_store_dwordx4 v[178:179], v[114:117], off offset:576
	s_waitcnt lgkmcnt(0)
	v_add_f32_e32 v112, v112, v113
	ds_bpermute_b32 v113, v208, v112
	v_pk_mul_f32 v[114:115], v[132:133], v[114:115]
	v_pk_mul_f32 v[116:117], v[134:135], v[116:117]
	v_cvt_pk_bf16_f32 v114, v114, v115
	s_nop 0
	v_cvt_pk_bf16_f32 v115, v116, v117
	global_store_dwordx2 v[130:131], v[114:115], off offset:288
	s_and_saveexec_b64 s[4:5], s[0:1]
	s_cbranch_execz .LBB0_1106
	v_readlane_b32 s34, v249, 31
	v_lshlrev_b64 v[114:115], 6, v[128:129]
	v_readlane_b32 s35, v249, 32
	s_lshl_b32 s12, s27, 2
	s_waitcnt lgkmcnt(0)
	v_add_f32_e32 v112, v112, v113
	v_lshl_add_u64 v[114:115], s[34:35], 0, v[114:115]
	v_lshl_add_u64 v[114:115], v[114:115], 0, s[12:13]
	s_lshl_b32 s12, s46, 2
	v_lshl_add_u64 v[114:115], v[114:115], 0, s[12:13]
	global_store_dword v[114:115], v112, off
.LBB0_1106:
	s_or_b64 exec, exec, s[4:5]
	v_or_b32_e32 v112, 32, v162
	s_waitcnt lgkmcnt(0)
	v_ashrrev_i32_e32 v113, 31, v112
	v_lshlrev_b64 v[114:115], 10, v[112:113]
	v_readlane_b32 s56, v248, 0
	v_lshl_add_u64 v[118:119], v[114:115], 0, v[160:161]
	v_readlane_b32 s62, v248, 6
	v_readlane_b32 s63, v248, 7
	v_readlane_b32 s4, v249, 43
	v_readlane_b32 s5, v249, 44
	v_lshl_add_u64 v[120:121], v[118:119], 2, s[62:63]
	global_load_dwordx4 v[236:239], v[120:121], off
	global_load_dwordx4 v[240:243], v[120:121], off offset:64
	global_load_dwordx4 v[244:247], v[120:121], off offset:512
	global_load_dwordx4 v[114:117], v[120:121], off offset:576
	v_lshl_add_u64 v[118:119], v[118:119], 1, s[4:5]
	v_readlane_b32 s57, v248, 1
	v_readlane_b32 s58, v248, 2
	v_readlane_b32 s59, v248, 3
	v_readlane_b32 s60, v248, 4
	v_readlane_b32 s61, v248, 5
	s_waitcnt vmcnt(3)
	v_pk_fma_f32 v[92:93], v[92:93], v[100:101], v[236:237]
	v_pk_fma_f32 v[94:95], v[94:95], v[102:103], v[238:239]
	v_pk_mul_f32 v[238:239], v[166:167], v[92:93]
	global_store_dwordx4 v[120:121], v[92:95], off
	v_pk_mul_f32 v[236:237], v[164:165], v[94:95]
	v_cvt_pk_bf16_f32 v238, v238, v239
	s_nop 0
	v_cvt_pk_bf16_f32 v239, v236, v237
	global_store_dwordx2 v[118:119], v[238:239], off
	v_mul_f32_e32 v93, v93, v93
	v_mul_f32_e32 v95, v95, v95
	v_fmac_f32_e32 v93, v92, v92
	v_fmac_f32_e32 v95, v94, v94
	v_add_f32_e32 v92, v93, v95
	s_waitcnt vmcnt(4)
	v_pk_fma_f32 v[88:89], v[88:89], v[108:109], v[240:241]
	v_pk_fma_f32 v[90:91], v[90:91], v[110:111], v[242:243]
	v_pk_mul_f32 v[242:243], v[142:143], v[88:89]
	global_store_dwordx4 v[120:121], v[88:91], off offset:64
	v_pk_mul_f32 v[240:241], v[140:141], v[90:91]
	v_cvt_pk_bf16_f32 v242, v242, v243
	s_nop 0
	v_cvt_pk_bf16_f32 v243, v240, v241
	global_store_dwordx2 v[118:119], v[242:243], off offset:32
	v_mul_f32_e32 v89, v89, v89
	v_mul_f32_e32 v91, v91, v91
	v_fmac_f32_e32 v89, v88, v88
	v_fmac_f32_e32 v91, v90, v90
	v_add_f32_e32 v88, v89, v91
	v_add_f32_e32 v88, v92, v88
	s_waitcnt vmcnt(5)
; __device__ __forceinline__ unsigned cvt_pk_bf16(float lo, float hi) { unsigned r; asm volatile("v_cvt_pk_bf16_f32 %0, %1, %2" : "=v"(r) : "v"(lo), "v"(hi)); return r; }
;     __device__ __forceinline__ void operator()(const f32x4 (&acc)[2][2][4][2], const Unit& u, int wr, int wc, int fr, int fq) const {
;     ...
;             for (int m = 0; m < 4; ++m) { const int row = row0 + ai * HALF + m * 16; const size_t off = (size_t)row * D + col0;
;                 float ssq = 0.f;
; #pragma unroll
;                 for (int bj = 0; bj < 2; ++bj)
; #pragma unroll
;                     for (int n = 0; n < 2; ++n) { const f32x4 bs = *(const f32x4*)(base + off + bj * HALF + n * 16);
;                         const f32x4 o = bs + gv[bj][n] * acc[ai][bj][m][n];
;                         *(f32x4*)(out + off + bj * HALF + n * 16) = o;
;                         if (FOLD) { ssq += (o.x * o.x + o.y * o.y) + (o.z * o.z + o.w * o.w); const f32x4 q = o * sv[bj][n];
;                             u32x2 w; w.x = cvt_pk_bf16(q.x, q.y); w.y = cvt_pk_bf16(q.z, q.w); *(u32x2*)(U2 + off + bj * HALF + n * 16) = w; } }
;                 if (FOLD) { ssq += __shfl_xor(ssq, 16); ssq += __shfl_xor(ssq, 32);
;                     if (fq == 0) part[(size_t)row * 16 + (u.pn & 3) * 4 + wc] = ssq; } }
	v_pk_fma_f32 v[84:85], v[84:85], v[104:105], v[244:245]
	v_pk_fma_f32 v[86:87], v[86:87], v[106:107], v[246:247]
	v_pk_mul_f32 v[246:247], v[138:139], v[84:85]
	global_store_dwordx4 v[120:121], v[84:87], off offset:512
	v_pk_mul_f32 v[244:245], v[136:137], v[86:87]
	v_cvt_pk_bf16_f32 v246, v246, v247
	s_nop 0
	v_cvt_pk_bf16_f32 v247, v244, v245
	global_store_dwordx2 v[118:119], v[246:247], off offset:256
	v_mul_f32_e32 v85, v85, v85
	v_mul_f32_e32 v87, v87, v87
	v_fmac_f32_e32 v85, v84, v84
	v_fmac_f32_e32 v87, v86, v86
	v_add_f32_e32 v84, v85, v87
	v_add_f32_e32 v86, v88, v84
	s_waitcnt vmcnt(6)
	v_pk_fma_f32 v[84:85], v[82:83], v[98:99], v[116:117]
	v_pk_fma_f32 v[82:83], v[80:81], v[96:97], v[114:115]
	v_mul_f32_e32 v81, v85, v85
	v_mul_f32_e32 v80, v83, v83
	v_fmac_f32_e32 v80, v82, v82
	v_fmac_f32_e32 v81, v84, v84
	v_add_f32_e32 v80, v80, v81
	v_add_f32_e32 v80, v86, v80
	ds_bpermute_b32 v81, v207, v80
	global_store_dwordx4 v[120:121], v[82:85], off offset:576
	s_waitcnt lgkmcnt(0)
	v_add_f32_e32 v80, v80, v81
	ds_bpermute_b32 v81, v208, v80
	v_pk_mul_f32 v[82:83], v[132:133], v[82:83]
	v_pk_mul_f32 v[84:85], v[134:135], v[84:85]
	v_cvt_pk_bf16_f32 v82, v82, v83
	s_nop 0
	v_cvt_pk_bf16_f32 v83, v84, v85
	global_store_dwordx2 v[118:119], v[82:83], off offset:288
	s_and_saveexec_b64 s[4:5], s[0:1]
	s_cbranch_execz .LBB0_1108
	v_readlane_b32 s34, v249, 31
	v_lshlrev_b64 v[82:83], 6, v[112:113]
	v_readlane_b32 s35, v249, 32
	s_lshl_b32 s12, s27, 2
	s_waitcnt lgkmcnt(0)
	v_add_f32_e32 v80, v80, v81
	v_lshl_add_u64 v[82:83], s[34:35], 0, v[82:83]
	v_lshl_add_u64 v[82:83], v[82:83], 0, s[12:13]
	s_lshl_b32 s12, s46, 2
	v_lshl_add_u64 v[82:83], v[82:83], 0, s[12:13]
	global_store_dword v[82:83], v80, off
.LBB0_1108:
	s_or_b64 exec, exec, s[4:5]
	v_or_b32_e32 v80, 48, v162
	s_waitcnt lgkmcnt(0)
	v_ashrrev_i32_e32 v81, 31, v80
	v_lshlrev_b64 v[82:83], 10, v[80:81]
	v_readlane_b32 s56, v248, 0
	v_lshl_add_u64 v[86:87], v[82:83], 0, v[160:161]
	v_readlane_b32 s62, v248, 6
	v_readlane_b32 s63, v248, 7
	v_readlane_b32 s4, v249, 43
	v_readlane_b32 s5, v249, 44
	v_lshl_add_u64 v[88:89], v[86:87], 2, s[62:63]
	global_load_dwordx4 v[236:239], v[88:89], off
	global_load_dwordx4 v[240:243], v[88:89], off offset:64
	global_load_dwordx4 v[244:247], v[88:89], off offset:512
	global_load_dwordx4 v[82:85], v[88:89], off offset:576
	v_lshl_add_u64 v[86:87], v[86:87], 1, s[4:5]
	v_readlane_b32 s57, v248, 1
	v_readlane_b32 s58, v248, 2
	v_readlane_b32 s59, v248, 3
	v_readlane_b32 s60, v248, 4
	v_readlane_b32 s61, v248, 5
	s_waitcnt vmcnt(3)
	v_pk_fma_f32 v[76:77], v[76:77], v[100:101], v[236:237]
	v_pk_fma_f32 v[78:79], v[78:79], v[102:103], v[238:239]
	v_pk_mul_f32 v[238:239], v[166:167], v[76:77]
	global_store_dwordx4 v[88:89], v[76:79], off
	v_pk_mul_f32 v[236:237], v[164:165], v[78:79]
	v_cvt_pk_bf16_f32 v238, v238, v239
	s_nop 0
	v_cvt_pk_bf16_f32 v239, v236, v237
	global_store_dwordx2 v[86:87], v[238:239], off
	v_mul_f32_e32 v77, v77, v77
	v_mul_f32_e32 v79, v79, v79
	v_fmac_f32_e32 v77, v76, v76
	v_fmac_f32_e32 v79, v78, v78
	v_add_f32_e32 v76, v77, v79
	s_waitcnt vmcnt(4)
	v_pk_fma_f32 v[72:73], v[72:73], v[108:109], v[240:241]
	v_pk_fma_f32 v[74:75], v[74:75], v[110:111], v[242:243]
	v_pk_mul_f32 v[242:243], v[142:143], v[72:73]
	global_store_dwordx4 v[88:89], v[72:75], off offset:64
	v_pk_mul_f32 v[240:241], v[140:141], v[74:75]
	v_cvt_pk_bf16_f32 v242, v242, v243
	s_nop 0
	v_cvt_pk_bf16_f32 v243, v240, v241
	global_store_dwordx2 v[86:87], v[242:243], off offset:32
	v_mul_f32_e32 v73, v73, v73
	v_mul_f32_e32 v75, v75, v75
	v_fmac_f32_e32 v73, v72, v72
	v_fmac_f32_e32 v75, v74, v74
	v_add_f32_e32 v72, v73, v75
	v_add_f32_e32 v72, v76, v72
	s_waitcnt vmcnt(5)
	v_pk_fma_f32 v[68:69], v[68:69], v[104:105], v[244:245]
	v_pk_fma_f32 v[70:71], v[70:71], v[106:107], v[246:247]
	v_pk_mul_f32 v[246:247], v[138:139], v[68:69]
	global_store_dwordx4 v[88:89], v[68:71], off offset:512
	v_pk_mul_f32 v[244:245], v[136:137], v[70:71]
	v_cvt_pk_bf16_f32 v246, v246, v247
	s_nop 0
	v_cvt_pk_bf16_f32 v247, v244, v245
	global_store_dwordx2 v[86:87], v[246:247], off offset:256
	v_mul_f32_e32 v69, v69, v69
	v_mul_f32_e32 v71, v71, v71
	v_fmac_f32_e32 v69, v68, v68
	v_fmac_f32_e32 v71, v70, v70
	v_add_f32_e32 v68, v69, v71
	v_add_f32_e32 v70, v72, v68
	s_waitcnt vmcnt(6)
	v_pk_fma_f32 v[68:69], v[66:67], v[98:99], v[84:85]
	v_pk_fma_f32 v[66:67], v[64:65], v[96:97], v[82:83]
	v_mul_f32_e32 v65, v69, v69
	v_mul_f32_e32 v64, v67, v67
	v_fmac_f32_e32 v64, v66, v66
	v_fmac_f32_e32 v65, v68, v68
	v_add_f32_e32 v64, v64, v65
	v_add_f32_e32 v64, v70, v64
	ds_bpermute_b32 v65, v207, v64
	global_store_dwordx4 v[88:89], v[66:69], off offset:576
	s_waitcnt lgkmcnt(0)
	v_add_f32_e32 v64, v64, v65
	ds_bpermute_b32 v65, v208, v64
	v_pk_mul_f32 v[66:67], v[132:133], v[66:67]
	v_pk_mul_f32 v[68:69], v[134:135], v[68:69]
	v_cvt_pk_bf16_f32 v66, v66, v67
	s_nop 0
	v_cvt_pk_bf16_f32 v67, v68, v69
	global_store_dwordx2 v[86:87], v[66:67], off offset:288
	s_and_saveexec_b64 s[4:5], s[0:1]
	s_cbranch_execz .LBB0_1110
	v_readlane_b32 s34, v249, 31
	v_lshlrev_b64 v[66:67], 6, v[80:81]
	v_readlane_b32 s35, v249, 32
	s_lshl_b32 s12, s27, 2
	s_waitcnt lgkmcnt(0)
	v_add_f32_e32 v64, v64, v65
	v_lshl_add_u64 v[66:67], s[34:35], 0, v[66:67]
	v_lshl_add_u64 v[66:67], v[66:67], 0, s[12:13]
	s_lshl_b32 s12, s46, 2
	v_lshl_add_u64 v[66:67], v[66:67], 0, s[12:13]
	global_store_dword v[66:67], v64, off
; __device__ __forceinline__ unsigned cvt_pk_bf16(float lo, float hi) { unsigned r; asm volatile("v_cvt_pk_bf16_f32 %0, %1, %2" : "=v"(r) : "v"(lo), "v"(hi)); return r; }
;     __device__ __forceinline__ void operator()(const f32x4 (&acc)[2][2][4][2], const Unit& u, int wr, int wc, int fr, int fq) const {
;     ...
;             for (int m = 0; m < 4; ++m) { const int row = row0 + ai * HALF + m * 16; const size_t off = (size_t)row * D + col0;
;                 float ssq = 0.f;
; #pragma unroll
;                 for (int bj = 0; bj < 2; ++bj)
; #pragma unroll
;                     for (int n = 0; n < 2; ++n) { const f32x4 bs = *(const f32x4*)(base + off + bj * HALF + n * 16);
;                         const f32x4 o = bs + gv[bj][n] * acc[ai][bj][m][n];
;                         *(f32x4*)(out + off + bj * HALF + n * 16) = o;
;                         if (FOLD) { ssq += (o.x * o.x + o.y * o.y) + (o.z * o.z + o.w * o.w); const f32x4 q = o * sv[bj][n];
;                             u32x2 w; w.x = cvt_pk_bf16(q.x, q.y); w.y = cvt_pk_bf16(q.z, q.w); *(u32x2*)(U2 + off + bj * HALF + n * 16) = w; } }
;                 if (FOLD) { ssq += __shfl_xor(ssq, 16); ssq += __shfl_xor(ssq, 32);
;                     if (fq == 0) part[(size_t)row * 16 + (u.pn & 3) * 4 + wc] = ssq; } }
.LBB0_1110:
	s_or_b64 exec, exec, s[4:5]
	v_add_u32_e32 v64, 0x80, v162
	s_waitcnt lgkmcnt(0)
	v_ashrrev_i32_e32 v65, 31, v64
	v_lshlrev_b64 v[66:67], 10, v[64:65]
	v_readlane_b32 s56, v248, 0
	v_lshl_add_u64 v[70:71], v[66:67], 0, v[160:161]
	v_readlane_b32 s62, v248, 6
	v_readlane_b32 s63, v248, 7
	v_readlane_b32 s4, v249, 43
	v_readlane_b32 s5, v249, 44
	v_lshl_add_u64 v[72:73], v[70:71], 2, s[62:63]
	global_load_dwordx4 v[236:239], v[72:73], off
	global_load_dwordx4 v[240:243], v[72:73], off offset:64
	global_load_dwordx4 v[244:247], v[72:73], off offset:512
	global_load_dwordx4 v[66:69], v[72:73], off offset:576
	v_lshl_add_u64 v[70:71], v[70:71], 1, s[4:5]
	v_readlane_b32 s57, v248, 1
	v_readlane_b32 s58, v248, 2
	v_readlane_b32 s59, v248, 3
	v_readlane_b32 s60, v248, 4
	v_readlane_b32 s61, v248, 5
	s_waitcnt vmcnt(3)
	v_pk_fma_f32 v[60:61], v[60:61], v[100:101], v[236:237]
	v_pk_fma_f32 v[62:63], v[62:63], v[102:103], v[238:239]
	v_pk_mul_f32 v[238:239], v[166:167], v[60:61]
	global_store_dwordx4 v[72:73], v[60:63], off
	v_pk_mul_f32 v[236:237], v[164:165], v[62:63]
	v_cvt_pk_bf16_f32 v238, v238, v239
	s_nop 0
	v_cvt_pk_bf16_f32 v239, v236, v237
	global_store_dwordx2 v[70:71], v[238:239], off
	v_mul_f32_e32 v61, v61, v61
	v_mul_f32_e32 v63, v63, v63
	v_fmac_f32_e32 v61, v60, v60
	v_fmac_f32_e32 v63, v62, v62
	v_add_f32_e32 v60, v61, v63
	s_waitcnt vmcnt(4)
	v_pk_fma_f32 v[56:57], v[56:57], v[108:109], v[240:241]
	v_pk_fma_f32 v[58:59], v[58:59], v[110:111], v[242:243]
	v_pk_mul_f32 v[242:243], v[142:143], v[56:57]
	global_store_dwordx4 v[72:73], v[56:59], off offset:64
	v_pk_mul_f32 v[240:241], v[140:141], v[58:59]
	v_cvt_pk_bf16_f32 v242, v242, v243
	s_nop 0
	v_cvt_pk_bf16_f32 v243, v240, v241
	global_store_dwordx2 v[70:71], v[242:243], off offset:32
	v_mul_f32_e32 v57, v57, v57
	v_mul_f32_e32 v59, v59, v59
	v_fmac_f32_e32 v57, v56, v56
	v_fmac_f32_e32 v59, v58, v58
	v_add_f32_e32 v56, v57, v59
	v_add_f32_e32 v56, v60, v56
	s_waitcnt vmcnt(5)
	v_pk_fma_f32 v[52:53], v[52:53], v[104:105], v[244:245]
	v_pk_fma_f32 v[54:55], v[54:55], v[106:107], v[246:247]
	v_pk_mul_f32 v[246:247], v[138:139], v[52:53]
	global_store_dwordx4 v[72:73], v[52:55], off offset:512
	v_pk_mul_f32 v[244:245], v[136:137], v[54:55]
	v_cvt_pk_bf16_f32 v246, v246, v247
	s_nop 0
	v_cvt_pk_bf16_f32 v247, v244, v245
	global_store_dwordx2 v[70:71], v[246:247], off offset:256
	v_mul_f32_e32 v53, v53, v53
	v_mul_f32_e32 v55, v55, v55
	v_fmac_f32_e32 v53, v52, v52
	v_fmac_f32_e32 v55, v54, v54
	v_add_f32_e32 v52, v53, v55
	v_add_f32_e32 v54, v56, v52
	s_waitcnt vmcnt(6)
	v_pk_fma_f32 v[52:53], v[50:51], v[98:99], v[68:69]
	v_pk_fma_f32 v[50:51], v[48:49], v[96:97], v[66:67]
	v_mul_f32_e32 v49, v53, v53
	v_mul_f32_e32 v48, v51, v51
	v_fmac_f32_e32 v48, v50, v50
	v_fmac_f32_e32 v49, v52, v52
	v_add_f32_e32 v48, v48, v49
	v_add_f32_e32 v48, v54, v48
	ds_bpermute_b32 v49, v207, v48
	global_store_dwordx4 v[72:73], v[50:53], off offset:576
	s_waitcnt lgkmcnt(0)
	v_add_f32_e32 v48, v48, v49
	ds_bpermute_b32 v49, v208, v48
	v_pk_mul_f32 v[50:51], v[132:133], v[50:51]
	v_pk_mul_f32 v[52:53], v[134:135], v[52:53]
	v_cvt_pk_bf16_f32 v50, v50, v51
	s_nop 0
	v_cvt_pk_bf16_f32 v51, v52, v53
	global_store_dwordx2 v[70:71], v[50:51], off offset:288
	s_and_saveexec_b64 s[4:5], s[0:1]
	s_cbranch_execz .LBB0_1112
	v_readlane_b32 s34, v249, 31
	v_lshlrev_b64 v[50:51], 6, v[64:65]
	v_readlane_b32 s35, v249, 32
	s_lshl_b32 s12, s27, 2
	s_waitcnt lgkmcnt(0)
	v_add_f32_e32 v48, v48, v49
	v_lshl_add_u64 v[50:51], s[34:35], 0, v[50:51]
	v_lshl_add_u64 v[50:51], v[50:51], 0, s[12:13]
	s_lshl_b32 s12, s46, 2
	v_lshl_add_u64 v[50:51], v[50:51], 0, s[12:13]
	global_store_dword v[50:51], v48, off
.LBB0_1112:
	s_or_b64 exec, exec, s[4:5]
	v_add_u32_e32 v48, 0x90, v162
	s_waitcnt lgkmcnt(0)
	v_ashrrev_i32_e32 v49, 31, v48
	v_lshlrev_b64 v[50:51], 10, v[48:49]
	v_readlane_b32 s56, v248, 0
	v_lshl_add_u64 v[54:55], v[50:51], 0, v[160:161]
	v_readlane_b32 s62, v248, 6
	v_readlane_b32 s63, v248, 7
	v_readlane_b32 s4, v249, 43
	v_readlane_b32 s5, v249, 44
	v_lshl_add_u64 v[56:57], v[54:55], 2, s[62:63]
	global_load_dwordx4 v[236:239], v[56:57], off
	global_load_dwordx4 v[240:243], v[56:57], off offset:64
	global_load_dwordx4 v[244:247], v[56:57], off offset:512
	global_load_dwordx4 v[50:53], v[56:57], off offset:576
	v_lshl_add_u64 v[54:55], v[54:55], 1, s[4:5]
	v_readlane_b32 s57, v248, 1
	v_readlane_b32 s58, v248, 2
	v_readlane_b32 s59, v248, 3
	v_readlane_b32 s60, v248, 4
	v_readlane_b32 s61, v248, 5
	s_waitcnt vmcnt(3)
	v_pk_fma_f32 v[44:45], v[44:45], v[100:101], v[236:237]
	v_pk_fma_f32 v[46:47], v[46:47], v[102:103], v[238:239]
	v_pk_mul_f32 v[238:239], v[166:167], v[44:45]
	global_store_dwordx4 v[56:57], v[44:47], off
	v_pk_mul_f32 v[236:237], v[164:165], v[46:47]
	v_cvt_pk_bf16_f32 v238, v238, v239
	s_nop 0
	v_cvt_pk_bf16_f32 v239, v236, v237
	global_store_dwordx2 v[54:55], v[238:239], off
	v_mul_f32_e32 v45, v45, v45
	v_mul_f32_e32 v47, v47, v47
	v_fmac_f32_e32 v45, v44, v44
	v_fmac_f32_e32 v47, v46, v46
	v_add_f32_e32 v44, v45, v47
	s_waitcnt vmcnt(4)
	v_pk_fma_f32 v[40:41], v[40:41], v[108:109], v[240:241]
	v_pk_fma_f32 v[42:43], v[42:43], v[110:111], v[242:243]
	v_pk_mul_f32 v[242:243], v[142:143], v[40:41]
	global_store_dwordx4 v[56:57], v[40:43], off offset:64
	v_pk_mul_f32 v[240:241], v[140:141], v[42:43]
	v_cvt_pk_bf16_f32 v242, v242, v243
	s_nop 0
	v_cvt_pk_bf16_f32 v243, v240, v241
	global_store_dwordx2 v[54:55], v[242:243], off offset:32
	v_mul_f32_e32 v41, v41, v41
	v_mul_f32_e32 v43, v43, v43
	v_fmac_f32_e32 v41, v40, v40
	v_fmac_f32_e32 v43, v42, v42
	v_add_f32_e32 v40, v41, v43
	v_add_f32_e32 v40, v44, v40
	s_waitcnt vmcnt(5)
	v_pk_fma_f32 v[36:37], v[36:37], v[104:105], v[244:245]
	v_pk_fma_f32 v[38:39], v[38:39], v[106:107], v[246:247]
	v_pk_mul_f32 v[246:247], v[138:139], v[36:37]
	global_store_dwordx4 v[56:57], v[36:39], off offset:512
	v_pk_mul_f32 v[244:245], v[136:137], v[38:39]
	v_cvt_pk_bf16_f32 v246, v246, v247
	s_nop 0
	v_cvt_pk_bf16_f32 v247, v244, v245
	global_store_dwordx2 v[54:55], v[246:247], off offset:256
	v_mul_f32_e32 v37, v37, v37
	v_mul_f32_e32 v39, v39, v39
	v_fmac_f32_e32 v37, v36, v36
	v_fmac_f32_e32 v39, v38, v38
	v_add_f32_e32 v36, v37, v39
	v_add_f32_e32 v38, v40, v36
	s_waitcnt vmcnt(6)
	v_pk_fma_f32 v[36:37], v[34:35], v[98:99], v[52:53]
	v_pk_fma_f32 v[34:35], v[32:33], v[96:97], v[50:51]
	v_mul_f32_e32 v33, v37, v37
	v_mul_f32_e32 v32, v35, v35
	v_fmac_f32_e32 v32, v34, v34
	v_fmac_f32_e32 v33, v36, v36
	v_add_f32_e32 v32, v32, v33
	v_add_f32_e32 v32, v38, v32
	ds_bpermute_b32 v33, v207, v32
	global_store_dwordx4 v[56:57], v[34:37], off offset:576
	s_waitcnt lgkmcnt(0)
	v_add_f32_e32 v32, v32, v33
	ds_bpermute_b32 v33, v208, v32
	v_pk_mul_f32 v[34:35], v[132:133], v[34:35]
	v_pk_mul_f32 v[36:37], v[134:135], v[36:37]
	v_cvt_pk_bf16_f32 v34, v34, v35
	s_nop 0
	v_cvt_pk_bf16_f32 v35, v36, v37
	global_store_dwordx2 v[54:55], v[34:35], off offset:288
	s_and_saveexec_b64 s[4:5], s[0:1]
	s_cbranch_execz .LBB0_1114
; __device__ __forceinline__ unsigned cvt_pk_bf16(float lo, float hi) { unsigned r; asm volatile("v_cvt_pk_bf16_f32 %0, %1, %2" : "=v"(r) : "v"(lo), "v"(hi)); return r; }
;     __device__ __forceinline__ void operator()(const f32x4 (&acc)[2][2][4][2], const Unit& u, int wr, int wc, int fr, int fq) const {
;     ...
;             for (int m = 0; m < 4; ++m) { const int row = row0 + ai * HALF + m * 16; const size_t off = (size_t)row * D + col0;
;                 float ssq = 0.f;
; #pragma unroll
;                 for (int bj = 0; bj < 2; ++bj)
; #pragma unroll
;                     for (int n = 0; n < 2; ++n) { const f32x4 bs = *(const f32x4*)(base + off + bj * HALF + n * 16);
;                         const f32x4 o = bs + gv[bj][n] * acc[ai][bj][m][n];
;                         *(f32x4*)(out + off + bj * HALF + n * 16) = o;
;                         if (FOLD) { ssq += (o.x * o.x + o.y * o.y) + (o.z * o.z + o.w * o.w); const f32x4 q = o * sv[bj][n];
;                             u32x2 w; w.x = cvt_pk_bf16(q.x, q.y); w.y = cvt_pk_bf16(q.z, q.w); *(u32x2*)(U2 + off + bj * HALF + n * 16) = w; } }
;                 if (FOLD) { ssq += __shfl_xor(ssq, 16); ssq += __shfl_xor(ssq, 32);
;                     if (fq == 0) part[(size_t)row * 16 + (u.pn & 3) * 4 + wc] = ssq; } }
	v_readlane_b32 s34, v249, 31
	v_lshlrev_b64 v[34:35], 6, v[48:49]
	v_readlane_b32 s35, v249, 32
	s_lshl_b32 s12, s27, 2
	s_waitcnt lgkmcnt(0)
	v_add_f32_e32 v32, v32, v33
	v_lshl_add_u64 v[34:35], s[34:35], 0, v[34:35]
	v_lshl_add_u64 v[34:35], v[34:35], 0, s[12:13]
	s_lshl_b32 s12, s46, 2
	v_lshl_add_u64 v[34:35], v[34:35], 0, s[12:13]
	global_store_dword v[34:35], v32, off
.LBB0_1114:
	s_or_b64 exec, exec, s[4:5]
	v_add_u32_e32 v32, 0xa0, v162
	s_waitcnt lgkmcnt(0)
	v_ashrrev_i32_e32 v33, 31, v32
	v_lshlrev_b64 v[34:35], 10, v[32:33]
	v_readlane_b32 s56, v248, 0
	v_lshl_add_u64 v[38:39], v[34:35], 0, v[160:161]
	v_readlane_b32 s62, v248, 6
	v_readlane_b32 s63, v248, 7
	v_readlane_b32 s4, v249, 43
	v_readlane_b32 s5, v249, 44
	v_lshl_add_u64 v[40:41], v[38:39], 2, s[62:63]
	global_load_dwordx4 v[236:239], v[40:41], off
	global_load_dwordx4 v[240:243], v[40:41], off offset:64
	global_load_dwordx4 v[244:247], v[40:41], off offset:512
	global_load_dwordx4 v[34:37], v[40:41], off offset:576
	v_lshl_add_u64 v[38:39], v[38:39], 1, s[4:5]
	v_readlane_b32 s57, v248, 1
	v_readlane_b32 s58, v248, 2
	v_readlane_b32 s59, v248, 3
	v_readlane_b32 s60, v248, 4
	v_readlane_b32 s61, v248, 5
	s_waitcnt vmcnt(3)
	v_pk_fma_f32 v[28:29], v[28:29], v[100:101], v[236:237]
	v_pk_fma_f32 v[30:31], v[30:31], v[102:103], v[238:239]
	v_pk_mul_f32 v[238:239], v[166:167], v[28:29]
	global_store_dwordx4 v[40:41], v[28:31], off
	v_pk_mul_f32 v[236:237], v[164:165], v[30:31]
	v_cvt_pk_bf16_f32 v238, v238, v239
	s_nop 0
	v_cvt_pk_bf16_f32 v239, v236, v237
	global_store_dwordx2 v[38:39], v[238:239], off
	v_mul_f32_e32 v29, v29, v29
	v_mul_f32_e32 v31, v31, v31
	v_fmac_f32_e32 v29, v28, v28
	v_fmac_f32_e32 v31, v30, v30
	v_add_f32_e32 v28, v29, v31
	s_waitcnt vmcnt(4)
	v_pk_fma_f32 v[24:25], v[24:25], v[108:109], v[240:241]
	v_pk_fma_f32 v[26:27], v[26:27], v[110:111], v[242:243]
	v_pk_mul_f32 v[242:243], v[142:143], v[24:25]
	global_store_dwordx4 v[40:41], v[24:27], off offset:64
	v_pk_mul_f32 v[240:241], v[140:141], v[26:27]
	v_cvt_pk_bf16_f32 v242, v242, v243
	s_nop 0
	v_cvt_pk_bf16_f32 v243, v240, v241
	global_store_dwordx2 v[38:39], v[242:243], off offset:32
	v_mul_f32_e32 v25, v25, v25
	v_mul_f32_e32 v27, v27, v27
	v_fmac_f32_e32 v25, v24, v24
	v_fmac_f32_e32 v27, v26, v26
	v_add_f32_e32 v24, v25, v27
	v_add_f32_e32 v24, v28, v24
	s_waitcnt vmcnt(5)
	v_pk_fma_f32 v[20:21], v[20:21], v[104:105], v[244:245]
	v_pk_fma_f32 v[22:23], v[22:23], v[106:107], v[246:247]
	v_pk_mul_f32 v[246:247], v[138:139], v[20:21]
	global_store_dwordx4 v[40:41], v[20:23], off offset:512
	v_pk_mul_f32 v[244:245], v[136:137], v[22:23]
	v_cvt_pk_bf16_f32 v246, v246, v247
	s_nop 0
	v_cvt_pk_bf16_f32 v247, v244, v245
	global_store_dwordx2 v[38:39], v[246:247], off offset:256
	v_mul_f32_e32 v21, v21, v21
	v_mul_f32_e32 v23, v23, v23
	v_fmac_f32_e32 v21, v20, v20
	v_fmac_f32_e32 v23, v22, v22
	v_add_f32_e32 v20, v21, v23
	v_add_f32_e32 v22, v24, v20
	s_waitcnt vmcnt(6)
	v_pk_fma_f32 v[20:21], v[18:19], v[98:99], v[36:37]
	v_pk_fma_f32 v[18:19], v[16:17], v[96:97], v[34:35]
	v_mul_f32_e32 v17, v21, v21
	v_mul_f32_e32 v16, v19, v19
	v_fmac_f32_e32 v16, v18, v18
	v_fmac_f32_e32 v17, v20, v20
	v_add_f32_e32 v16, v16, v17
	v_add_f32_e32 v16, v22, v16
	ds_bpermute_b32 v17, v207, v16
	global_store_dwordx4 v[40:41], v[18:21], off offset:576
	s_waitcnt lgkmcnt(0)
	v_add_f32_e32 v16, v16, v17
	ds_bpermute_b32 v17, v208, v16
	v_pk_mul_f32 v[18:19], v[132:133], v[18:19]
	v_pk_mul_f32 v[20:21], v[134:135], v[20:21]
	v_cvt_pk_bf16_f32 v18, v18, v19
	s_nop 0
	v_cvt_pk_bf16_f32 v19, v20, v21
	global_store_dwordx2 v[38:39], v[18:19], off offset:288
	s_and_saveexec_b64 s[4:5], s[0:1]
	s_cbranch_execz .LBB0_1116
	v_readlane_b32 s34, v249, 31
	v_lshlrev_b64 v[18:19], 6, v[32:33]
	v_readlane_b32 s35, v249, 32
	s_lshl_b32 s12, s27, 2
	s_waitcnt lgkmcnt(0)
	v_add_f32_e32 v16, v16, v17
	v_lshl_add_u64 v[18:19], s[34:35], 0, v[18:19]
	v_lshl_add_u64 v[18:19], v[18:19], 0, s[12:13]
	s_lshl_b32 s12, s46, 2
	v_lshl_add_u64 v[18:19], v[18:19], 0, s[12:13]
	global_store_dword v[18:19], v16, off
; __device__ __forceinline__ unsigned cvt_pk_bf16(float lo, float hi) { unsigned r; asm volatile("v_cvt_pk_bf16_f32 %0, %1, %2" : "=v"(r) : "v"(lo), "v"(hi)); return r; }
;     __device__ __forceinline__ void operator()(const f32x4 (&acc)[2][2][4][2], const Unit& u, int wr, int wc, int fr, int fq) const {
;     ...
;             for (int m = 0; m < 4; ++m) { const int row = row0 + ai * HALF + m * 16; const size_t off = (size_t)row * D + col0;
;                 float ssq = 0.f;
; #pragma unroll
;                 for (int bj = 0; bj < 2; ++bj)
; #pragma unroll
;                     for (int n = 0; n < 2; ++n) { const f32x4 bs = *(const f32x4*)(base + off + bj * HALF + n * 16);
;                         const f32x4 o = bs + gv[bj][n] * acc[ai][bj][m][n];
;                         *(f32x4*)(out + off + bj * HALF + n * 16) = o;
;                         if (FOLD) { ssq += (o.x * o.x + o.y * o.y) + (o.z * o.z + o.w * o.w); const f32x4 q = o * sv[bj][n];
;                             u32x2 w; w.x = cvt_pk_bf16(q.x, q.y); w.y = cvt_pk_bf16(q.z, q.w); *(u32x2*)(U2 + off + bj * HALF + n * 16) = w; } }
;                 if (FOLD) { ssq += __shfl_xor(ssq, 16); ssq += __shfl_xor(ssq, 32);
;                     if (fq == 0) part[(size_t)row * 16 + (u.pn & 3) * 4 + wc] = ssq; } }
.LBB0_1116:
	s_or_b64 exec, exec, s[4:5]
	v_add_u32_e32 v16, 0xb0, v162
	s_waitcnt lgkmcnt(0)
	v_ashrrev_i32_e32 v17, 31, v16
	v_lshlrev_b64 v[18:19], 10, v[16:17]
	v_readlane_b32 s56, v248, 0
	v_lshl_add_u64 v[22:23], v[18:19], 0, v[160:161]
	v_readlane_b32 s62, v248, 6
	v_readlane_b32 s63, v248, 7
	v_readlane_b32 s4, v249, 43
	v_readlane_b32 s5, v249, 44
	v_lshl_add_u64 v[24:25], v[22:23], 2, s[62:63]
	global_load_dwordx4 v[236:239], v[24:25], off
	global_load_dwordx4 v[240:243], v[24:25], off offset:64
	global_load_dwordx4 v[244:247], v[24:25], off offset:512
	global_load_dwordx4 v[18:21], v[24:25], off offset:576
	v_lshl_add_u64 v[22:23], v[22:23], 1, s[4:5]
	v_readlane_b32 s57, v248, 1
	v_readlane_b32 s58, v248, 2
	v_readlane_b32 s59, v248, 3
	v_readlane_b32 s60, v248, 4
	v_readlane_b32 s61, v248, 5
	s_waitcnt vmcnt(3)
	v_pk_fma_f32 v[12:13], v[12:13], v[100:101], v[236:237]
	v_pk_fma_f32 v[14:15], v[14:15], v[102:103], v[238:239]
	v_pk_mul_f32 v[238:239], v[166:167], v[12:13]
	global_store_dwordx4 v[24:25], v[12:15], off
	v_pk_mul_f32 v[236:237], v[164:165], v[14:15]
	v_cvt_pk_bf16_f32 v238, v238, v239
	s_nop 0
	v_cvt_pk_bf16_f32 v239, v236, v237
	global_store_dwordx2 v[22:23], v[238:239], off
	v_mul_f32_e32 v13, v13, v13
	v_mul_f32_e32 v15, v15, v15
	v_fmac_f32_e32 v13, v12, v12
	v_fmac_f32_e32 v15, v14, v14
	v_add_f32_e32 v12, v13, v15
	s_waitcnt vmcnt(4)
	v_pk_fma_f32 v[8:9], v[8:9], v[108:109], v[240:241]
	v_pk_fma_f32 v[10:11], v[10:11], v[110:111], v[242:243]
	v_pk_mul_f32 v[242:243], v[142:143], v[8:9]
	global_store_dwordx4 v[24:25], v[8:11], off offset:64
	v_pk_mul_f32 v[240:241], v[140:141], v[10:11]
	v_cvt_pk_bf16_f32 v242, v242, v243
	s_nop 0
	v_cvt_pk_bf16_f32 v243, v240, v241
	global_store_dwordx2 v[22:23], v[242:243], off offset:32
	v_mul_f32_e32 v9, v9, v9
	v_mul_f32_e32 v11, v11, v11
	v_fmac_f32_e32 v9, v8, v8
	v_fmac_f32_e32 v11, v10, v10
	v_add_f32_e32 v8, v9, v11
	v_add_f32_e32 v8, v12, v8
	s_waitcnt vmcnt(5)
	v_pk_fma_f32 v[4:5], v[4:5], v[104:105], v[244:245]
	v_pk_fma_f32 v[6:7], v[6:7], v[106:107], v[246:247]
	v_pk_mul_f32 v[246:247], v[138:139], v[4:5]
	global_store_dwordx4 v[24:25], v[4:7], off offset:512
	v_pk_mul_f32 v[244:245], v[136:137], v[6:7]
	v_cvt_pk_bf16_f32 v246, v246, v247
	s_nop 0
	v_cvt_pk_bf16_f32 v247, v244, v245
	global_store_dwordx2 v[22:23], v[246:247], off offset:256
	v_mul_f32_e32 v5, v5, v5
	v_mul_f32_e32 v7, v7, v7
	v_fmac_f32_e32 v5, v4, v4
	v_fmac_f32_e32 v7, v6, v6
	v_add_f32_e32 v4, v5, v7
	v_add_f32_e32 v6, v8, v4
	s_waitcnt vmcnt(6)
	v_pk_fma_f32 v[4:5], v[2:3], v[98:99], v[20:21]
	v_pk_fma_f32 v[2:3], v[0:1], v[96:97], v[18:19]
	v_mul_f32_e32 v1, v5, v5
	v_mul_f32_e32 v0, v3, v3
	v_fmac_f32_e32 v0, v2, v2
	v_fmac_f32_e32 v1, v4, v4
	v_add_f32_e32 v0, v0, v1
	v_add_f32_e32 v0, v6, v0
	ds_bpermute_b32 v1, v207, v0
	global_store_dwordx4 v[24:25], v[2:5], off offset:576
	s_waitcnt lgkmcnt(0)
	v_add_f32_e32 v0, v0, v1
	ds_bpermute_b32 v1, v208, v0
	v_pk_mul_f32 v[2:3], v[132:133], v[2:3]
	v_pk_mul_f32 v[4:5], v[134:135], v[4:5]
	v_cvt_pk_bf16_f32 v2, v2, v3
	s_nop 0
	v_cvt_pk_bf16_f32 v3, v4, v5
	global_store_dwordx2 v[22:23], v[2:3], off offset:288
	s_and_saveexec_b64 s[4:5], s[0:1]
	s_cbranch_execz .LBB0_1118
	v_readlane_b32 s34, v249, 31
	v_lshlrev_b64 v[2:3], 6, v[16:17]
	v_readlane_b32 s35, v249, 32
	s_lshl_b32 s12, s27, 2
	s_waitcnt lgkmcnt(0)
	v_add_f32_e32 v0, v0, v1
	v_lshl_add_u64 v[2:3], s[34:35], 0, v[2:3]
	v_lshl_add_u64 v[2:3], v[2:3], 0, s[12:13]
	s_lshl_b32 s12, s46, 2
	v_lshl_add_u64 v[2:3], v[2:3], 0, s[12:13]
	global_store_dword v[2:3], v0, off

; __device__ __forceinline__ unsigned cvt_pk_bf16(float lo, float hi) { unsigned r; asm volatile("v_cvt_pk_bf16_f32 %0, %1, %2" : "=v"(r) : "v"(lo), "v"(hi)); return r; }
;     __device__ __forceinline__ void operator()(const f32x4 (&acc)[2][2][4][2], const Unit& u, int wr, int wc, int fr, int fq) const {
;     ...
;             for (int m = 0; m < 4; ++m) { const int row = row0 + ai * HALF + m * 16; const size_t off = (size_t)row * D + col0;
;                 float ssq = 0.f;
; #pragma unroll
;                 for (int bj = 0; bj < 2; ++bj)
; #pragma unroll
;                     for (int n = 0; n < 2; ++n) { const f32x4 bs = *(const f32x4*)(base + off + bj * HALF + n * 16);
;                         const f32x4 o = bs + gv[bj][n] * acc[ai][bj][m][n];
;                         *(f32x4*)(out + off + bj * HALF + n * 16) = o;
;                         if (FOLD) { ssq += (o.x * o.x + o.y * o.y) + (o.z * o.z + o.w * o.w); const f32x4 q = o * sv[bj][n];
;                             u32x2 w; w.x = cvt_pk_bf16(q.x, q.y); w.y = cvt_pk_bf16(q.z, q.w); *(u32x2*)(U2 + off + bj * HALF + n * 16) = w; } }
;                 if (FOLD) { ssq += __shfl_xor(ssq, 16); ssq += __shfl_xor(ssq, 32);
;                     if (fq == 0) part[(size_t)row * 16 + (u.pn & 3) * 4 + wc] = ssq; } }
.LBB0_1274:
	s_or_b64 exec, exec, s[34:35]
	v_or_b32_e32 v112, 16, v150
	s_waitcnt lgkmcnt(0)
	v_ashrrev_i32_e32 v113, 31, v112
	v_lshlrev_b64 v[114:115], 10, v[112:113]
	v_readlane_b32 s72, v248, 0
	v_lshl_add_u64 v[114:115], v[114:115], 0, v[144:145]
	v_readlane_b32 s78, v248, 6
	v_readlane_b32 s79, v248, 7
	v_readlane_b32 s34, v249, 43
	v_readlane_b32 s35, v249, 44
	v_lshl_add_u64 v[178:179], v[114:115], 2, s[78:79]
	global_load_dwordx4 v[236:239], v[178:179], off
	global_load_dwordx4 v[240:243], v[178:179], off offset:64
	global_load_dwordx4 v[244:247], v[178:179], off offset:512
	global_load_dwordx4 v[174:177], v[178:179], off offset:576
	v_lshl_add_u64 v[114:115], v[114:115], 1, s[34:35]
	v_readlane_b32 s73, v248, 1
	v_readlane_b32 s74, v248, 2
	v_readlane_b32 s75, v248, 3
	v_readlane_b32 s76, v248, 4
	v_readlane_b32 s77, v248, 5
	s_waitcnt vmcnt(3)
	v_pk_fma_f32 v[108:109], v[108:109], v[162:163], v[236:237]
	v_pk_fma_f32 v[110:111], v[110:111], v[160:161], v[238:239]
	v_pk_mul_f32 v[238:239], v[166:167], v[108:109]
	global_store_dwordx4 v[178:179], v[108:111], off
	v_pk_mul_f32 v[236:237], v[164:165], v[110:111]
	v_cvt_pk_bf16_f32 v238, v238, v239
	s_nop 0
	v_cvt_pk_bf16_f32 v239, v236, v237
	global_store_dwordx2 v[114:115], v[238:239], off
	v_mul_f32_e32 v109, v109, v109
	v_mul_f32_e32 v111, v111, v111
	v_fmac_f32_e32 v109, v108, v108
	v_fmac_f32_e32 v111, v110, v110
	v_add_f32_e32 v108, v109, v111
	s_waitcnt vmcnt(4)
	v_pk_fma_f32 v[104:105], v[104:105], v[154:155], v[240:241]
	v_pk_fma_f32 v[106:107], v[106:107], v[158:159], v[242:243]
	v_pk_mul_f32 v[242:243], v[148:149], v[104:105]
	global_store_dwordx4 v[178:179], v[104:107], off offset:64
	v_pk_mul_f32 v[240:241], v[126:127], v[106:107]
	v_cvt_pk_bf16_f32 v242, v242, v243
	s_nop 0
	v_cvt_pk_bf16_f32 v243, v240, v241
	global_store_dwordx2 v[114:115], v[242:243], off offset:32
	v_mul_f32_e32 v105, v105, v105
	v_mul_f32_e32 v107, v107, v107
	v_fmac_f32_e32 v105, v104, v104
	v_fmac_f32_e32 v107, v106, v106
	v_add_f32_e32 v104, v105, v107
	v_add_f32_e32 v104, v108, v104
	s_waitcnt vmcnt(5)
	v_pk_fma_f32 v[100:101], v[100:101], v[152:153], v[244:245]
	v_pk_fma_f32 v[102:103], v[102:103], v[156:157], v[246:247]
	v_pk_mul_f32 v[246:247], v[146:147], v[100:101]
	global_store_dwordx4 v[178:179], v[100:103], off offset:512
	v_pk_mul_f32 v[244:245], v[124:125], v[102:103]
	v_cvt_pk_bf16_f32 v246, v246, v247
	s_nop 0
	v_cvt_pk_bf16_f32 v247, v244, v245
	global_store_dwordx2 v[114:115], v[246:247], off offset:256
	v_mul_f32_e32 v101, v101, v101
	v_mul_f32_e32 v103, v103, v103
	v_fmac_f32_e32 v101, v100, v100
	v_fmac_f32_e32 v103, v102, v102
	v_add_f32_e32 v100, v101, v103
	v_add_f32_e32 v102, v104, v100
	s_waitcnt vmcnt(6)
	v_pk_fma_f32 v[100:101], v[98:99], v[122:123], v[176:177]
	v_pk_fma_f32 v[98:99], v[96:97], v[120:121], v[174:175]
	v_mul_f32_e32 v97, v101, v101
	v_mul_f32_e32 v96, v99, v99
	v_fmac_f32_e32 v96, v98, v98
	v_fmac_f32_e32 v97, v100, v100
	v_add_f32_e32 v96, v96, v97
	v_add_f32_e32 v96, v102, v96
	ds_bpermute_b32 v97, v207, v96
	global_store_dwordx4 v[178:179], v[98:101], off offset:576
	s_waitcnt lgkmcnt(0)
	v_add_f32_e32 v96, v96, v97
	ds_bpermute_b32 v97, v208, v96
	v_pk_mul_f32 v[98:99], v[116:117], v[98:99]
	v_pk_mul_f32 v[100:101], v[118:119], v[100:101]
	v_cvt_pk_bf16_f32 v98, v98, v99
	s_nop 0
	v_cvt_pk_bf16_f32 v99, v100, v101
	global_store_dwordx2 v[114:115], v[98:99], off offset:288
	s_and_saveexec_b64 s[34:35], s[0:1]
	s_cbranch_execz .LBB0_1276
	v_readlane_b32 s40, v249, 31
	s_waitcnt lgkmcnt(0)
	v_add_f32_e32 v98, v96, v97
	v_lshlrev_b64 v[96:97], 6, v[112:113]
	v_readlane_b32 s41, v249, 32
	s_lshl_b32 s20, s36, 2
	s_nop 0
	v_lshl_add_u64 v[96:97], s[40:41], 0, v[96:97]
	v_lshl_add_u64 v[96:97], v[96:97], 0, s[20:21]
	s_lshl_b32 s20, s50, 2
	v_lshl_add_u64 v[96:97], v[96:97], 0, s[20:21]
	global_store_dword v[96:97], v98, off
.LBB0_1276:
	s_or_b64 exec, exec, s[34:35]
	v_or_b32_e32 v96, 32, v150
	s_waitcnt lgkmcnt(0)
	v_ashrrev_i32_e32 v97, 31, v96
	v_lshlrev_b64 v[98:99], 10, v[96:97]
	v_readlane_b32 s72, v248, 0
	v_lshl_add_u64 v[102:103], v[98:99], 0, v[144:145]
	v_readlane_b32 s78, v248, 6
	v_readlane_b32 s79, v248, 7
	v_readlane_b32 s34, v249, 43
	v_readlane_b32 s35, v249, 44
	v_lshl_add_u64 v[104:105], v[102:103], 2, s[78:79]
	global_load_dwordx4 v[236:239], v[104:105], off
	global_load_dwordx4 v[240:243], v[104:105], off offset:64
	global_load_dwordx4 v[244:247], v[104:105], off offset:512
	global_load_dwordx4 v[98:101], v[104:105], off offset:576
	v_lshl_add_u64 v[102:103], v[102:103], 1, s[34:35]
	v_readlane_b32 s73, v248, 1
	v_readlane_b32 s74, v248, 2
	v_readlane_b32 s75, v248, 3
	v_readlane_b32 s76, v248, 4
	v_readlane_b32 s77, v248, 5
	s_waitcnt vmcnt(3)
	v_pk_fma_f32 v[92:93], v[92:93], v[162:163], v[236:237]
	v_pk_fma_f32 v[94:95], v[94:95], v[160:161], v[238:239]
	v_pk_mul_f32 v[238:239], v[166:167], v[92:93]
	global_store_dwordx4 v[104:105], v[92:95], off
	v_pk_mul_f32 v[236:237], v[164:165], v[94:95]
	v_cvt_pk_bf16_f32 v238, v238, v239
	s_nop 0
	v_cvt_pk_bf16_f32 v239, v236, v237
	global_store_dwordx2 v[102:103], v[238:239], off
	v_mul_f32_e32 v93, v93, v93
	v_mul_f32_e32 v95, v95, v95
	v_fmac_f32_e32 v93, v92, v92
	v_fmac_f32_e32 v95, v94, v94
	v_add_f32_e32 v92, v93, v95
	s_waitcnt vmcnt(4)
	v_pk_fma_f32 v[88:89], v[88:89], v[154:155], v[240:241]
	v_pk_fma_f32 v[90:91], v[90:91], v[158:159], v[242:243]
	v_pk_mul_f32 v[242:243], v[148:149], v[88:89]
	global_store_dwordx4 v[104:105], v[88:91], off offset:64
	v_pk_mul_f32 v[240:241], v[126:127], v[90:91]
	v_cvt_pk_bf16_f32 v242, v242, v243
	s_nop 0
	v_cvt_pk_bf16_f32 v243, v240, v241
	global_store_dwordx2 v[102:103], v[242:243], off offset:32
	v_mul_f32_e32 v89, v89, v89
	v_mul_f32_e32 v91, v91, v91
	v_fmac_f32_e32 v89, v88, v88
	v_fmac_f32_e32 v91, v90, v90
	v_add_f32_e32 v88, v89, v91
	v_add_f32_e32 v88, v92, v88
	s_waitcnt vmcnt(5)
; __device__ __forceinline__ unsigned cvt_pk_bf16(float lo, float hi) { unsigned r; asm volatile("v_cvt_pk_bf16_f32 %0, %1, %2" : "=v"(r) : "v"(lo), "v"(hi)); return r; }
;     __device__ __forceinline__ void operator()(const f32x4 (&acc)[2][2][4][2], const Unit& u, int wr, int wc, int fr, int fq) const {
;     ...
;             for (int m = 0; m < 4; ++m) { const int row = row0 + ai * HALF + m * 16; const size_t off = (size_t)row * D + col0;
;                 float ssq = 0.f;
; #pragma unroll
;                 for (int bj = 0; bj < 2; ++bj)
; #pragma unroll
;                     for (int n = 0; n < 2; ++n) { const f32x4 bs = *(const f32x4*)(base + off + bj * HALF + n * 16);
;                         const f32x4 o = bs + gv[bj][n] * acc[ai][bj][m][n];
;                         *(f32x4*)(out + off + bj * HALF + n * 16) = o;
;                         if (FOLD) { ssq += (o.x * o.x + o.y * o.y) + (o.z * o.z + o.w * o.w); const f32x4 q = o * sv[bj][n];
;                             u32x2 w; w.x = cvt_pk_bf16(q.x, q.y); w.y = cvt_pk_bf16(q.z, q.w); *(u32x2*)(U2 + off + bj * HALF + n * 16) = w; } }
;                 if (FOLD) { ssq += __shfl_xor(ssq, 16); ssq += __shfl_xor(ssq, 32);
;                     if (fq == 0) part[(size_t)row * 16 + (u.pn & 3) * 4 + wc] = ssq; } }
	v_pk_fma_f32 v[84:85], v[84:85], v[152:153], v[244:245]
	v_pk_fma_f32 v[86:87], v[86:87], v[156:157], v[246:247]
	v_pk_mul_f32 v[246:247], v[146:147], v[84:85]
	global_store_dwordx4 v[104:105], v[84:87], off offset:512
	v_pk_mul_f32 v[244:245], v[124:125], v[86:87]
	v_cvt_pk_bf16_f32 v246, v246, v247
	s_nop 0
	v_cvt_pk_bf16_f32 v247, v244, v245
	global_store_dwordx2 v[102:103], v[246:247], off offset:256
	v_mul_f32_e32 v85, v85, v85
	v_mul_f32_e32 v87, v87, v87
	v_fmac_f32_e32 v85, v84, v84
	v_fmac_f32_e32 v87, v86, v86
	v_add_f32_e32 v84, v85, v87
	v_add_f32_e32 v86, v88, v84
	s_waitcnt vmcnt(6)
	v_pk_fma_f32 v[84:85], v[82:83], v[122:123], v[100:101]
	v_pk_fma_f32 v[82:83], v[80:81], v[120:121], v[98:99]
	v_mul_f32_e32 v81, v85, v85
	v_mul_f32_e32 v80, v83, v83
	v_fmac_f32_e32 v80, v82, v82
	v_fmac_f32_e32 v81, v84, v84
	v_add_f32_e32 v80, v80, v81
	v_add_f32_e32 v80, v86, v80
	ds_bpermute_b32 v81, v207, v80
	global_store_dwordx4 v[104:105], v[82:85], off offset:576
	s_waitcnt lgkmcnt(0)
	v_add_f32_e32 v80, v80, v81
	ds_bpermute_b32 v81, v208, v80
	v_pk_mul_f32 v[82:83], v[116:117], v[82:83]
	v_pk_mul_f32 v[84:85], v[118:119], v[84:85]
	v_cvt_pk_bf16_f32 v82, v82, v83
	s_nop 0
	v_cvt_pk_bf16_f32 v83, v84, v85
	global_store_dwordx2 v[102:103], v[82:83], off offset:288
	s_and_saveexec_b64 s[34:35], s[0:1]
	s_cbranch_execz .LBB0_1278
	v_readlane_b32 s40, v249, 31
	s_waitcnt lgkmcnt(0)
	v_add_f32_e32 v82, v80, v81
	v_lshlrev_b64 v[80:81], 6, v[96:97]
	v_readlane_b32 s41, v249, 32
	s_lshl_b32 s20, s36, 2
	s_nop 0
	v_lshl_add_u64 v[80:81], s[40:41], 0, v[80:81]
	v_lshl_add_u64 v[80:81], v[80:81], 0, s[20:21]
	s_lshl_b32 s20, s50, 2
	v_lshl_add_u64 v[80:81], v[80:81], 0, s[20:21]
	global_store_dword v[80:81], v82, off
.LBB0_1278:
	s_or_b64 exec, exec, s[34:35]
	v_or_b32_e32 v80, 48, v150
	s_waitcnt lgkmcnt(0)
	v_ashrrev_i32_e32 v81, 31, v80
	v_lshlrev_b64 v[82:83], 10, v[80:81]
	v_readlane_b32 s72, v248, 0
	v_lshl_add_u64 v[86:87], v[82:83], 0, v[144:145]
	v_readlane_b32 s78, v248, 6
	v_readlane_b32 s79, v248, 7
	v_readlane_b32 s34, v249, 43
	v_readlane_b32 s35, v249, 44
	v_lshl_add_u64 v[88:89], v[86:87], 2, s[78:79]
	global_load_dwordx4 v[236:239], v[88:89], off
	global_load_dwordx4 v[240:243], v[88:89], off offset:64
	global_load_dwordx4 v[244:247], v[88:89], off offset:512
	global_load_dwordx4 v[82:85], v[88:89], off offset:576
	v_lshl_add_u64 v[86:87], v[86:87], 1, s[34:35]
	v_readlane_b32 s73, v248, 1
	v_readlane_b32 s74, v248, 2
	v_readlane_b32 s75, v248, 3
	v_readlane_b32 s76, v248, 4
	v_readlane_b32 s77, v248, 5
	s_waitcnt vmcnt(3)
	v_pk_fma_f32 v[76:77], v[76:77], v[162:163], v[236:237]
	v_pk_fma_f32 v[78:79], v[78:79], v[160:161], v[238:239]
	v_pk_mul_f32 v[238:239], v[166:167], v[76:77]
	global_store_dwordx4 v[88:89], v[76:79], off
	v_pk_mul_f32 v[236:237], v[164:165], v[78:79]
	v_cvt_pk_bf16_f32 v238, v238, v239
	s_nop 0
	v_cvt_pk_bf16_f32 v239, v236, v237
	global_store_dwordx2 v[86:87], v[238:239], off
	v_mul_f32_e32 v77, v77, v77
	v_mul_f32_e32 v79, v79, v79
	v_fmac_f32_e32 v77, v76, v76
	v_fmac_f32_e32 v79, v78, v78
	v_add_f32_e32 v76, v77, v79
	s_waitcnt vmcnt(4)
	v_pk_fma_f32 v[72:73], v[72:73], v[154:155], v[240:241]
	v_pk_fma_f32 v[74:75], v[74:75], v[158:159], v[242:243]
	v_pk_mul_f32 v[242:243], v[148:149], v[72:73]
	global_store_dwordx4 v[88:89], v[72:75], off offset:64
	v_pk_mul_f32 v[240:241], v[126:127], v[74:75]
	v_cvt_pk_bf16_f32 v242, v242, v243
	s_nop 0
	v_cvt_pk_bf16_f32 v243, v240, v241
	global_store_dwordx2 v[86:87], v[242:243], off offset:32
	v_mul_f32_e32 v73, v73, v73
	v_mul_f32_e32 v75, v75, v75
	v_fmac_f32_e32 v73, v72, v72
	v_fmac_f32_e32 v75, v74, v74
	v_add_f32_e32 v72, v73, v75
	v_add_f32_e32 v72, v76, v72
	s_waitcnt vmcnt(5)
	v_pk_fma_f32 v[68:69], v[68:69], v[152:153], v[244:245]
	v_pk_fma_f32 v[70:71], v[70:71], v[156:157], v[246:247]
	v_pk_mul_f32 v[246:247], v[146:147], v[68:69]
	global_store_dwordx4 v[88:89], v[68:71], off offset:512
	v_pk_mul_f32 v[244:245], v[124:125], v[70:71]
	v_cvt_pk_bf16_f32 v246, v246, v247
	s_nop 0
	v_cvt_pk_bf16_f32 v247, v244, v245
	global_store_dwordx2 v[86:87], v[246:247], off offset:256
	v_mul_f32_e32 v69, v69, v69
	v_mul_f32_e32 v71, v71, v71
	v_fmac_f32_e32 v69, v68, v68
	v_fmac_f32_e32 v71, v70, v70
	v_add_f32_e32 v68, v69, v71
	v_add_f32_e32 v70, v72, v68
	s_waitcnt vmcnt(6)
	v_pk_fma_f32 v[68:69], v[66:67], v[122:123], v[84:85]
	v_pk_fma_f32 v[66:67], v[64:65], v[120:121], v[82:83]
	v_mul_f32_e32 v65, v69, v69
	v_mul_f32_e32 v64, v67, v67
	v_fmac_f32_e32 v64, v66, v66
	v_fmac_f32_e32 v65, v68, v68
	v_add_f32_e32 v64, v64, v65
	v_add_f32_e32 v64, v70, v64
	ds_bpermute_b32 v65, v207, v64
	global_store_dwordx4 v[88:89], v[66:69], off offset:576
	s_waitcnt lgkmcnt(0)
	v_add_f32_e32 v64, v64, v65
	ds_bpermute_b32 v65, v208, v64
	v_pk_mul_f32 v[66:67], v[116:117], v[66:67]
	v_pk_mul_f32 v[68:69], v[118:119], v[68:69]
	v_cvt_pk_bf16_f32 v66, v66, v67
	s_nop 0
	v_cvt_pk_bf16_f32 v67, v68, v69
	global_store_dwordx2 v[86:87], v[66:67], off offset:288
	s_and_saveexec_b64 s[34:35], s[0:1]
	s_cbranch_execz .LBB0_1280
	v_readlane_b32 s40, v249, 31
	s_waitcnt lgkmcnt(0)
	v_add_f32_e32 v66, v64, v65
	v_lshlrev_b64 v[64:65], 6, v[80:81]
	v_readlane_b32 s41, v249, 32
	s_lshl_b32 s20, s36, 2
	s_nop 0
	v_lshl_add_u64 v[64:65], s[40:41], 0, v[64:65]
	v_lshl_add_u64 v[64:65], v[64:65], 0, s[20:21]
	s_lshl_b32 s20, s50, 2
	v_lshl_add_u64 v[64:65], v[64:65], 0, s[20:21]
	global_store_dword v[64:65], v66, off
; __device__ __forceinline__ unsigned cvt_pk_bf16(float lo, float hi) { unsigned r; asm volatile("v_cvt_pk_bf16_f32 %0, %1, %2" : "=v"(r) : "v"(lo), "v"(hi)); return r; }
;     __device__ __forceinline__ void operator()(const f32x4 (&acc)[2][2][4][2], const Unit& u, int wr, int wc, int fr, int fq) const {
;     ...
;             for (int m = 0; m < 4; ++m) { const int row = row0 + ai * HALF + m * 16; const size_t off = (size_t)row * D + col0;
;                 float ssq = 0.f;
; #pragma unroll
;                 for (int bj = 0; bj < 2; ++bj)
; #pragma unroll
;                     for (int n = 0; n < 2; ++n) { const f32x4 bs = *(const f32x4*)(base + off + bj * HALF + n * 16);
;                         const f32x4 o = bs + gv[bj][n] * acc[ai][bj][m][n];
;                         *(f32x4*)(out + off + bj * HALF + n * 16) = o;
;                         if (FOLD) { ssq += (o.x * o.x + o.y * o.y) + (o.z * o.z + o.w * o.w); const f32x4 q = o * sv[bj][n];
;                             u32x2 w; w.x = cvt_pk_bf16(q.x, q.y); w.y = cvt_pk_bf16(q.z, q.w); *(u32x2*)(U2 + off + bj * HALF + n * 16) = w; } }
;                 if (FOLD) { ssq += __shfl_xor(ssq, 16); ssq += __shfl_xor(ssq, 32);
;                     if (fq == 0) part[(size_t)row * 16 + (u.pn & 3) * 4 + wc] = ssq; } }
.LBB0_1280:
	s_or_b64 exec, exec, s[34:35]
	v_add_u32_e32 v64, 0x80, v150
	s_waitcnt lgkmcnt(0)
	v_ashrrev_i32_e32 v65, 31, v64
	v_lshlrev_b64 v[66:67], 10, v[64:65]
	v_readlane_b32 s72, v248, 0
	v_lshl_add_u64 v[70:71], v[66:67], 0, v[144:145]
	v_readlane_b32 s78, v248, 6
	v_readlane_b32 s79, v248, 7
	v_readlane_b32 s34, v249, 43
	v_readlane_b32 s35, v249, 44
	v_lshl_add_u64 v[72:73], v[70:71], 2, s[78:79]
	global_load_dwordx4 v[236:239], v[72:73], off
	global_load_dwordx4 v[240:243], v[72:73], off offset:64
	global_load_dwordx4 v[244:247], v[72:73], off offset:512
	global_load_dwordx4 v[66:69], v[72:73], off offset:576
	v_lshl_add_u64 v[70:71], v[70:71], 1, s[34:35]
	v_readlane_b32 s73, v248, 1
	v_readlane_b32 s74, v248, 2
	v_readlane_b32 s75, v248, 3
	v_readlane_b32 s76, v248, 4
	v_readlane_b32 s77, v248, 5
	s_waitcnt vmcnt(3)
	v_pk_fma_f32 v[60:61], v[60:61], v[162:163], v[236:237]
	v_pk_fma_f32 v[62:63], v[62:63], v[160:161], v[238:239]
	v_pk_mul_f32 v[238:239], v[166:167], v[60:61]
	global_store_dwordx4 v[72:73], v[60:63], off
	v_pk_mul_f32 v[236:237], v[164:165], v[62:63]
	v_cvt_pk_bf16_f32 v238, v238, v239
	s_nop 0
	v_cvt_pk_bf16_f32 v239, v236, v237
	global_store_dwordx2 v[70:71], v[238:239], off
	v_mul_f32_e32 v61, v61, v61
	v_mul_f32_e32 v63, v63, v63
	v_fmac_f32_e32 v61, v60, v60
	v_fmac_f32_e32 v63, v62, v62
	v_add_f32_e32 v60, v61, v63
	s_waitcnt vmcnt(4)
	v_pk_fma_f32 v[56:57], v[56:57], v[154:155], v[240:241]
	v_pk_fma_f32 v[58:59], v[58:59], v[158:159], v[242:243]
	v_pk_mul_f32 v[242:243], v[148:149], v[56:57]
	global_store_dwordx4 v[72:73], v[56:59], off offset:64
	v_pk_mul_f32 v[240:241], v[126:127], v[58:59]
	v_cvt_pk_bf16_f32 v242, v242, v243
	s_nop 0
	v_cvt_pk_bf16_f32 v243, v240, v241
	global_store_dwordx2 v[70:71], v[242:243], off offset:32
	v_mul_f32_e32 v57, v57, v57
	v_mul_f32_e32 v59, v59, v59
	v_fmac_f32_e32 v57, v56, v56
	v_fmac_f32_e32 v59, v58, v58
	v_add_f32_e32 v56, v57, v59
	v_add_f32_e32 v56, v60, v56
	s_waitcnt vmcnt(5)
	v_pk_fma_f32 v[52:53], v[52:53], v[152:153], v[244:245]
	v_pk_fma_f32 v[54:55], v[54:55], v[156:157], v[246:247]
	v_pk_mul_f32 v[246:247], v[146:147], v[52:53]
	global_store_dwordx4 v[72:73], v[52:55], off offset:512
	v_pk_mul_f32 v[244:245], v[124:125], v[54:55]
	v_cvt_pk_bf16_f32 v246, v246, v247
	s_nop 0
	v_cvt_pk_bf16_f32 v247, v244, v245
	global_store_dwordx2 v[70:71], v[246:247], off offset:256
	v_mul_f32_e32 v53, v53, v53
	v_mul_f32_e32 v55, v55, v55
	v_fmac_f32_e32 v53, v52, v52
	v_fmac_f32_e32 v55, v54, v54
	v_add_f32_e32 v52, v53, v55
	v_add_f32_e32 v54, v56, v52
	s_waitcnt vmcnt(6)
	v_pk_fma_f32 v[52:53], v[50:51], v[122:123], v[68:69]
	v_pk_fma_f32 v[50:51], v[48:49], v[120:121], v[66:67]
	v_mul_f32_e32 v49, v53, v53
	v_mul_f32_e32 v48, v51, v51
	v_fmac_f32_e32 v48, v50, v50
	v_fmac_f32_e32 v49, v52, v52
	v_add_f32_e32 v48, v48, v49
	v_add_f32_e32 v48, v54, v48
	ds_bpermute_b32 v49, v207, v48
	global_store_dwordx4 v[72:73], v[50:53], off offset:576
	s_waitcnt lgkmcnt(0)
	v_add_f32_e32 v48, v48, v49
	ds_bpermute_b32 v49, v208, v48
	v_pk_mul_f32 v[50:51], v[116:117], v[50:51]
	v_pk_mul_f32 v[52:53], v[118:119], v[52:53]
	v_cvt_pk_bf16_f32 v50, v50, v51
	s_nop 0
	v_cvt_pk_bf16_f32 v51, v52, v53
	global_store_dwordx2 v[70:71], v[50:51], off offset:288
	s_and_saveexec_b64 s[34:35], s[0:1]
	s_cbranch_execz .LBB0_1282
	v_readlane_b32 s40, v249, 31
	s_waitcnt lgkmcnt(0)
	v_add_f32_e32 v50, v48, v49
	v_lshlrev_b64 v[48:49], 6, v[64:65]
	v_readlane_b32 s41, v249, 32
	s_lshl_b32 s20, s36, 2
	s_nop 0
	v_lshl_add_u64 v[48:49], s[40:41], 0, v[48:49]
	v_lshl_add_u64 v[48:49], v[48:49], 0, s[20:21]
	s_lshl_b32 s20, s50, 2
	v_lshl_add_u64 v[48:49], v[48:49], 0, s[20:21]
	global_store_dword v[48:49], v50, off
.LBB0_1282:
	s_or_b64 exec, exec, s[34:35]
	v_add_u32_e32 v48, 0x90, v150
	s_waitcnt lgkmcnt(0)
	v_ashrrev_i32_e32 v49, 31, v48
	v_lshlrev_b64 v[50:51], 10, v[48:49]
	v_readlane_b32 s72, v248, 0
	v_lshl_add_u64 v[54:55], v[50:51], 0, v[144:145]
	v_readlane_b32 s78, v248, 6
	v_readlane_b32 s79, v248, 7
	v_readlane_b32 s34, v249, 43
	v_readlane_b32 s35, v249, 44
	v_lshl_add_u64 v[56:57], v[54:55], 2, s[78:79]
	global_load_dwordx4 v[236:239], v[56:57], off
	global_load_dwordx4 v[240:243], v[56:57], off offset:64
	global_load_dwordx4 v[244:247], v[56:57], off offset:512
	global_load_dwordx4 v[50:53], v[56:57], off offset:576
	v_lshl_add_u64 v[54:55], v[54:55], 1, s[34:35]
	v_readlane_b32 s73, v248, 1
	v_readlane_b32 s74, v248, 2
	v_readlane_b32 s75, v248, 3
	v_readlane_b32 s76, v248, 4
	v_readlane_b32 s77, v248, 5
	s_waitcnt vmcnt(3)
	v_pk_fma_f32 v[44:45], v[44:45], v[162:163], v[236:237]
	v_pk_fma_f32 v[46:47], v[46:47], v[160:161], v[238:239]
	v_pk_mul_f32 v[238:239], v[166:167], v[44:45]
	global_store_dwordx4 v[56:57], v[44:47], off
	v_pk_mul_f32 v[236:237], v[164:165], v[46:47]
	v_cvt_pk_bf16_f32 v238, v238, v239
	s_nop 0
	v_cvt_pk_bf16_f32 v239, v236, v237
	global_store_dwordx2 v[54:55], v[238:239], off
	v_mul_f32_e32 v45, v45, v45
	v_mul_f32_e32 v47, v47, v47
	v_fmac_f32_e32 v45, v44, v44
	v_fmac_f32_e32 v47, v46, v46
	v_add_f32_e32 v44, v45, v47
	s_waitcnt vmcnt(4)
	v_pk_fma_f32 v[40:41], v[40:41], v[154:155], v[240:241]
	v_pk_fma_f32 v[42:43], v[42:43], v[158:159], v[242:243]
	v_pk_mul_f32 v[242:243], v[148:149], v[40:41]
	global_store_dwordx4 v[56:57], v[40:43], off offset:64
	v_pk_mul_f32 v[240:241], v[126:127], v[42:43]
	v_cvt_pk_bf16_f32 v242, v242, v243
	s_nop 0
	v_cvt_pk_bf16_f32 v243, v240, v241
	global_store_dwordx2 v[54:55], v[242:243], off offset:32
	v_mul_f32_e32 v41, v41, v41
	v_mul_f32_e32 v43, v43, v43
	v_fmac_f32_e32 v41, v40, v40
	v_fmac_f32_e32 v43, v42, v42
	v_add_f32_e32 v40, v41, v43
	v_add_f32_e32 v40, v44, v40
	s_waitcnt vmcnt(5)
; __device__ __forceinline__ unsigned cvt_pk_bf16(float lo, float hi) { unsigned r; asm volatile("v_cvt_pk_bf16_f32 %0, %1, %2" : "=v"(r) : "v"(lo), "v"(hi)); return r; }
;     __device__ __forceinline__ void operator()(const f32x4 (&acc)[2][2][4][2], const Unit& u, int wr, int wc, int fr, int fq) const {
;     ...
;             for (int m = 0; m < 4; ++m) { const int row = row0 + ai * HALF + m * 16; const size_t off = (size_t)row * D + col0;
;                 float ssq = 0.f;
; #pragma unroll
;                 for (int bj = 0; bj < 2; ++bj)
; #pragma unroll
;                     for (int n = 0; n < 2; ++n) { const f32x4 bs = *(const f32x4*)(base + off + bj * HALF + n * 16);
;                         const f32x4 o = bs + gv[bj][n] * acc[ai][bj][m][n];
;                         *(f32x4*)(out + off + bj * HALF + n * 16) = o;
;                         if (FOLD) { ssq += (o.x * o.x + o.y * o.y) + (o.z * o.z + o.w * o.w); const f32x4 q = o * sv[bj][n];
;                             u32x2 w; w.x = cvt_pk_bf16(q.x, q.y); w.y = cvt_pk_bf16(q.z, q.w); *(u32x2*)(U2 + off + bj * HALF + n * 16) = w; } }
;                 if (FOLD) { ssq += __shfl_xor(ssq, 16); ssq += __shfl_xor(ssq, 32);
;                     if (fq == 0) part[(size_t)row * 16 + (u.pn & 3) * 4 + wc] = ssq; } }
	v_pk_fma_f32 v[36:37], v[36:37], v[152:153], v[244:245]
	v_pk_fma_f32 v[38:39], v[38:39], v[156:157], v[246:247]
	v_pk_mul_f32 v[246:247], v[146:147], v[36:37]
	global_store_dwordx4 v[56:57], v[36:39], off offset:512
	v_pk_mul_f32 v[244:245], v[124:125], v[38:39]
	v_cvt_pk_bf16_f32 v246, v246, v247
	s_nop 0
	v_cvt_pk_bf16_f32 v247, v244, v245
	global_store_dwordx2 v[54:55], v[246:247], off offset:256
	v_mul_f32_e32 v37, v37, v37
	v_mul_f32_e32 v39, v39, v39
	v_fmac_f32_e32 v37, v36, v36
	v_fmac_f32_e32 v39, v38, v38
	v_add_f32_e32 v36, v37, v39
	v_add_f32_e32 v38, v40, v36
	s_waitcnt vmcnt(6)
	v_pk_fma_f32 v[36:37], v[34:35], v[122:123], v[52:53]
	v_pk_fma_f32 v[34:35], v[32:33], v[120:121], v[50:51]
	v_mul_f32_e32 v33, v37, v37
	v_mul_f32_e32 v32, v35, v35
	v_fmac_f32_e32 v32, v34, v34
	v_fmac_f32_e32 v33, v36, v36
	v_add_f32_e32 v32, v32, v33
	v_add_f32_e32 v32, v38, v32
	ds_bpermute_b32 v33, v207, v32
	global_store_dwordx4 v[56:57], v[34:37], off offset:576
	s_waitcnt lgkmcnt(0)
	v_add_f32_e32 v32, v32, v33
	ds_bpermute_b32 v33, v208, v32
	v_pk_mul_f32 v[34:35], v[116:117], v[34:35]
	v_pk_mul_f32 v[36:37], v[118:119], v[36:37]
	v_cvt_pk_bf16_f32 v34, v34, v35
	s_nop 0
	v_cvt_pk_bf16_f32 v35, v36, v37
	global_store_dwordx2 v[54:55], v[34:35], off offset:288
	s_and_saveexec_b64 s[34:35], s[0:1]
	s_cbranch_execz .LBB0_1284
	v_readlane_b32 s40, v249, 31
	s_waitcnt lgkmcnt(0)
	v_add_f32_e32 v34, v32, v33
	v_lshlrev_b64 v[32:33], 6, v[48:49]
	v_readlane_b32 s41, v249, 32
	s_lshl_b32 s20, s36, 2
	s_nop 0
	v_lshl_add_u64 v[32:33], s[40:41], 0, v[32:33]
	v_lshl_add_u64 v[32:33], v[32:33], 0, s[20:21]
	s_lshl_b32 s20, s50, 2
	v_lshl_add_u64 v[32:33], v[32:33], 0, s[20:21]
	global_store_dword v[32:33], v34, off
.LBB0_1284:
	s_or_b64 exec, exec, s[34:35]
	v_add_u32_e32 v32, 0xa0, v150
	s_waitcnt lgkmcnt(0)
	v_ashrrev_i32_e32 v33, 31, v32
	v_lshlrev_b64 v[34:35], 10, v[32:33]
	v_readlane_b32 s72, v248, 0
	v_lshl_add_u64 v[38:39], v[34:35], 0, v[144:145]
	v_readlane_b32 s78, v248, 6
	v_readlane_b32 s79, v248, 7
	v_readlane_b32 s34, v249, 43
	v_readlane_b32 s35, v249, 44
	v_lshl_add_u64 v[40:41], v[38:39], 2, s[78:79]
	global_load_dwordx4 v[236:239], v[40:41], off
	global_load_dwordx4 v[240:243], v[40:41], off offset:64
	global_load_dwordx4 v[244:247], v[40:41], off offset:512
	global_load_dwordx4 v[34:37], v[40:41], off offset:576
	v_lshl_add_u64 v[38:39], v[38:39], 1, s[34:35]
	v_readlane_b32 s73, v248, 1
	v_readlane_b32 s74, v248, 2
	v_readlane_b32 s75, v248, 3
	v_readlane_b32 s76, v248, 4
	v_readlane_b32 s77, v248, 5
	s_waitcnt vmcnt(3)
	v_pk_fma_f32 v[28:29], v[28:29], v[162:163], v[236:237]
	v_pk_fma_f32 v[30:31], v[30:31], v[160:161], v[238:239]
	v_pk_mul_f32 v[238:239], v[166:167], v[28:29]
	global_store_dwordx4 v[40:41], v[28:31], off
	v_pk_mul_f32 v[236:237], v[164:165], v[30:31]
	v_cvt_pk_bf16_f32 v238, v238, v239
	s_nop 0
	v_cvt_pk_bf16_f32 v239, v236, v237
	global_store_dwordx2 v[38:39], v[238:239], off
	v_mul_f32_e32 v29, v29, v29
	v_mul_f32_e32 v31, v31, v31
	v_fmac_f32_e32 v29, v28, v28
	v_fmac_f32_e32 v31, v30, v30
	v_add_f32_e32 v28, v29, v31
	s_waitcnt vmcnt(4)
	v_pk_fma_f32 v[24:25], v[24:25], v[154:155], v[240:241]
	v_pk_fma_f32 v[26:27], v[26:27], v[158:159], v[242:243]
	v_pk_mul_f32 v[242:243], v[148:149], v[24:25]
	global_store_dwordx4 v[40:41], v[24:27], off offset:64
	v_pk_mul_f32 v[240:241], v[126:127], v[26:27]
	v_cvt_pk_bf16_f32 v242, v242, v243
	s_nop 0
	v_cvt_pk_bf16_f32 v243, v240, v241
	global_store_dwordx2 v[38:39], v[242:243], off offset:32
	v_mul_f32_e32 v25, v25, v25
	v_mul_f32_e32 v27, v27, v27
	v_fmac_f32_e32 v25, v24, v24
	v_fmac_f32_e32 v27, v26, v26
	v_add_f32_e32 v24, v25, v27
	v_add_f32_e32 v24, v28, v24
	s_waitcnt vmcnt(5)
	v_pk_fma_f32 v[20:21], v[20:21], v[152:153], v[244:245]
	v_pk_fma_f32 v[22:23], v[22:23], v[156:157], v[246:247]
	v_pk_mul_f32 v[246:247], v[146:147], v[20:21]
	global_store_dwordx4 v[40:41], v[20:23], off offset:512
	v_pk_mul_f32 v[244:245], v[124:125], v[22:23]
	v_cvt_pk_bf16_f32 v246, v246, v247
	s_nop 0
	v_cvt_pk_bf16_f32 v247, v244, v245
	global_store_dwordx2 v[38:39], v[246:247], off offset:256
	v_mul_f32_e32 v21, v21, v21
	v_mul_f32_e32 v23, v23, v23
	v_fmac_f32_e32 v21, v20, v20
	v_fmac_f32_e32 v23, v22, v22
	v_add_f32_e32 v20, v21, v23
	v_add_f32_e32 v22, v24, v20
	s_waitcnt vmcnt(6)
	v_pk_fma_f32 v[20:21], v[18:19], v[122:123], v[36:37]
	v_pk_fma_f32 v[18:19], v[16:17], v[120:121], v[34:35]
	v_mul_f32_e32 v17, v21, v21
	v_mul_f32_e32 v16, v19, v19
	v_fmac_f32_e32 v16, v18, v18
	v_fmac_f32_e32 v17, v20, v20
	v_add_f32_e32 v16, v16, v17
	v_add_f32_e32 v16, v22, v16
	ds_bpermute_b32 v17, v207, v16
	global_store_dwordx4 v[40:41], v[18:21], off offset:576
	s_waitcnt lgkmcnt(0)
	v_add_f32_e32 v16, v16, v17
	ds_bpermute_b32 v17, v208, v16
	v_pk_mul_f32 v[18:19], v[116:117], v[18:19]
	v_pk_mul_f32 v[20:21], v[118:119], v[20:21]
	v_cvt_pk_bf16_f32 v18, v18, v19
	s_nop 0
	v_cvt_pk_bf16_f32 v19, v20, v21
	global_store_dwordx2 v[38:39], v[18:19], off offset:288
	s_and_saveexec_b64 s[34:35], s[0:1]
	s_cbranch_execz .LBB0_1286
	v_readlane_b32 s40, v249, 31
	s_waitcnt lgkmcnt(0)
	v_add_f32_e32 v18, v16, v17
	v_lshlrev_b64 v[16:17], 6, v[32:33]
	v_readlane_b32 s41, v249, 32
	s_lshl_b32 s20, s36, 2
	s_nop 0
	v_lshl_add_u64 v[16:17], s[40:41], 0, v[16:17]
	v_lshl_add_u64 v[16:17], v[16:17], 0, s[20:21]
	s_lshl_b32 s20, s50, 2
	v_lshl_add_u64 v[16:17], v[16:17], 0, s[20:21]
	global_store_dword v[16:17], v18, off
; __device__ __forceinline__ unsigned cvt_pk_bf16(float lo, float hi) { unsigned r; asm volatile("v_cvt_pk_bf16_f32 %0, %1, %2" : "=v"(r) : "v"(lo), "v"(hi)); return r; }
;     __device__ __forceinline__ void operator()(const f32x4 (&acc)[2][2][4][2], const Unit& u, int wr, int wc, int fr, int fq) const {
;     ...
;             for (int m = 0; m < 4; ++m) { const int row = row0 + ai * HALF + m * 16; const size_t off = (size_t)row * D + col0;
;                 float ssq = 0.f;
; #pragma unroll
;                 for (int bj = 0; bj < 2; ++bj)
; #pragma unroll
;                     for (int n = 0; n < 2; ++n) { const f32x4 bs = *(const f32x4*)(base + off + bj * HALF + n * 16);
;                         const f32x4 o = bs + gv[bj][n] * acc[ai][bj][m][n];
;                         *(f32x4*)(out + off + bj * HALF + n * 16) = o;
;                         if (FOLD) { ssq += (o.x * o.x + o.y * o.y) + (o.z * o.z + o.w * o.w); const f32x4 q = o * sv[bj][n];
;                             u32x2 w; w.x = cvt_pk_bf16(q.x, q.y); w.y = cvt_pk_bf16(q.z, q.w); *(u32x2*)(U2 + off + bj * HALF + n * 16) = w; } }
;                 if (FOLD) { ssq += __shfl_xor(ssq, 16); ssq += __shfl_xor(ssq, 32);
;                     if (fq == 0) part[(size_t)row * 16 + (u.pn & 3) * 4 + wc] = ssq; } }
.LBB0_1286:
	s_or_b64 exec, exec, s[34:35]
	v_add_u32_e32 v16, 0xb0, v150
	s_waitcnt lgkmcnt(0)
	v_ashrrev_i32_e32 v17, 31, v16
	v_lshlrev_b64 v[18:19], 10, v[16:17]
	v_readlane_b32 s72, v248, 0
	v_lshl_add_u64 v[22:23], v[18:19], 0, v[144:145]
	v_readlane_b32 s78, v248, 6
	v_readlane_b32 s79, v248, 7
	v_readlane_b32 s34, v249, 43
	v_readlane_b32 s35, v249, 44
	v_lshl_add_u64 v[24:25], v[22:23], 2, s[78:79]
	global_load_dwordx4 v[236:239], v[24:25], off
	global_load_dwordx4 v[240:243], v[24:25], off offset:64
	global_load_dwordx4 v[244:247], v[24:25], off offset:512
	global_load_dwordx4 v[18:21], v[24:25], off offset:576
	v_lshl_add_u64 v[22:23], v[22:23], 1, s[34:35]
	v_readlane_b32 s73, v248, 1
	v_readlane_b32 s74, v248, 2
	v_readlane_b32 s75, v248, 3
	v_readlane_b32 s76, v248, 4
	v_readlane_b32 s77, v248, 5
	s_waitcnt vmcnt(3)
	v_pk_fma_f32 v[12:13], v[12:13], v[162:163], v[236:237]
	v_pk_fma_f32 v[14:15], v[14:15], v[160:161], v[238:239]
	v_pk_mul_f32 v[238:239], v[166:167], v[12:13]
	global_store_dwordx4 v[24:25], v[12:15], off
	v_pk_mul_f32 v[236:237], v[164:165], v[14:15]
	v_cvt_pk_bf16_f32 v238, v238, v239
	s_nop 0
	v_cvt_pk_bf16_f32 v239, v236, v237
	global_store_dwordx2 v[22:23], v[238:239], off
	v_mul_f32_e32 v13, v13, v13
	v_mul_f32_e32 v15, v15, v15
	v_fmac_f32_e32 v13, v12, v12
	v_fmac_f32_e32 v15, v14, v14
	v_add_f32_e32 v12, v13, v15
	s_waitcnt vmcnt(4)
	v_pk_fma_f32 v[8:9], v[8:9], v[154:155], v[240:241]
	v_pk_fma_f32 v[10:11], v[10:11], v[158:159], v[242:243]
	v_pk_mul_f32 v[242:243], v[148:149], v[8:9]
	global_store_dwordx4 v[24:25], v[8:11], off offset:64
	v_pk_mul_f32 v[240:241], v[126:127], v[10:11]
	v_cvt_pk_bf16_f32 v242, v242, v243
	s_nop 0
	v_cvt_pk_bf16_f32 v243, v240, v241
	global_store_dwordx2 v[22:23], v[242:243], off offset:32
	v_mul_f32_e32 v9, v9, v9
	v_mul_f32_e32 v11, v11, v11
	v_fmac_f32_e32 v9, v8, v8
	v_fmac_f32_e32 v11, v10, v10
	v_add_f32_e32 v8, v9, v11
	v_add_f32_e32 v8, v12, v8
	s_waitcnt vmcnt(5)
	v_pk_fma_f32 v[4:5], v[4:5], v[152:153], v[244:245]
	v_pk_fma_f32 v[6:7], v[6:7], v[156:157], v[246:247]
	v_pk_mul_f32 v[246:247], v[146:147], v[4:5]
	global_store_dwordx4 v[24:25], v[4:7], off offset:512
	v_pk_mul_f32 v[244:245], v[124:125], v[6:7]
	v_cvt_pk_bf16_f32 v246, v246, v247
	s_nop 0
	v_cvt_pk_bf16_f32 v247, v244, v245
	global_store_dwordx2 v[22:23], v[246:247], off offset:256
	v_mul_f32_e32 v5, v5, v5
	v_mul_f32_e32 v7, v7, v7
	v_fmac_f32_e32 v5, v4, v4
	v_fmac_f32_e32 v7, v6, v6
	v_add_f32_e32 v4, v5, v7
	v_add_f32_e32 v6, v8, v4
	s_waitcnt vmcnt(6)
	v_pk_fma_f32 v[4:5], v[2:3], v[122:123], v[20:21]
	v_pk_fma_f32 v[2:3], v[0:1], v[120:121], v[18:19]
	v_mul_f32_e32 v1, v5, v5
	v_mul_f32_e32 v0, v3, v3
	v_fmac_f32_e32 v0, v2, v2
	v_fmac_f32_e32 v1, v4, v4
	v_add_f32_e32 v0, v0, v1
	v_add_f32_e32 v0, v6, v0
	ds_bpermute_b32 v1, v207, v0
	global_store_dwordx4 v[24:25], v[2:5], off offset:576
	s_waitcnt lgkmcnt(0)
	v_add_f32_e32 v0, v0, v1
	ds_bpermute_b32 v1, v208, v0
	v_pk_mul_f32 v[2:3], v[116:117], v[2:3]
	v_pk_mul_f32 v[4:5], v[118:119], v[4:5]
	v_cvt_pk_bf16_f32 v2, v2, v3
	s_nop 0
	v_cvt_pk_bf16_f32 v3, v4, v5
	global_store_dwordx2 v[22:23], v[2:3], off offset:288
	s_and_saveexec_b64 s[34:35], s[0:1]
	s_cbranch_execz .LBB0_1288
	v_readlane_b32 s40, v249, 31
	s_waitcnt lgkmcnt(0)
	v_add_f32_e32 v2, v0, v1
	v_lshlrev_b64 v[0:1], 6, v[16:17]
	v_readlane_b32 s41, v249, 32
	s_lshl_b32 s20, s36, 2
	s_nop 0
	v_lshl_add_u64 v[0:1], s[40:41], 0, v[0:1]
	v_lshl_add_u64 v[0:1], v[0:1], 0, s[20:21]
	s_lshl_b32 s20, s50, 2
	v_lshl_add_u64 v[0:1], v[0:1], 0, s[20:21]
	global_store_dword v[0:1], v2, off

;     __device__ __forceinline__ void operator()(const f32x4 (&acc)[2][2][4][2], const Unit& u, int wr, int wc, int fr, int fq) const {
;     ...
;         const float* gp = gate + (size_t)(u.pm >> 4) * NMOD;
;         f32x4 gv[2][2], sv[2][2];
; #pragma unroll
;         for (int bj = 0; bj < 2; ++bj)
; #pragma unroll
;             for (int n = 0; n < 2; ++n) { gv[bj][n] = *(const f32x4*)(gp + col0 + bj * HALF + n * 16) * (HALFSC ? 0.5f : 1.0f);
;                 if (FOLD) sv[bj][n] = *(const f32x4*)(scn + (size_t)(u.pm >> 4) * NMOD + col0 + bj * HALF + n * 16) + 1.0f; }
; #pragma unroll
;         for (int ai = 0; ai < 2; ++ai)
; #pragma unroll
;             for (int m = 0; m < 4; ++m) { const int row = row0 + ai * HALF + m * 16; const size_t off = (size_t)row * D + col0;
;                 float ssq = 0.f;
; #pragma unroll
;                 for (int bj = 0; bj < 2; ++bj)
; #pragma unroll
;                     for (int n = 0; n < 2; ++n) { const f32x4 bs = *(const f32x4*)(base + off + bj * HALF + n * 16);
;                         const f32x4 o = bs + gv[bj][n] * acc[ai][bj][m][n];
;                         *(f32x4*)(out + off + bj * HALF + n * 16) = o;
.LBB0_1440:
	s_ashr_i32 s28, s55, 4
	v_lshl_or_b32 v144, s56, 8, v166
	s_mul_hi_i32 s29, s28, 0x9000
	s_mul_i32 s28, s28, 0x9000
	s_add_u32 s28, s43, s28
	v_ashrrev_i32_e32 v145, 31, v144
	s_addc_u32 s29, s44, s29
	v_lshlrev_b64 v[162:163], 2, v[144:145]
	v_lshl_add_u64 v[160:161], s[28:29], 0, v[162:163]
	global_load_dwordx4 v[144:147], v[160:161], off
	v_lshl_add_u32 v174, s55, 8, v164
	v_ashrrev_i32_e32 v175, 31, v174
	v_readlane_b32 s56, v248, 0
	v_readlane_b32 s62, v248, 6
	v_readlane_b32 s63, v248, 7
	s_mov_b64 s[28:29], 0x80000
	v_readlane_b32 s57, v248, 1
	v_readlane_b32 s58, v248, 2
	v_readlane_b32 s59, v248, 3
	v_readlane_b32 s60, v248, 4
	v_readlane_b32 s61, v248, 5
	s_waitcnt vmcnt(0)
	v_pk_mul_f32 v[156:157], v[146:147], 0.5 op_sel_hi:[1,0]
	v_pk_mul_f32 v[158:159], v[144:145], 0.5 op_sel_hi:[1,0]
	global_load_dwordx4 v[144:147], v[160:161], off offset:64
	s_waitcnt vmcnt(0)
	v_pk_mul_f32 v[152:153], v[146:147], 0.5 op_sel_hi:[1,0]
	v_pk_mul_f32 v[154:155], v[144:145], 0.5 op_sel_hi:[1,0]
	global_load_dwordx4 v[144:147], v[160:161], off offset:512
	s_waitcnt vmcnt(0)
	v_pk_mul_f32 v[148:149], v[146:147], 0.5 op_sel_hi:[1,0]
	v_pk_mul_f32 v[150:151], v[144:145], 0.5 op_sel_hi:[1,0]
	global_load_dwordx4 v[144:147], v[160:161], off offset:576
	v_lshlrev_b64 v[160:161], 12, v[174:175]
	v_lshl_add_u64 v[160:161], s[62:63], 0, v[160:161]
	v_lshl_add_u64 v[160:161], v[160:161], 0, v[162:163]
	global_load_dwordx4 v[216:219], v[160:161], off
	global_load_dwordx4 v[220:223], v[160:161], off offset:64
	global_load_dwordx4 v[236:239], v[160:161], off offset:512
	global_load_dwordx4 v[240:243], v[160:161], off offset:576
	s_waitcnt vmcnt(3)
	v_pk_mul_f32 v[146:147], v[146:147], 0.5 op_sel_hi:[1,0]
	v_pk_mul_f32 v[144:145], v[144:145], 0.5 op_sel_hi:[1,0]
	v_pk_fma_f32 v[126:127], v[126:127], v[156:157], v[218:219]
	v_pk_fma_f32 v[124:125], v[124:125], v[158:159], v[216:217]
	global_store_dwordx4 v[160:161], v[124:127], off
	s_waitcnt vmcnt(3)
	v_pk_fma_f32 v[122:123], v[122:123], v[152:153], v[222:223]
	v_pk_fma_f32 v[120:121], v[120:121], v[154:155], v[220:221]
	global_store_dwordx4 v[160:161], v[120:123], off offset:64
	s_waitcnt vmcnt(3)
	v_pk_fma_f32 v[118:119], v[118:119], v[148:149], v[238:239]
	v_pk_fma_f32 v[116:117], v[116:117], v[150:151], v[236:237]
	global_store_dwordx4 v[160:161], v[116:119], off offset:512
	s_waitcnt vmcnt(3)
	v_pk_fma_f32 v[114:115], v[114:115], v[146:147], v[242:243]
	v_pk_fma_f32 v[112:113], v[112:113], v[144:145], v[240:241]
	global_store_dwordx4 v[160:161], v[112:115], off offset:576
	s_nop 1
	v_or_b32_e32 v112, 16, v174
	v_ashrrev_i32_e32 v113, 31, v112
	v_lshlrev_b64 v[112:113], 12, v[112:113]
	v_lshl_add_u64 v[112:113], s[62:63], 0, v[112:113]
	v_lshl_add_u64 v[116:117], v[112:113], 0, v[162:163]
	global_load_dwordx4 v[216:219], v[116:117], off
	global_load_dwordx4 v[220:223], v[116:117], off offset:64
	global_load_dwordx4 v[236:239], v[116:117], off offset:512
	global_load_dwordx4 v[240:243], v[116:117], off offset:576
	s_waitcnt vmcnt(3)
	v_pk_fma_f32 v[110:111], v[110:111], v[156:157], v[218:219]
	v_pk_fma_f32 v[108:109], v[108:109], v[158:159], v[216:217]
	global_store_dwordx4 v[116:117], v[108:111], off
	s_waitcnt vmcnt(3)
	v_pk_fma_f32 v[106:107], v[106:107], v[152:153], v[222:223]
	v_pk_fma_f32 v[104:105], v[104:105], v[154:155], v[220:221]
	global_store_dwordx4 v[116:117], v[104:107], off offset:64
	s_waitcnt vmcnt(3)
	v_pk_fma_f32 v[102:103], v[102:103], v[148:149], v[238:239]
	v_pk_fma_f32 v[100:101], v[100:101], v[150:151], v[236:237]
	global_store_dwordx4 v[116:117], v[100:103], off offset:512
	s_waitcnt vmcnt(3)
	v_pk_fma_f32 v[98:99], v[98:99], v[146:147], v[242:243]
	v_pk_fma_f32 v[96:97], v[96:97], v[144:145], v[240:241]
	global_store_dwordx4 v[116:117], v[96:99], off offset:576
	s_nop 1
	v_or_b32_e32 v96, 32, v174
	v_ashrrev_i32_e32 v97, 31, v96
	v_lshlrev_b64 v[96:97], 12, v[96:97]
	v_lshl_add_u64 v[96:97], s[62:63], 0, v[96:97]
	v_lshl_add_u64 v[100:101], v[96:97], 0, v[162:163]
	global_load_dwordx4 v[216:219], v[100:101], off
	global_load_dwordx4 v[220:223], v[100:101], off offset:64
	global_load_dwordx4 v[236:239], v[100:101], off offset:512
	global_load_dwordx4 v[240:243], v[100:101], off offset:576
	s_waitcnt vmcnt(3)
	v_pk_fma_f32 v[94:95], v[94:95], v[156:157], v[218:219]
	v_pk_fma_f32 v[92:93], v[92:93], v[158:159], v[216:217]
	global_store_dwordx4 v[100:101], v[92:95], off
	s_waitcnt vmcnt(3)
	v_pk_fma_f32 v[90:91], v[90:91], v[152:153], v[222:223]
	v_pk_fma_f32 v[88:89], v[88:89], v[154:155], v[220:221]
	global_store_dwordx4 v[100:101], v[88:91], off offset:64
	s_waitcnt vmcnt(3)
	v_pk_fma_f32 v[86:87], v[86:87], v[148:149], v[238:239]
	v_pk_fma_f32 v[84:85], v[84:85], v[150:151], v[236:237]
	global_store_dwordx4 v[100:101], v[84:87], off offset:512
	s_waitcnt vmcnt(3)
	v_pk_fma_f32 v[82:83], v[82:83], v[146:147], v[242:243]
	v_pk_fma_f32 v[80:81], v[80:81], v[144:145], v[240:241]
	global_store_dwordx4 v[100:101], v[80:83], off offset:576
	s_nop 1
	v_or_b32_e32 v80, 48, v174
	v_ashrrev_i32_e32 v81, 31, v80
	v_lshlrev_b64 v[80:81], 12, v[80:81]
	v_lshl_add_u64 v[80:81], s[62:63], 0, v[80:81]
	v_lshl_add_u64 v[84:85], v[80:81], 0, v[162:163]
	global_load_dwordx4 v[216:219], v[84:85], off
	global_load_dwordx4 v[220:223], v[84:85], off offset:64
	global_load_dwordx4 v[236:239], v[84:85], off offset:512
	global_load_dwordx4 v[240:243], v[84:85], off offset:576
	s_waitcnt vmcnt(3)
;     __device__ __forceinline__ void operator()(const f32x4 (&acc)[2][2][4][2], const Unit& u, int wr, int wc, int fr, int fq) const {
;     ...
;             for (int m = 0; m < 4; ++m) { const int row = row0 + ai * HALF + m * 16; const size_t off = (size_t)row * D + col0;
;                 float ssq = 0.f;
; #pragma unroll
;                 for (int bj = 0; bj < 2; ++bj)
; #pragma unroll
;                     for (int n = 0; n < 2; ++n) { const f32x4 bs = *(const f32x4*)(base + off + bj * HALF + n * 16);
;                         const f32x4 o = bs + gv[bj][n] * acc[ai][bj][m][n];
;                         *(f32x4*)(out + off + bj * HALF + n * 16) = o;
	v_pk_fma_f32 v[78:79], v[78:79], v[156:157], v[218:219]
	v_pk_fma_f32 v[76:77], v[76:77], v[158:159], v[216:217]
	global_store_dwordx4 v[84:85], v[76:79], off
	s_waitcnt vmcnt(3)
	v_pk_fma_f32 v[74:75], v[74:75], v[152:153], v[222:223]
	v_pk_fma_f32 v[72:73], v[72:73], v[154:155], v[220:221]
	global_store_dwordx4 v[84:85], v[72:75], off offset:64
	s_waitcnt vmcnt(3)
	v_pk_fma_f32 v[70:71], v[70:71], v[148:149], v[238:239]
	v_pk_fma_f32 v[68:69], v[68:69], v[150:151], v[236:237]
	global_store_dwordx4 v[84:85], v[68:71], off offset:512
	s_waitcnt vmcnt(3)
	v_pk_fma_f32 v[64:65], v[64:65], v[144:145], v[240:241]
	v_lshl_add_u64 v[68:69], v[160:161], 0, s[28:29]
	s_mov_b32 s28, 0x80000
	v_pk_fma_f32 v[66:67], v[66:67], v[146:147], v[242:243]
	v_add_co_u32_e32 v70, vcc, s28, v160
	global_store_dwordx4 v[84:85], v[64:67], off offset:576
	s_nop 0
	v_addc_co_u32_e32 v71, vcc, 0, v161, vcc
	global_load_dwordx4 v[216:219], v[70:71], off
	global_load_dwordx4 v[220:223], v[68:69], off offset:64
	global_load_dwordx4 v[236:239], v[68:69], off offset:512
	global_load_dwordx4 v[240:243], v[68:69], off offset:576
	s_mov_b64 s[28:29], 0x90000
	s_waitcnt vmcnt(3)
	v_pk_fma_f32 v[62:63], v[62:63], v[156:157], v[218:219]
	v_pk_fma_f32 v[60:61], v[60:61], v[158:159], v[216:217]
	global_store_dwordx4 v[70:71], v[60:63], off
	s_waitcnt vmcnt(3)
	v_pk_fma_f32 v[58:59], v[58:59], v[152:153], v[222:223]
	v_pk_fma_f32 v[56:57], v[56:57], v[154:155], v[220:221]
	global_store_dwordx4 v[68:69], v[56:59], off offset:64
	s_waitcnt vmcnt(3)
	v_pk_fma_f32 v[54:55], v[54:55], v[148:149], v[238:239]
	v_pk_fma_f32 v[52:53], v[52:53], v[150:151], v[236:237]
	global_store_dwordx4 v[68:69], v[52:55], off offset:512
	s_waitcnt vmcnt(3)
	v_pk_fma_f32 v[50:51], v[50:51], v[146:147], v[242:243]
	v_pk_fma_f32 v[48:49], v[48:49], v[144:145], v[240:241]
	global_store_dwordx4 v[68:69], v[48:51], off offset:576
	s_nop 1
	v_lshl_add_u64 v[48:49], v[160:161], 0, s[28:29]
	s_mov_b32 s28, 0x90000
	v_add_co_u32_e32 v54, vcc, s28, v160
	s_mov_b64 s[28:29], 0xa0000
	s_nop 0
	v_addc_co_u32_e32 v55, vcc, 0, v161, vcc
	global_load_dwordx4 v[216:219], v[54:55], off
	global_load_dwordx4 v[220:223], v[48:49], off offset:64
	global_load_dwordx4 v[236:239], v[48:49], off offset:512
	global_load_dwordx4 v[240:243], v[48:49], off offset:576
	s_waitcnt vmcnt(3)
	v_pk_fma_f32 v[46:47], v[46:47], v[156:157], v[218:219]
	v_pk_fma_f32 v[44:45], v[44:45], v[158:159], v[216:217]
	global_store_dwordx4 v[54:55], v[44:47], off
	s_waitcnt vmcnt(3)
	v_pk_fma_f32 v[42:43], v[42:43], v[152:153], v[222:223]
	v_pk_fma_f32 v[40:41], v[40:41], v[154:155], v[220:221]
	global_store_dwordx4 v[48:49], v[40:43], off offset:64
	s_waitcnt vmcnt(3)
	v_pk_fma_f32 v[38:39], v[38:39], v[148:149], v[238:239]
	v_pk_fma_f32 v[36:37], v[36:37], v[150:151], v[236:237]
	global_store_dwordx4 v[48:49], v[36:39], off offset:512
	s_waitcnt vmcnt(3)
	v_pk_fma_f32 v[32:33], v[32:33], v[144:145], v[240:241]
	v_lshl_add_u64 v[36:37], v[160:161], 0, s[28:29]
	s_mov_b32 s28, 0xa0000
	v_pk_fma_f32 v[34:35], v[34:35], v[146:147], v[242:243]
	v_add_co_u32_e32 v38, vcc, s28, v160
	global_store_dwordx4 v[48:49], v[32:35], off offset:576
	s_nop 0
	v_addc_co_u32_e32 v39, vcc, 0, v161, vcc
	global_load_dwordx4 v[216:219], v[38:39], off
	global_load_dwordx4 v[220:223], v[36:37], off offset:64
	global_load_dwordx4 v[236:239], v[36:37], off offset:512
	global_load_dwordx4 v[240:243], v[36:37], off offset:576
	s_mov_b64 s[28:29], 0xb0000
	s_waitcnt vmcnt(3)
	v_pk_fma_f32 v[30:31], v[30:31], v[156:157], v[218:219]
	v_pk_fma_f32 v[28:29], v[28:29], v[158:159], v[216:217]
	global_store_dwordx4 v[38:39], v[28:31], off
	s_waitcnt vmcnt(3)
	v_pk_fma_f32 v[26:27], v[26:27], v[152:153], v[222:223]
	v_pk_fma_f32 v[24:25], v[24:25], v[154:155], v[220:221]
	global_store_dwordx4 v[36:37], v[24:27], off offset:64
	s_waitcnt vmcnt(3)
	v_pk_fma_f32 v[22:23], v[22:23], v[148:149], v[238:239]
	v_pk_fma_f32 v[20:21], v[20:21], v[150:151], v[236:237]
	global_store_dwordx4 v[36:37], v[20:23], off offset:512
	s_waitcnt vmcnt(3)
	v_pk_fma_f32 v[18:19], v[18:19], v[146:147], v[242:243]
	v_pk_fma_f32 v[16:17], v[16:17], v[144:145], v[240:241]
	global_store_dwordx4 v[36:37], v[16:19], off offset:576
	s_nop 1
	v_lshl_add_u64 v[16:17], v[160:161], 0, s[28:29]
	s_mov_b32 s28, 0xb0000
	v_add_co_u32_e32 v22, vcc, s28, v160
	s_mov_b64 s[28:29], -1
	s_nop 0
	v_addc_co_u32_e32 v23, vcc, 0, v161, vcc
	global_load_dwordx4 v[216:219], v[22:23], off
	global_load_dwordx4 v[220:223], v[16:17], off offset:64
	global_load_dwordx4 v[236:239], v[16:17], off offset:512
	global_load_dwordx4 v[240:243], v[16:17], off offset:576
	s_and_b64 vcc, exec, s[0:1]
	s_waitcnt vmcnt(3)
	v_pk_fma_f32 v[14:15], v[14:15], v[156:157], v[218:219]
	v_pk_fma_f32 v[12:13], v[12:13], v[158:159], v[216:217]
	global_store_dwordx4 v[22:23], v[12:15], off
	s_waitcnt vmcnt(3)
	v_pk_fma_f32 v[10:11], v[10:11], v[152:153], v[222:223]
	v_pk_fma_f32 v[8:9], v[8:9], v[154:155], v[220:221]
	global_store_dwordx4 v[16:17], v[8:11], off offset:64
	s_waitcnt vmcnt(3)
	v_pk_fma_f32 v[6:7], v[6:7], v[148:149], v[238:239]
	v_pk_fma_f32 v[4:5], v[4:5], v[150:151], v[236:237]
	global_store_dwordx4 v[16:17], v[4:7], off offset:512
	s_waitcnt vmcnt(3)
	v_pk_fma_f32 v[2:3], v[2:3], v[146:147], v[242:243]
	v_pk_fma_f32 v[0:1], v[0:1], v[144:145], v[240:241]
	global_store_dwordx4 v[16:17], v[0:3], off offset:576
	s_cbranch_vccnz .LBB0_1424
	s_andn2_b64 vcc, exec, s[14:15]
	s_cbranch_vccnz .LBB0_1423
	s_barrier
	s_branch .LBB0_1423

; __device__ __forceinline__ unsigned cvt_pk_bf16(float lo, float hi) { unsigned r; asm volatile("v_cvt_pk_bf16_f32 %0, %1, %2" : "=v"(r) : "v"(lo), "v"(hi)); return r; }
;     __device__ __forceinline__ void operator()(const f32x4 (&acc)[2][2][4][2], const Unit& u, int wr, int wc, int fr, int fq) const {
;     ...
;         for (int ai = 0; ai < 2; ++ai)
; #pragma unroll
;             for (int m = 0; m < 4; ++m) { const int row = row0 + ai * HALF + m * 16; const size_t off = (size_t)row * D + col0;
;                 float ssq = 0.f;
; #pragma unroll
;                 for (int bj = 0; bj < 2; ++bj)
; #pragma unroll
;                     for (int n = 0; n < 2; ++n) { const f32x4 bs = *(const f32x4*)(base + off + bj * HALF + n * 16);
;                         const f32x4 o = bs + gv[bj][n] * acc[ai][bj][m][n];
;                         *(f32x4*)(out + off + bj * HALF + n * 16) = o;
;                         if (FOLD) { ssq += (o.x * o.x + o.y * o.y) + (o.z * o.z + o.w * o.w); const f32x4 q = o * sv[bj][n];
;                             u32x2 w; w.x = cvt_pk_bf16(q.x, q.y); w.y = cvt_pk_bf16(q.z, q.w); *(u32x2*)(U2 + off + bj * HALF + n * 16) = w; } }
;                 if (FOLD) { ssq += __shfl_xor(ssq, 16); ssq += __shfl_xor(ssq, 32);
;                     if (fq == 0) part[(size_t)row * 16 + (u.pn & 3) * 4 + wc] = ssq; } }
.LBB0_2447:
	s_or_b64 exec, exec, s[6:7]
	v_or_b32_e32 v128, 16, v162
	s_waitcnt lgkmcnt(0)
	v_ashrrev_i32_e32 v129, 31, v128
	v_lshlrev_b64 v[130:131], 10, v[128:129]
	v_readlane_b32 s60, v248, 0
	v_lshl_add_u64 v[130:131], v[130:131], 0, v[160:161]
	v_readlane_b32 s66, v248, 6
	v_readlane_b32 s67, v248, 7
	v_readlane_b32 s6, v249, 43
	v_readlane_b32 s7, v249, 44
	v_lshl_add_u64 v[178:179], v[130:131], 2, s[66:67]
	global_load_dwordx4 v[236:239], v[178:179], off
	global_load_dwordx4 v[240:243], v[178:179], off offset:64
	global_load_dwordx4 v[244:247], v[178:179], off offset:512
	global_load_dwordx4 v[174:177], v[178:179], off offset:576
	v_lshl_add_u64 v[130:131], v[130:131], 1, s[6:7]
	v_readlane_b32 s61, v248, 1
	v_readlane_b32 s62, v248, 2
	v_readlane_b32 s63, v248, 3
	v_readlane_b32 s64, v248, 4
	v_readlane_b32 s65, v248, 5
	s_waitcnt vmcnt(3)
	v_pk_fma_f32 v[124:125], v[124:125], v[100:101], v[236:237]
	v_pk_fma_f32 v[126:127], v[126:127], v[102:103], v[238:239]
	v_pk_mul_f32 v[238:239], v[166:167], v[124:125]
	global_store_dwordx4 v[178:179], v[124:127], off
	v_pk_mul_f32 v[236:237], v[164:165], v[126:127]
	v_cvt_pk_bf16_f32 v238, v238, v239
	s_nop 0
	v_cvt_pk_bf16_f32 v239, v236, v237
	global_store_dwordx2 v[130:131], v[238:239], off
	v_mul_f32_e32 v125, v125, v125
	v_mul_f32_e32 v127, v127, v127
	v_fmac_f32_e32 v125, v124, v124
	v_fmac_f32_e32 v127, v126, v126
	v_add_f32_e32 v124, v125, v127
	s_waitcnt vmcnt(4)
	v_pk_fma_f32 v[120:121], v[120:121], v[108:109], v[240:241]
	v_pk_fma_f32 v[122:123], v[122:123], v[110:111], v[242:243]
	v_pk_mul_f32 v[242:243], v[142:143], v[120:121]
	global_store_dwordx4 v[178:179], v[120:123], off offset:64
	v_pk_mul_f32 v[240:241], v[140:141], v[122:123]
	v_cvt_pk_bf16_f32 v242, v242, v243
	s_nop 0
	v_cvt_pk_bf16_f32 v243, v240, v241
	global_store_dwordx2 v[130:131], v[242:243], off offset:32
	v_mul_f32_e32 v121, v121, v121
	v_mul_f32_e32 v123, v123, v123
	v_fmac_f32_e32 v121, v120, v120
	v_fmac_f32_e32 v123, v122, v122
	v_add_f32_e32 v120, v121, v123
	v_add_f32_e32 v120, v124, v120
	s_waitcnt vmcnt(5)
	v_pk_fma_f32 v[116:117], v[116:117], v[104:105], v[244:245]
	v_pk_fma_f32 v[118:119], v[118:119], v[106:107], v[246:247]
	v_pk_mul_f32 v[246:247], v[138:139], v[116:117]
	global_store_dwordx4 v[178:179], v[116:119], off offset:512
	v_pk_mul_f32 v[244:245], v[136:137], v[118:119]
	v_cvt_pk_bf16_f32 v246, v246, v247
	s_nop 0
	v_cvt_pk_bf16_f32 v247, v244, v245
	global_store_dwordx2 v[130:131], v[246:247], off offset:256
	v_mul_f32_e32 v117, v117, v117
	v_mul_f32_e32 v119, v119, v119
	v_fmac_f32_e32 v117, v116, v116
	v_fmac_f32_e32 v119, v118, v118
	v_add_f32_e32 v116, v117, v119
	v_add_f32_e32 v118, v120, v116
	s_waitcnt vmcnt(6)
	v_pk_fma_f32 v[116:117], v[114:115], v[98:99], v[176:177]
	v_pk_fma_f32 v[114:115], v[112:113], v[96:97], v[174:175]
	v_mul_f32_e32 v113, v117, v117
	v_mul_f32_e32 v112, v115, v115
	v_fmac_f32_e32 v112, v114, v114
	v_fmac_f32_e32 v113, v116, v116
	v_add_f32_e32 v112, v112, v113
	v_add_f32_e32 v112, v118, v112
	ds_bpermute_b32 v113, v207, v112
	global_store_dwordx4 v[178:179], v[114:117], off offset:576
	s_waitcnt lgkmcnt(0)
	v_add_f32_e32 v112, v112, v113
	ds_bpermute_b32 v113, v208, v112
	v_pk_mul_f32 v[114:115], v[132:133], v[114:115]
	v_pk_mul_f32 v[116:117], v[134:135], v[116:117]
	v_cvt_pk_bf16_f32 v114, v114, v115
	s_nop 0
	v_cvt_pk_bf16_f32 v115, v116, v117
	global_store_dwordx2 v[130:131], v[114:115], off offset:288
	s_and_saveexec_b64 s[6:7], s[0:1]
	s_cbranch_execz .LBB0_2449
	v_readlane_b32 s34, v249, 31
	v_lshlrev_b64 v[114:115], 6, v[128:129]
	v_readlane_b32 s35, v249, 32
	s_lshl_b32 s14, s27, 2
	s_waitcnt lgkmcnt(0)
	v_add_f32_e32 v112, v112, v113
	v_lshl_add_u64 v[114:115], s[34:35], 0, v[114:115]
	v_lshl_add_u64 v[114:115], v[114:115], 0, s[14:15]
	s_lshl_b32 s14, s49, 2
	v_lshl_add_u64 v[114:115], v[114:115], 0, s[14:15]
	global_store_dword v[114:115], v112, off
.LBB0_2449:
	s_or_b64 exec, exec, s[6:7]
	v_or_b32_e32 v112, 32, v162
	s_waitcnt lgkmcnt(0)
	v_ashrrev_i32_e32 v113, 31, v112
	v_lshlrev_b64 v[114:115], 10, v[112:113]
	v_readlane_b32 s60, v248, 0
	v_lshl_add_u64 v[118:119], v[114:115], 0, v[160:161]
	v_readlane_b32 s66, v248, 6
	v_readlane_b32 s67, v248, 7
	v_readlane_b32 s6, v249, 43
	v_readlane_b32 s7, v249, 44
	v_lshl_add_u64 v[120:121], v[118:119], 2, s[66:67]
	global_load_dwordx4 v[236:239], v[120:121], off
	global_load_dwordx4 v[240:243], v[120:121], off offset:64
	global_load_dwordx4 v[244:247], v[120:121], off offset:512
	global_load_dwordx4 v[114:117], v[120:121], off offset:576
	v_lshl_add_u64 v[118:119], v[118:119], 1, s[6:7]
	v_readlane_b32 s61, v248, 1
	v_readlane_b32 s62, v248, 2
	v_readlane_b32 s63, v248, 3
	v_readlane_b32 s64, v248, 4
	v_readlane_b32 s65, v248, 5
	s_waitcnt vmcnt(3)
	v_pk_fma_f32 v[92:93], v[92:93], v[100:101], v[236:237]
	v_pk_fma_f32 v[94:95], v[94:95], v[102:103], v[238:239]
	v_pk_mul_f32 v[238:239], v[166:167], v[92:93]
	global_store_dwordx4 v[120:121], v[92:95], off
	v_pk_mul_f32 v[236:237], v[164:165], v[94:95]
	v_cvt_pk_bf16_f32 v238, v238, v239
	s_nop 0
	v_cvt_pk_bf16_f32 v239, v236, v237
	global_store_dwordx2 v[118:119], v[238:239], off
	v_mul_f32_e32 v93, v93, v93
	v_mul_f32_e32 v95, v95, v95
	v_fmac_f32_e32 v93, v92, v92
	v_fmac_f32_e32 v95, v94, v94
	v_add_f32_e32 v92, v93, v95
	s_waitcnt vmcnt(4)
	v_pk_fma_f32 v[88:89], v[88:89], v[108:109], v[240:241]
	v_pk_fma_f32 v[90:91], v[90:91], v[110:111], v[242:243]
	v_pk_mul_f32 v[242:243], v[142:143], v[88:89]
	global_store_dwordx4 v[120:121], v[88:91], off offset:64
	v_pk_mul_f32 v[240:241], v[140:141], v[90:91]
	v_cvt_pk_bf16_f32 v242, v242, v243
	s_nop 0
	v_cvt_pk_bf16_f32 v243, v240, v241
	global_store_dwordx2 v[118:119], v[242:243], off offset:32
	v_mul_f32_e32 v89, v89, v89
	v_mul_f32_e32 v91, v91, v91
	v_fmac_f32_e32 v89, v88, v88
	v_fmac_f32_e32 v91, v90, v90
	v_add_f32_e32 v88, v89, v91
	v_add_f32_e32 v88, v92, v88
	s_waitcnt vmcnt(5)
; __device__ __forceinline__ unsigned cvt_pk_bf16(float lo, float hi) { unsigned r; asm volatile("v_cvt_pk_bf16_f32 %0, %1, %2" : "=v"(r) : "v"(lo), "v"(hi)); return r; }
;     __device__ __forceinline__ void operator()(const f32x4 (&acc)[2][2][4][2], const Unit& u, int wr, int wc, int fr, int fq) const {
;     ...
;         for (int ai = 0; ai < 2; ++ai)
; #pragma unroll
;             for (int m = 0; m < 4; ++m) { const int row = row0 + ai * HALF + m * 16; const size_t off = (size_t)row * D + col0;
;                 float ssq = 0.f;
; #pragma unroll
;                 for (int bj = 0; bj < 2; ++bj)
; #pragma unroll
;                     for (int n = 0; n < 2; ++n) { const f32x4 bs = *(const f32x4*)(base + off + bj * HALF + n * 16);
;                         const f32x4 o = bs + gv[bj][n] * acc[ai][bj][m][n];
;                         *(f32x4*)(out + off + bj * HALF + n * 16) = o;
;                         if (FOLD) { ssq += (o.x * o.x + o.y * o.y) + (o.z * o.z + o.w * o.w); const f32x4 q = o * sv[bj][n];
;                             u32x2 w; w.x = cvt_pk_bf16(q.x, q.y); w.y = cvt_pk_bf16(q.z, q.w); *(u32x2*)(U2 + off + bj * HALF + n * 16) = w; } }
;                 if (FOLD) { ssq += __shfl_xor(ssq, 16); ssq += __shfl_xor(ssq, 32);
;                     if (fq == 0) part[(size_t)row * 16 + (u.pn & 3) * 4 + wc] = ssq; } }
	v_pk_fma_f32 v[84:85], v[84:85], v[104:105], v[244:245]
	v_pk_fma_f32 v[86:87], v[86:87], v[106:107], v[246:247]
	v_pk_mul_f32 v[246:247], v[138:139], v[84:85]
	global_store_dwordx4 v[120:121], v[84:87], off offset:512
	v_pk_mul_f32 v[244:245], v[136:137], v[86:87]
	v_cvt_pk_bf16_f32 v246, v246, v247
	s_nop 0
	v_cvt_pk_bf16_f32 v247, v244, v245
	global_store_dwordx2 v[118:119], v[246:247], off offset:256
	v_mul_f32_e32 v85, v85, v85
	v_mul_f32_e32 v87, v87, v87
	v_fmac_f32_e32 v85, v84, v84
	v_fmac_f32_e32 v87, v86, v86
	v_add_f32_e32 v84, v85, v87
	v_add_f32_e32 v86, v88, v84
	s_waitcnt vmcnt(6)
	v_pk_fma_f32 v[84:85], v[82:83], v[98:99], v[116:117]
	v_pk_fma_f32 v[82:83], v[80:81], v[96:97], v[114:115]
	v_mul_f32_e32 v81, v85, v85
	v_mul_f32_e32 v80, v83, v83
	v_fmac_f32_e32 v80, v82, v82
	v_fmac_f32_e32 v81, v84, v84
	v_add_f32_e32 v80, v80, v81
	v_add_f32_e32 v80, v86, v80
	ds_bpermute_b32 v81, v207, v80
	global_store_dwordx4 v[120:121], v[82:85], off offset:576
	s_waitcnt lgkmcnt(0)
	v_add_f32_e32 v80, v80, v81
	ds_bpermute_b32 v81, v208, v80
	v_pk_mul_f32 v[82:83], v[132:133], v[82:83]
	v_pk_mul_f32 v[84:85], v[134:135], v[84:85]
	v_cvt_pk_bf16_f32 v82, v82, v83
	s_nop 0
	v_cvt_pk_bf16_f32 v83, v84, v85
	global_store_dwordx2 v[118:119], v[82:83], off offset:288
	s_and_saveexec_b64 s[6:7], s[0:1]
	s_cbranch_execz .LBB0_2451
	v_readlane_b32 s34, v249, 31
	v_lshlrev_b64 v[82:83], 6, v[112:113]
	v_readlane_b32 s35, v249, 32
	s_lshl_b32 s14, s27, 2
	s_waitcnt lgkmcnt(0)
	v_add_f32_e32 v80, v80, v81
	v_lshl_add_u64 v[82:83], s[34:35], 0, v[82:83]
	v_lshl_add_u64 v[82:83], v[82:83], 0, s[14:15]
	s_lshl_b32 s14, s49, 2
	v_lshl_add_u64 v[82:83], v[82:83], 0, s[14:15]
	global_store_dword v[82:83], v80, off
.LBB0_2451:
	s_or_b64 exec, exec, s[6:7]
	v_or_b32_e32 v80, 48, v162
	s_waitcnt lgkmcnt(0)
	v_ashrrev_i32_e32 v81, 31, v80
	v_lshlrev_b64 v[82:83], 10, v[80:81]
	v_readlane_b32 s60, v248, 0
	v_lshl_add_u64 v[86:87], v[82:83], 0, v[160:161]
	v_readlane_b32 s66, v248, 6
	v_readlane_b32 s67, v248, 7
	v_readlane_b32 s6, v249, 43
	v_readlane_b32 s7, v249, 44
	v_lshl_add_u64 v[88:89], v[86:87], 2, s[66:67]
	global_load_dwordx4 v[236:239], v[88:89], off
	global_load_dwordx4 v[240:243], v[88:89], off offset:64
	global_load_dwordx4 v[244:247], v[88:89], off offset:512
	global_load_dwordx4 v[82:85], v[88:89], off offset:576
	v_lshl_add_u64 v[86:87], v[86:87], 1, s[6:7]
	v_readlane_b32 s61, v248, 1
	v_readlane_b32 s62, v248, 2
	v_readlane_b32 s63, v248, 3
	v_readlane_b32 s64, v248, 4
	v_readlane_b32 s65, v248, 5
	s_waitcnt vmcnt(3)
	v_pk_fma_f32 v[76:77], v[76:77], v[100:101], v[236:237]
	v_pk_fma_f32 v[78:79], v[78:79], v[102:103], v[238:239]
	v_pk_mul_f32 v[238:239], v[166:167], v[76:77]
	global_store_dwordx4 v[88:89], v[76:79], off
	v_pk_mul_f32 v[236:237], v[164:165], v[78:79]
	v_cvt_pk_bf16_f32 v238, v238, v239
	s_nop 0
	v_cvt_pk_bf16_f32 v239, v236, v237
	global_store_dwordx2 v[86:87], v[238:239], off
	v_mul_f32_e32 v77, v77, v77
	v_mul_f32_e32 v79, v79, v79
	v_fmac_f32_e32 v77, v76, v76
	v_fmac_f32_e32 v79, v78, v78
	v_add_f32_e32 v76, v77, v79
	s_waitcnt vmcnt(4)
	v_pk_fma_f32 v[72:73], v[72:73], v[108:109], v[240:241]
	v_pk_fma_f32 v[74:75], v[74:75], v[110:111], v[242:243]
	v_pk_mul_f32 v[242:243], v[142:143], v[72:73]
	global_store_dwordx4 v[88:89], v[72:75], off offset:64
	v_pk_mul_f32 v[240:241], v[140:141], v[74:75]
	v_cvt_pk_bf16_f32 v242, v242, v243
	s_nop 0
	v_cvt_pk_bf16_f32 v243, v240, v241
	global_store_dwordx2 v[86:87], v[242:243], off offset:32
	v_mul_f32_e32 v73, v73, v73
	v_mul_f32_e32 v75, v75, v75
	v_fmac_f32_e32 v73, v72, v72
	v_fmac_f32_e32 v75, v74, v74
	v_add_f32_e32 v72, v73, v75
	v_add_f32_e32 v72, v76, v72
	s_waitcnt vmcnt(5)
	v_pk_fma_f32 v[68:69], v[68:69], v[104:105], v[244:245]
	v_pk_fma_f32 v[70:71], v[70:71], v[106:107], v[246:247]
	v_pk_mul_f32 v[246:247], v[138:139], v[68:69]
	global_store_dwordx4 v[88:89], v[68:71], off offset:512
	v_pk_mul_f32 v[244:245], v[136:137], v[70:71]
	v_cvt_pk_bf16_f32 v246, v246, v247
	s_nop 0
	v_cvt_pk_bf16_f32 v247, v244, v245
	global_store_dwordx2 v[86:87], v[246:247], off offset:256
	v_mul_f32_e32 v69, v69, v69
	v_mul_f32_e32 v71, v71, v71
	v_fmac_f32_e32 v69, v68, v68
	v_fmac_f32_e32 v71, v70, v70
	v_add_f32_e32 v68, v69, v71
	v_add_f32_e32 v70, v72, v68
	s_waitcnt vmcnt(6)
	v_pk_fma_f32 v[68:69], v[66:67], v[98:99], v[84:85]
	v_pk_fma_f32 v[66:67], v[64:65], v[96:97], v[82:83]
	v_mul_f32_e32 v65, v69, v69
	v_mul_f32_e32 v64, v67, v67
	v_fmac_f32_e32 v64, v66, v66
	v_fmac_f32_e32 v65, v68, v68
	v_add_f32_e32 v64, v64, v65
	v_add_f32_e32 v64, v70, v64
	ds_bpermute_b32 v65, v207, v64
	global_store_dwordx4 v[88:89], v[66:69], off offset:576
	s_waitcnt lgkmcnt(0)
	v_add_f32_e32 v64, v64, v65
	ds_bpermute_b32 v65, v208, v64
	v_pk_mul_f32 v[66:67], v[132:133], v[66:67]
	v_pk_mul_f32 v[68:69], v[134:135], v[68:69]
	v_cvt_pk_bf16_f32 v66, v66, v67
	s_nop 0
	v_cvt_pk_bf16_f32 v67, v68, v69
	global_store_dwordx2 v[86:87], v[66:67], off offset:288
	s_and_saveexec_b64 s[6:7], s[0:1]
	s_cbranch_execz .LBB0_2453
	v_readlane_b32 s34, v249, 31
	v_lshlrev_b64 v[66:67], 6, v[80:81]
	v_readlane_b32 s35, v249, 32
	s_lshl_b32 s14, s27, 2
	s_waitcnt lgkmcnt(0)
	v_add_f32_e32 v64, v64, v65
	v_lshl_add_u64 v[66:67], s[34:35], 0, v[66:67]
	v_lshl_add_u64 v[66:67], v[66:67], 0, s[14:15]
	s_lshl_b32 s14, s49, 2
	v_lshl_add_u64 v[66:67], v[66:67], 0, s[14:15]
	global_store_dword v[66:67], v64, off
; __device__ __forceinline__ unsigned cvt_pk_bf16(float lo, float hi) { unsigned r; asm volatile("v_cvt_pk_bf16_f32 %0, %1, %2" : "=v"(r) : "v"(lo), "v"(hi)); return r; }
;     __device__ __forceinline__ void operator()(const f32x4 (&acc)[2][2][4][2], const Unit& u, int wr, int wc, int fr, int fq) const {
;     ...
;         for (int ai = 0; ai < 2; ++ai)
; #pragma unroll
;             for (int m = 0; m < 4; ++m) { const int row = row0 + ai * HALF + m * 16; const size_t off = (size_t)row * D + col0;
;                 float ssq = 0.f;
; #pragma unroll
;                 for (int bj = 0; bj < 2; ++bj)
; #pragma unroll
;                     for (int n = 0; n < 2; ++n) { const f32x4 bs = *(const f32x4*)(base + off + bj * HALF + n * 16);
;                         const f32x4 o = bs + gv[bj][n] * acc[ai][bj][m][n];
;                         *(f32x4*)(out + off + bj * HALF + n * 16) = o;
;                         if (FOLD) { ssq += (o.x * o.x + o.y * o.y) + (o.z * o.z + o.w * o.w); const f32x4 q = o * sv[bj][n];
;                             u32x2 w; w.x = cvt_pk_bf16(q.x, q.y); w.y = cvt_pk_bf16(q.z, q.w); *(u32x2*)(U2 + off + bj * HALF + n * 16) = w; } }
;                 if (FOLD) { ssq += __shfl_xor(ssq, 16); ssq += __shfl_xor(ssq, 32);
;                     if (fq == 0) part[(size_t)row * 16 + (u.pn & 3) * 4 + wc] = ssq; } }
.LBB0_2453:
	s_or_b64 exec, exec, s[6:7]
	v_add_u32_e32 v64, 0x80, v162
	s_waitcnt lgkmcnt(0)
	v_ashrrev_i32_e32 v65, 31, v64
	v_lshlrev_b64 v[66:67], 10, v[64:65]
	v_readlane_b32 s60, v248, 0
	v_lshl_add_u64 v[70:71], v[66:67], 0, v[160:161]
	v_readlane_b32 s66, v248, 6
	v_readlane_b32 s67, v248, 7
	v_readlane_b32 s6, v249, 43
	v_readlane_b32 s7, v249, 44
	v_lshl_add_u64 v[72:73], v[70:71], 2, s[66:67]
	global_load_dwordx4 v[236:239], v[72:73], off
	global_load_dwordx4 v[240:243], v[72:73], off offset:64
	global_load_dwordx4 v[244:247], v[72:73], off offset:512
	global_load_dwordx4 v[66:69], v[72:73], off offset:576
	v_lshl_add_u64 v[70:71], v[70:71], 1, s[6:7]
	v_readlane_b32 s61, v248, 1
	v_readlane_b32 s62, v248, 2
	v_readlane_b32 s63, v248, 3
	v_readlane_b32 s64, v248, 4
	v_readlane_b32 s65, v248, 5
	s_waitcnt vmcnt(3)
	v_pk_fma_f32 v[60:61], v[60:61], v[100:101], v[236:237]
	v_pk_fma_f32 v[62:63], v[62:63], v[102:103], v[238:239]
	v_pk_mul_f32 v[238:239], v[166:167], v[60:61]
	global_store_dwordx4 v[72:73], v[60:63], off
	v_pk_mul_f32 v[236:237], v[164:165], v[62:63]
	v_cvt_pk_bf16_f32 v238, v238, v239
	s_nop 0
	v_cvt_pk_bf16_f32 v239, v236, v237
	global_store_dwordx2 v[70:71], v[238:239], off
	v_mul_f32_e32 v61, v61, v61
	v_mul_f32_e32 v63, v63, v63
	v_fmac_f32_e32 v61, v60, v60
	v_fmac_f32_e32 v63, v62, v62
	v_add_f32_e32 v60, v61, v63
	s_waitcnt vmcnt(4)
	v_pk_fma_f32 v[56:57], v[56:57], v[108:109], v[240:241]
	v_pk_fma_f32 v[58:59], v[58:59], v[110:111], v[242:243]
	v_pk_mul_f32 v[242:243], v[142:143], v[56:57]
	global_store_dwordx4 v[72:73], v[56:59], off offset:64
	v_pk_mul_f32 v[240:241], v[140:141], v[58:59]
	v_cvt_pk_bf16_f32 v242, v242, v243
	s_nop 0
	v_cvt_pk_bf16_f32 v243, v240, v241
	global_store_dwordx2 v[70:71], v[242:243], off offset:32
	v_mul_f32_e32 v57, v57, v57
	v_mul_f32_e32 v59, v59, v59
	v_fmac_f32_e32 v57, v56, v56
	v_fmac_f32_e32 v59, v58, v58
	v_add_f32_e32 v56, v57, v59
	v_add_f32_e32 v56, v60, v56
	s_waitcnt vmcnt(5)
	v_pk_fma_f32 v[52:53], v[52:53], v[104:105], v[244:245]
	v_pk_fma_f32 v[54:55], v[54:55], v[106:107], v[246:247]
	v_pk_mul_f32 v[246:247], v[138:139], v[52:53]
	global_store_dwordx4 v[72:73], v[52:55], off offset:512
	v_pk_mul_f32 v[244:245], v[136:137], v[54:55]
	v_cvt_pk_bf16_f32 v246, v246, v247
	s_nop 0
	v_cvt_pk_bf16_f32 v247, v244, v245
	global_store_dwordx2 v[70:71], v[246:247], off offset:256
	v_mul_f32_e32 v53, v53, v53
	v_mul_f32_e32 v55, v55, v55
	v_fmac_f32_e32 v53, v52, v52
	v_fmac_f32_e32 v55, v54, v54
	v_add_f32_e32 v52, v53, v55
	v_add_f32_e32 v54, v56, v52
	s_waitcnt vmcnt(6)
	v_pk_fma_f32 v[52:53], v[50:51], v[98:99], v[68:69]
	v_pk_fma_f32 v[50:51], v[48:49], v[96:97], v[66:67]
	v_mul_f32_e32 v49, v53, v53
	v_mul_f32_e32 v48, v51, v51
	v_fmac_f32_e32 v48, v50, v50
	v_fmac_f32_e32 v49, v52, v52
	v_add_f32_e32 v48, v48, v49
	v_add_f32_e32 v48, v54, v48
	ds_bpermute_b32 v49, v207, v48
	global_store_dwordx4 v[72:73], v[50:53], off offset:576
	s_waitcnt lgkmcnt(0)
	v_add_f32_e32 v48, v48, v49
	ds_bpermute_b32 v49, v208, v48
	v_pk_mul_f32 v[50:51], v[132:133], v[50:51]
	v_pk_mul_f32 v[52:53], v[134:135], v[52:53]
	v_cvt_pk_bf16_f32 v50, v50, v51
	s_nop 0
	v_cvt_pk_bf16_f32 v51, v52, v53
	global_store_dwordx2 v[70:71], v[50:51], off offset:288
	s_and_saveexec_b64 s[6:7], s[0:1]
	s_cbranch_execz .LBB0_2455
	v_readlane_b32 s34, v249, 31
	v_lshlrev_b64 v[50:51], 6, v[64:65]
	v_readlane_b32 s35, v249, 32
	s_lshl_b32 s14, s27, 2
	s_waitcnt lgkmcnt(0)
	v_add_f32_e32 v48, v48, v49
	v_lshl_add_u64 v[50:51], s[34:35], 0, v[50:51]
	v_lshl_add_u64 v[50:51], v[50:51], 0, s[14:15]
	s_lshl_b32 s14, s49, 2
	v_lshl_add_u64 v[50:51], v[50:51], 0, s[14:15]
	global_store_dword v[50:51], v48, off
.LBB0_2455:
	s_or_b64 exec, exec, s[6:7]
	v_add_u32_e32 v48, 0x90, v162
	s_waitcnt lgkmcnt(0)
	v_ashrrev_i32_e32 v49, 31, v48
	v_lshlrev_b64 v[50:51], 10, v[48:49]
	v_readlane_b32 s60, v248, 0
	v_lshl_add_u64 v[54:55], v[50:51], 0, v[160:161]
	v_readlane_b32 s66, v248, 6
	v_readlane_b32 s67, v248, 7
	v_readlane_b32 s6, v249, 43
	v_readlane_b32 s7, v249, 44
	v_lshl_add_u64 v[56:57], v[54:55], 2, s[66:67]
	global_load_dwordx4 v[236:239], v[56:57], off
	global_load_dwordx4 v[240:243], v[56:57], off offset:64
	global_load_dwordx4 v[244:247], v[56:57], off offset:512
	global_load_dwordx4 v[50:53], v[56:57], off offset:576
	v_lshl_add_u64 v[54:55], v[54:55], 1, s[6:7]
	v_readlane_b32 s61, v248, 1
	v_readlane_b32 s62, v248, 2
	v_readlane_b32 s63, v248, 3
	v_readlane_b32 s64, v248, 4
	v_readlane_b32 s65, v248, 5
	s_waitcnt vmcnt(3)
	v_pk_fma_f32 v[44:45], v[44:45], v[100:101], v[236:237]
	v_pk_fma_f32 v[46:47], v[46:47], v[102:103], v[238:239]
	v_pk_mul_f32 v[238:239], v[166:167], v[44:45]
	global_store_dwordx4 v[56:57], v[44:47], off
	v_pk_mul_f32 v[236:237], v[164:165], v[46:47]
	v_cvt_pk_bf16_f32 v238, v238, v239
	s_nop 0
	v_cvt_pk_bf16_f32 v239, v236, v237
	global_store_dwordx2 v[54:55], v[238:239], off
	v_mul_f32_e32 v45, v45, v45
	v_mul_f32_e32 v47, v47, v47
	v_fmac_f32_e32 v45, v44, v44
	v_fmac_f32_e32 v47, v46, v46
	v_add_f32_e32 v44, v45, v47
	s_waitcnt vmcnt(4)
	v_pk_fma_f32 v[40:41], v[40:41], v[108:109], v[240:241]
	v_pk_fma_f32 v[42:43], v[42:43], v[110:111], v[242:243]
	v_pk_mul_f32 v[242:243], v[142:143], v[40:41]
	global_store_dwordx4 v[56:57], v[40:43], off offset:64
	v_pk_mul_f32 v[240:241], v[140:141], v[42:43]
	v_cvt_pk_bf16_f32 v242, v242, v243
	s_nop 0
	v_cvt_pk_bf16_f32 v243, v240, v241
	global_store_dwordx2 v[54:55], v[242:243], off offset:32
	v_mul_f32_e32 v41, v41, v41
	v_mul_f32_e32 v43, v43, v43
	v_fmac_f32_e32 v41, v40, v40
	v_fmac_f32_e32 v43, v42, v42
	v_add_f32_e32 v40, v41, v43
	v_add_f32_e32 v40, v44, v40
	s_waitcnt vmcnt(5)
	v_pk_fma_f32 v[36:37], v[36:37], v[104:105], v[244:245]
	v_pk_fma_f32 v[38:39], v[38:39], v[106:107], v[246:247]
	v_pk_mul_f32 v[246:247], v[138:139], v[36:37]
	global_store_dwordx4 v[56:57], v[36:39], off offset:512
	v_pk_mul_f32 v[244:245], v[136:137], v[38:39]
	v_cvt_pk_bf16_f32 v246, v246, v247
	s_nop 0
	v_cvt_pk_bf16_f32 v247, v244, v245
	global_store_dwordx2 v[54:55], v[246:247], off offset:256
	v_mul_f32_e32 v37, v37, v37
	v_mul_f32_e32 v39, v39, v39
	v_fmac_f32_e32 v37, v36, v36
	v_fmac_f32_e32 v39, v38, v38
	v_add_f32_e32 v36, v37, v39
	v_add_f32_e32 v38, v40, v36
	s_waitcnt vmcnt(6)
	v_pk_fma_f32 v[36:37], v[34:35], v[98:99], v[52:53]
	v_pk_fma_f32 v[34:35], v[32:33], v[96:97], v[50:51]
	v_mul_f32_e32 v33, v37, v37
	v_mul_f32_e32 v32, v35, v35
	v_fmac_f32_e32 v32, v34, v34
	v_fmac_f32_e32 v33, v36, v36
	v_add_f32_e32 v32, v32, v33
	v_add_f32_e32 v32, v38, v32
	ds_bpermute_b32 v33, v207, v32
	global_store_dwordx4 v[56:57], v[34:37], off offset:576
	s_waitcnt lgkmcnt(0)
	v_add_f32_e32 v32, v32, v33
	ds_bpermute_b32 v33, v208, v32
	v_pk_mul_f32 v[34:35], v[132:133], v[34:35]
	v_pk_mul_f32 v[36:37], v[134:135], v[36:37]
	v_cvt_pk_bf16_f32 v34, v34, v35
	s_nop 0
	v_cvt_pk_bf16_f32 v35, v36, v37
	global_store_dwordx2 v[54:55], v[34:35], off offset:288
	s_and_saveexec_b64 s[6:7], s[0:1]
	s_cbranch_execz .LBB0_2457
; __device__ __forceinline__ unsigned cvt_pk_bf16(float lo, float hi) { unsigned r; asm volatile("v_cvt_pk_bf16_f32 %0, %1, %2" : "=v"(r) : "v"(lo), "v"(hi)); return r; }
;     __device__ __forceinline__ void operator()(const f32x4 (&acc)[2][2][4][2], const Unit& u, int wr, int wc, int fr, int fq) const {
;     ...
;         for (int ai = 0; ai < 2; ++ai)
; #pragma unroll
;             for (int m = 0; m < 4; ++m) { const int row = row0 + ai * HALF + m * 16; const size_t off = (size_t)row * D + col0;
;                 float ssq = 0.f;
; #pragma unroll
;                 for (int bj = 0; bj < 2; ++bj)
; #pragma unroll
;                     for (int n = 0; n < 2; ++n) { const f32x4 bs = *(const f32x4*)(base + off + bj * HALF + n * 16);
;                         const f32x4 o = bs + gv[bj][n] * acc[ai][bj][m][n];
;                         *(f32x4*)(out + off + bj * HALF + n * 16) = o;
;                         if (FOLD) { ssq += (o.x * o.x + o.y * o.y) + (o.z * o.z + o.w * o.w); const f32x4 q = o * sv[bj][n];
;                             u32x2 w; w.x = cvt_pk_bf16(q.x, q.y); w.y = cvt_pk_bf16(q.z, q.w); *(u32x2*)(U2 + off + bj * HALF + n * 16) = w; } }
;                 if (FOLD) { ssq += __shfl_xor(ssq, 16); ssq += __shfl_xor(ssq, 32);
;                     if (fq == 0) part[(size_t)row * 16 + (u.pn & 3) * 4 + wc] = ssq; } }
	v_readlane_b32 s34, v249, 31
	v_lshlrev_b64 v[34:35], 6, v[48:49]
	v_readlane_b32 s35, v249, 32
	s_lshl_b32 s14, s27, 2
	s_waitcnt lgkmcnt(0)
	v_add_f32_e32 v32, v32, v33
	v_lshl_add_u64 v[34:35], s[34:35], 0, v[34:35]
	v_lshl_add_u64 v[34:35], v[34:35], 0, s[14:15]
	s_lshl_b32 s14, s49, 2
	v_lshl_add_u64 v[34:35], v[34:35], 0, s[14:15]
	global_store_dword v[34:35], v32, off
.LBB0_2457:
	s_or_b64 exec, exec, s[6:7]
	v_add_u32_e32 v32, 0xa0, v162
	s_waitcnt lgkmcnt(0)
	v_ashrrev_i32_e32 v33, 31, v32
	v_lshlrev_b64 v[34:35], 10, v[32:33]
	v_readlane_b32 s60, v248, 0
	v_lshl_add_u64 v[38:39], v[34:35], 0, v[160:161]
	v_readlane_b32 s66, v248, 6
	v_readlane_b32 s67, v248, 7
	v_readlane_b32 s6, v249, 43
	v_readlane_b32 s7, v249, 44
	v_lshl_add_u64 v[40:41], v[38:39], 2, s[66:67]
	global_load_dwordx4 v[236:239], v[40:41], off
	global_load_dwordx4 v[240:243], v[40:41], off offset:64
	global_load_dwordx4 v[244:247], v[40:41], off offset:512
	global_load_dwordx4 v[34:37], v[40:41], off offset:576
	v_lshl_add_u64 v[38:39], v[38:39], 1, s[6:7]
	v_readlane_b32 s61, v248, 1
	v_readlane_b32 s62, v248, 2
	v_readlane_b32 s63, v248, 3
	v_readlane_b32 s64, v248, 4
	v_readlane_b32 s65, v248, 5
	s_waitcnt vmcnt(3)
	v_pk_fma_f32 v[28:29], v[28:29], v[100:101], v[236:237]
	v_pk_fma_f32 v[30:31], v[30:31], v[102:103], v[238:239]
	v_pk_mul_f32 v[238:239], v[166:167], v[28:29]
	global_store_dwordx4 v[40:41], v[28:31], off
	v_pk_mul_f32 v[236:237], v[164:165], v[30:31]
	v_cvt_pk_bf16_f32 v238, v238, v239
	s_nop 0
	v_cvt_pk_bf16_f32 v239, v236, v237
	global_store_dwordx2 v[38:39], v[238:239], off
	v_mul_f32_e32 v29, v29, v29
	v_mul_f32_e32 v31, v31, v31
	v_fmac_f32_e32 v29, v28, v28
	v_fmac_f32_e32 v31, v30, v30
	v_add_f32_e32 v28, v29, v31
	s_waitcnt vmcnt(4)
	v_pk_fma_f32 v[24:25], v[24:25], v[108:109], v[240:241]
	v_pk_fma_f32 v[26:27], v[26:27], v[110:111], v[242:243]
	v_pk_mul_f32 v[242:243], v[142:143], v[24:25]
	global_store_dwordx4 v[40:41], v[24:27], off offset:64
	v_pk_mul_f32 v[240:241], v[140:141], v[26:27]
	v_cvt_pk_bf16_f32 v242, v242, v243
	s_nop 0
	v_cvt_pk_bf16_f32 v243, v240, v241
	global_store_dwordx2 v[38:39], v[242:243], off offset:32
	v_mul_f32_e32 v25, v25, v25
	v_mul_f32_e32 v27, v27, v27
	v_fmac_f32_e32 v25, v24, v24
	v_fmac_f32_e32 v27, v26, v26
	v_add_f32_e32 v24, v25, v27
	v_add_f32_e32 v24, v28, v24
	s_waitcnt vmcnt(5)
	v_pk_fma_f32 v[20:21], v[20:21], v[104:105], v[244:245]
	v_pk_fma_f32 v[22:23], v[22:23], v[106:107], v[246:247]
	v_pk_mul_f32 v[246:247], v[138:139], v[20:21]
	global_store_dwordx4 v[40:41], v[20:23], off offset:512
	v_pk_mul_f32 v[244:245], v[136:137], v[22:23]
	v_cvt_pk_bf16_f32 v246, v246, v247
	s_nop 0
	v_cvt_pk_bf16_f32 v247, v244, v245
	global_store_dwordx2 v[38:39], v[246:247], off offset:256
	v_mul_f32_e32 v21, v21, v21
	v_mul_f32_e32 v23, v23, v23
	v_fmac_f32_e32 v21, v20, v20
	v_fmac_f32_e32 v23, v22, v22
	v_add_f32_e32 v20, v21, v23
	v_add_f32_e32 v22, v24, v20
	s_waitcnt vmcnt(6)
	v_pk_fma_f32 v[20:21], v[18:19], v[98:99], v[36:37]
	v_pk_fma_f32 v[18:19], v[16:17], v[96:97], v[34:35]
	v_mul_f32_e32 v17, v21, v21
	v_mul_f32_e32 v16, v19, v19
	v_fmac_f32_e32 v16, v18, v18
	v_fmac_f32_e32 v17, v20, v20
	v_add_f32_e32 v16, v16, v17
	v_add_f32_e32 v16, v22, v16
	ds_bpermute_b32 v17, v207, v16
	global_store_dwordx4 v[40:41], v[18:21], off offset:576
	s_waitcnt lgkmcnt(0)
	v_add_f32_e32 v16, v16, v17
	ds_bpermute_b32 v17, v208, v16
	v_pk_mul_f32 v[18:19], v[132:133], v[18:19]
	v_pk_mul_f32 v[20:21], v[134:135], v[20:21]
	v_cvt_pk_bf16_f32 v18, v18, v19
	s_nop 0
	v_cvt_pk_bf16_f32 v19, v20, v21
	global_store_dwordx2 v[38:39], v[18:19], off offset:288
	s_and_saveexec_b64 s[6:7], s[0:1]
	s_cbranch_execz .LBB0_2459
	v_readlane_b32 s34, v249, 31
	v_lshlrev_b64 v[18:19], 6, v[32:33]
	v_readlane_b32 s35, v249, 32
	s_lshl_b32 s14, s27, 2
	s_waitcnt lgkmcnt(0)
	v_add_f32_e32 v16, v16, v17
	v_lshl_add_u64 v[18:19], s[34:35], 0, v[18:19]
	v_lshl_add_u64 v[18:19], v[18:19], 0, s[14:15]
	s_lshl_b32 s14, s49, 2
	v_lshl_add_u64 v[18:19], v[18:19], 0, s[14:15]
	global_store_dword v[18:19], v16, off
; __device__ __forceinline__ unsigned cvt_pk_bf16(float lo, float hi) { unsigned r; asm volatile("v_cvt_pk_bf16_f32 %0, %1, %2" : "=v"(r) : "v"(lo), "v"(hi)); return r; }
;     __device__ __forceinline__ void operator()(const f32x4 (&acc)[2][2][4][2], const Unit& u, int wr, int wc, int fr, int fq) const {
;     ...
;         for (int ai = 0; ai < 2; ++ai)
; #pragma unroll
;             for (int m = 0; m < 4; ++m) { const int row = row0 + ai * HALF + m * 16; const size_t off = (size_t)row * D + col0;
;                 float ssq = 0.f;
; #pragma unroll
;                 for (int bj = 0; bj < 2; ++bj)
; #pragma unroll
;                     for (int n = 0; n < 2; ++n) { const f32x4 bs = *(const f32x4*)(base + off + bj * HALF + n * 16);
;                         const f32x4 o = bs + gv[bj][n] * acc[ai][bj][m][n];
;                         *(f32x4*)(out + off + bj * HALF + n * 16) = o;
;                         if (FOLD) { ssq += (o.x * o.x + o.y * o.y) + (o.z * o.z + o.w * o.w); const f32x4 q = o * sv[bj][n];
;                             u32x2 w; w.x = cvt_pk_bf16(q.x, q.y); w.y = cvt_pk_bf16(q.z, q.w); *(u32x2*)(U2 + off + bj * HALF + n * 16) = w; } }
;                 if (FOLD) { ssq += __shfl_xor(ssq, 16); ssq += __shfl_xor(ssq, 32);
;                     if (fq == 0) part[(size_t)row * 16 + (u.pn & 3) * 4 + wc] = ssq; } }
.LBB0_2459:
	s_or_b64 exec, exec, s[6:7]
	v_add_u32_e32 v16, 0xb0, v162
	s_waitcnt lgkmcnt(0)
	v_ashrrev_i32_e32 v17, 31, v16
	v_lshlrev_b64 v[18:19], 10, v[16:17]
	v_readlane_b32 s60, v248, 0
	v_lshl_add_u64 v[22:23], v[18:19], 0, v[160:161]
	v_readlane_b32 s66, v248, 6
	v_readlane_b32 s67, v248, 7
	v_readlane_b32 s6, v249, 43
	v_readlane_b32 s7, v249, 44
	v_lshl_add_u64 v[24:25], v[22:23], 2, s[66:67]
	global_load_dwordx4 v[236:239], v[24:25], off
	global_load_dwordx4 v[240:243], v[24:25], off offset:64
	global_load_dwordx4 v[244:247], v[24:25], off offset:512
	global_load_dwordx4 v[18:21], v[24:25], off offset:576
	v_lshl_add_u64 v[22:23], v[22:23], 1, s[6:7]
	v_readlane_b32 s61, v248, 1
	v_readlane_b32 s62, v248, 2
	v_readlane_b32 s63, v248, 3
	v_readlane_b32 s64, v248, 4
	v_readlane_b32 s65, v248, 5
	s_waitcnt vmcnt(3)
	v_pk_fma_f32 v[12:13], v[12:13], v[100:101], v[236:237]
	v_pk_fma_f32 v[14:15], v[14:15], v[102:103], v[238:239]
	v_pk_mul_f32 v[238:239], v[166:167], v[12:13]
	global_store_dwordx4 v[24:25], v[12:15], off
	v_pk_mul_f32 v[236:237], v[164:165], v[14:15]
	v_cvt_pk_bf16_f32 v238, v238, v239
	s_nop 0
	v_cvt_pk_bf16_f32 v239, v236, v237
	global_store_dwordx2 v[22:23], v[238:239], off
	v_mul_f32_e32 v13, v13, v13
	v_mul_f32_e32 v15, v15, v15
	v_fmac_f32_e32 v13, v12, v12
	v_fmac_f32_e32 v15, v14, v14
	v_add_f32_e32 v12, v13, v15
	s_waitcnt vmcnt(4)
	v_pk_fma_f32 v[8:9], v[8:9], v[108:109], v[240:241]
	v_pk_fma_f32 v[10:11], v[10:11], v[110:111], v[242:243]
	v_pk_mul_f32 v[242:243], v[142:143], v[8:9]
	global_store_dwordx4 v[24:25], v[8:11], off offset:64
	v_pk_mul_f32 v[240:241], v[140:141], v[10:11]
	v_cvt_pk_bf16_f32 v242, v242, v243
	s_nop 0
	v_cvt_pk_bf16_f32 v243, v240, v241
	global_store_dwordx2 v[22:23], v[242:243], off offset:32
	v_mul_f32_e32 v9, v9, v9
	v_mul_f32_e32 v11, v11, v11
	v_fmac_f32_e32 v9, v8, v8
	v_fmac_f32_e32 v11, v10, v10
	v_add_f32_e32 v8, v9, v11
	v_add_f32_e32 v8, v12, v8
	s_waitcnt vmcnt(5)
	v_pk_fma_f32 v[4:5], v[4:5], v[104:105], v[244:245]
	v_pk_fma_f32 v[6:7], v[6:7], v[106:107], v[246:247]
	v_pk_mul_f32 v[246:247], v[138:139], v[4:5]
	global_store_dwordx4 v[24:25], v[4:7], off offset:512
	v_pk_mul_f32 v[244:245], v[136:137], v[6:7]
	v_cvt_pk_bf16_f32 v246, v246, v247
	s_nop 0
	v_cvt_pk_bf16_f32 v247, v244, v245
	global_store_dwordx2 v[22:23], v[246:247], off offset:256
	v_mul_f32_e32 v5, v5, v5
	v_mul_f32_e32 v7, v7, v7
	v_fmac_f32_e32 v5, v4, v4
	v_fmac_f32_e32 v7, v6, v6
	v_add_f32_e32 v4, v5, v7
	v_add_f32_e32 v6, v8, v4
	s_waitcnt vmcnt(6)
	v_pk_fma_f32 v[4:5], v[2:3], v[98:99], v[20:21]
	v_pk_fma_f32 v[2:3], v[0:1], v[96:97], v[18:19]
	v_mul_f32_e32 v1, v5, v5
	v_mul_f32_e32 v0, v3, v3
	v_fmac_f32_e32 v0, v2, v2
	v_fmac_f32_e32 v1, v4, v4
	v_add_f32_e32 v0, v0, v1
	v_add_f32_e32 v0, v6, v0
	ds_bpermute_b32 v1, v207, v0
	global_store_dwordx4 v[24:25], v[2:5], off offset:576
	s_waitcnt lgkmcnt(0)
	v_add_f32_e32 v0, v0, v1
	ds_bpermute_b32 v1, v208, v0
	v_pk_mul_f32 v[2:3], v[132:133], v[2:3]
	v_pk_mul_f32 v[4:5], v[134:135], v[4:5]
	v_cvt_pk_bf16_f32 v2, v2, v3
	s_nop 0
	v_cvt_pk_bf16_f32 v3, v4, v5
	global_store_dwordx2 v[22:23], v[2:3], off offset:288
	s_and_saveexec_b64 s[6:7], s[0:1]
	s_cbranch_execz .LBB0_2461
	v_readlane_b32 s34, v249, 31
	v_lshlrev_b64 v[2:3], 6, v[16:17]
	v_readlane_b32 s35, v249, 32
	s_lshl_b32 s14, s27, 2
	s_waitcnt lgkmcnt(0)
	v_add_f32_e32 v0, v0, v1
	v_lshl_add_u64 v[2:3], s[34:35], 0, v[2:3]
	v_lshl_add_u64 v[2:3], v[2:3], 0, s[14:15]
	s_lshl_b32 s14, s49, 2
	v_lshl_add_u64 v[2:3], v[2:3], 0, s[14:15]
	global_store_dword v[2:3], v0, off

;     __device__ __forceinline__ void operator()(const f32x4 (&acc)[2][2][4][2], const Unit& u, int wr, int wc, int fr, int fq) const {
;         const int row0 = u.pm * BM + wr * 64 + fr, col0 = u.pn * BM + wc * 32 + 4 * fq;
;         const float* gp = gate + (size_t)(u.pm >> 4) * NMOD;
;         f32x4 gv[2][2], sv[2][2];
; #pragma unroll
;         for (int bj = 0; bj < 2; ++bj)
; #pragma unroll
;             for (int n = 0; n < 2; ++n) { gv[bj][n] = *(const f32x4*)(gp + col0 + bj * HALF + n * 16) * (HALFSC ? 0.5f : 1.0f);
;                 if (FOLD) sv[bj][n] = *(const f32x4*)(scn + (size_t)(u.pm >> 4) * NMOD + col0 + bj * HALF + n * 16) + 1.0f; }
; #pragma unroll
;         for (int ai = 0; ai < 2; ++ai)
; #pragma unroll
;             for (int m = 0; m < 4; ++m) { const int row = row0 + ai * HALF + m * 16; const size_t off = (size_t)row * D + col0;
;                 float ssq = 0.f;
; #pragma unroll
;                 for (int bj = 0; bj < 2; ++bj)
; #pragma unroll
;                     for (int n = 0; n < 2; ++n) { const f32x4 bs = *(const f32x4*)(base + off + bj * HALF + n * 16);
;                         const f32x4 o = bs + gv[bj][n] * acc[ai][bj][m][n];
;                         *(f32x4*)(out + off + bj * HALF + n * 16) = o;
.LBB0_2613:
	s_ashr_i32 s22, s46, 4
	v_lshl_or_b32 v144, s47, 8, v166
	s_mul_hi_i32 s23, s22, 0x9000
	s_mul_i32 s22, s22, 0x9000
	s_add_u32 s22, s36, s22
	v_ashrrev_i32_e32 v145, 31, v144
	s_addc_u32 s23, s37, s23
	v_lshlrev_b64 v[162:163], 2, v[144:145]
	v_lshl_add_u64 v[160:161], s[22:23], 0, v[162:163]
	global_load_dwordx4 v[144:147], v[160:161], off
	v_lshl_add_u32 v174, s46, 8, v164
	v_readlane_b32 s48, v248, 0
	v_ashrrev_i32_e32 v175, 31, v174
	v_readlane_b32 s54, v248, 6
	v_readlane_b32 s55, v248, 7
	s_mov_b64 s[22:23], s[54:55]
	v_readlane_b32 s49, v248, 1
	v_readlane_b32 s50, v248, 2
	v_readlane_b32 s51, v248, 3
	v_readlane_b32 s52, v248, 4
	v_readlane_b32 s53, v248, 5
	s_waitcnt vmcnt(0)
	v_pk_mul_f32 v[156:157], v[146:147], 0.5 op_sel_hi:[1,0]
	v_pk_mul_f32 v[158:159], v[144:145], 0.5 op_sel_hi:[1,0]
	global_load_dwordx4 v[144:147], v[160:161], off offset:64
	s_waitcnt vmcnt(0)
	v_pk_mul_f32 v[152:153], v[146:147], 0.5 op_sel_hi:[1,0]
	v_pk_mul_f32 v[154:155], v[144:145], 0.5 op_sel_hi:[1,0]
	global_load_dwordx4 v[144:147], v[160:161], off offset:512
	s_waitcnt vmcnt(0)
	v_pk_mul_f32 v[148:149], v[146:147], 0.5 op_sel_hi:[1,0]
	v_pk_mul_f32 v[150:151], v[144:145], 0.5 op_sel_hi:[1,0]
	global_load_dwordx4 v[144:147], v[160:161], off offset:576
	v_lshlrev_b64 v[160:161], 12, v[174:175]
	v_lshl_add_u64 v[160:161], s[22:23], 0, v[160:161]
	v_lshl_add_u64 v[160:161], v[160:161], 0, v[162:163]
	global_load_dwordx4 v[216:219], v[160:161], off
	global_load_dwordx4 v[220:223], v[160:161], off offset:64
	global_load_dwordx4 v[236:239], v[160:161], off offset:512
	global_load_dwordx4 v[240:243], v[160:161], off offset:576
	s_waitcnt vmcnt(3)
	v_pk_mul_f32 v[146:147], v[146:147], 0.5 op_sel_hi:[1,0]
	v_pk_mul_f32 v[144:145], v[144:145], 0.5 op_sel_hi:[1,0]
	v_pk_fma_f32 v[126:127], v[126:127], v[156:157], v[218:219]
	v_pk_fma_f32 v[124:125], v[124:125], v[158:159], v[216:217]
	global_store_dwordx4 v[160:161], v[124:127], off
	s_waitcnt vmcnt(3)
	v_pk_fma_f32 v[122:123], v[122:123], v[152:153], v[222:223]
	v_pk_fma_f32 v[120:121], v[120:121], v[154:155], v[220:221]
	global_store_dwordx4 v[160:161], v[120:123], off offset:64
	s_waitcnt vmcnt(3)
	v_pk_fma_f32 v[118:119], v[118:119], v[148:149], v[238:239]
	v_pk_fma_f32 v[116:117], v[116:117], v[150:151], v[236:237]
	global_store_dwordx4 v[160:161], v[116:119], off offset:512
	s_waitcnt vmcnt(3)
	v_pk_fma_f32 v[114:115], v[114:115], v[146:147], v[242:243]
	v_pk_fma_f32 v[112:113], v[112:113], v[144:145], v[240:241]
	global_store_dwordx4 v[160:161], v[112:115], off offset:576
	s_nop 1
	v_or_b32_e32 v112, 16, v174
	v_ashrrev_i32_e32 v113, 31, v112
	v_lshlrev_b64 v[112:113], 12, v[112:113]
	v_lshl_add_u64 v[112:113], s[22:23], 0, v[112:113]
	v_lshl_add_u64 v[116:117], v[112:113], 0, v[162:163]
	global_load_dwordx4 v[216:219], v[116:117], off
	global_load_dwordx4 v[220:223], v[116:117], off offset:64
	global_load_dwordx4 v[236:239], v[116:117], off offset:512
	global_load_dwordx4 v[240:243], v[116:117], off offset:576
	s_waitcnt vmcnt(3)
	v_pk_fma_f32 v[110:111], v[110:111], v[156:157], v[218:219]
	v_pk_fma_f32 v[108:109], v[108:109], v[158:159], v[216:217]
	global_store_dwordx4 v[116:117], v[108:111], off
	s_waitcnt vmcnt(3)
	v_pk_fma_f32 v[106:107], v[106:107], v[152:153], v[222:223]
	v_pk_fma_f32 v[104:105], v[104:105], v[154:155], v[220:221]
	global_store_dwordx4 v[116:117], v[104:107], off offset:64
	s_waitcnt vmcnt(3)
	v_pk_fma_f32 v[102:103], v[102:103], v[148:149], v[238:239]
	v_pk_fma_f32 v[100:101], v[100:101], v[150:151], v[236:237]
	global_store_dwordx4 v[116:117], v[100:103], off offset:512
	s_waitcnt vmcnt(3)
	v_pk_fma_f32 v[98:99], v[98:99], v[146:147], v[242:243]
	v_pk_fma_f32 v[96:97], v[96:97], v[144:145], v[240:241]
	global_store_dwordx4 v[116:117], v[96:99], off offset:576
	s_nop 1
	v_or_b32_e32 v96, 32, v174
	v_ashrrev_i32_e32 v97, 31, v96
	v_lshlrev_b64 v[96:97], 12, v[96:97]
	v_lshl_add_u64 v[96:97], s[22:23], 0, v[96:97]
	v_lshl_add_u64 v[100:101], v[96:97], 0, v[162:163]
	global_load_dwordx4 v[216:219], v[100:101], off
	global_load_dwordx4 v[220:223], v[100:101], off offset:64
	global_load_dwordx4 v[236:239], v[100:101], off offset:512
	global_load_dwordx4 v[240:243], v[100:101], off offset:576
	s_waitcnt vmcnt(3)
	v_pk_fma_f32 v[94:95], v[94:95], v[156:157], v[218:219]
	v_pk_fma_f32 v[92:93], v[92:93], v[158:159], v[216:217]
	global_store_dwordx4 v[100:101], v[92:95], off
	s_waitcnt vmcnt(3)
	v_pk_fma_f32 v[90:91], v[90:91], v[152:153], v[222:223]
	v_pk_fma_f32 v[88:89], v[88:89], v[154:155], v[220:221]
	global_store_dwordx4 v[100:101], v[88:91], off offset:64
	s_waitcnt vmcnt(3)
	v_pk_fma_f32 v[86:87], v[86:87], v[148:149], v[238:239]
	v_pk_fma_f32 v[84:85], v[84:85], v[150:151], v[236:237]
	global_store_dwordx4 v[100:101], v[84:87], off offset:512
	s_waitcnt vmcnt(3)
	v_pk_fma_f32 v[82:83], v[82:83], v[146:147], v[242:243]
	v_pk_fma_f32 v[80:81], v[80:81], v[144:145], v[240:241]
	global_store_dwordx4 v[100:101], v[80:83], off offset:576
	s_nop 1
	v_or_b32_e32 v80, 48, v174
	v_ashrrev_i32_e32 v81, 31, v80
	v_lshlrev_b64 v[80:81], 12, v[80:81]
	v_lshl_add_u64 v[80:81], s[22:23], 0, v[80:81]
	v_lshl_add_u64 v[84:85], v[80:81], 0, v[162:163]
	global_load_dwordx4 v[216:219], v[84:85], off
	global_load_dwordx4 v[220:223], v[84:85], off offset:64
	global_load_dwordx4 v[236:239], v[84:85], off offset:512
	global_load_dwordx4 v[240:243], v[84:85], off offset:576
	s_mov_b64 s[22:23], 0x80000
	s_waitcnt vmcnt(3)
;     __device__ __forceinline__ void operator()(const f32x4 (&acc)[2][2][4][2], const Unit& u, int wr, int wc, int fr, int fq) const {
;     ...
;             for (int m = 0; m < 4; ++m) { const int row = row0 + ai * HALF + m * 16; const size_t off = (size_t)row * D + col0;
;                 float ssq = 0.f;
; #pragma unroll
;                 for (int bj = 0; bj < 2; ++bj)
; #pragma unroll
;                     for (int n = 0; n < 2; ++n) { const f32x4 bs = *(const f32x4*)(base + off + bj * HALF + n * 16);
;                         const f32x4 o = bs + gv[bj][n] * acc[ai][bj][m][n];
;                         *(f32x4*)(out + off + bj * HALF + n * 16) = o;
	v_pk_fma_f32 v[78:79], v[78:79], v[156:157], v[218:219]
	v_pk_fma_f32 v[76:77], v[76:77], v[158:159], v[216:217]
	global_store_dwordx4 v[84:85], v[76:79], off
	s_waitcnt vmcnt(3)
	v_pk_fma_f32 v[74:75], v[74:75], v[152:153], v[222:223]
	v_pk_fma_f32 v[72:73], v[72:73], v[154:155], v[220:221]
	global_store_dwordx4 v[84:85], v[72:75], off offset:64
	s_waitcnt vmcnt(3)
	v_pk_fma_f32 v[70:71], v[70:71], v[148:149], v[238:239]
	v_pk_fma_f32 v[68:69], v[68:69], v[150:151], v[236:237]
	global_store_dwordx4 v[84:85], v[68:71], off offset:512
	s_waitcnt vmcnt(3)
	v_pk_fma_f32 v[64:65], v[64:65], v[144:145], v[240:241]
	v_lshl_add_u64 v[68:69], v[160:161], 0, s[22:23]
	s_mov_b32 s22, 0x80000
	v_pk_fma_f32 v[66:67], v[66:67], v[146:147], v[242:243]
	v_add_co_u32_e32 v70, vcc, s22, v160
	global_store_dwordx4 v[84:85], v[64:67], off offset:576
	s_nop 0
	v_addc_co_u32_e32 v71, vcc, 0, v161, vcc
	global_load_dwordx4 v[216:219], v[70:71], off
	global_load_dwordx4 v[220:223], v[68:69], off offset:64
	global_load_dwordx4 v[236:239], v[68:69], off offset:512
	global_load_dwordx4 v[240:243], v[68:69], off offset:576
	s_mov_b64 s[22:23], 0x90000
	s_waitcnt vmcnt(3)
	v_pk_fma_f32 v[62:63], v[62:63], v[156:157], v[218:219]
	v_pk_fma_f32 v[60:61], v[60:61], v[158:159], v[216:217]
	global_store_dwordx4 v[70:71], v[60:63], off
	s_waitcnt vmcnt(3)
	v_pk_fma_f32 v[58:59], v[58:59], v[152:153], v[222:223]
	v_pk_fma_f32 v[56:57], v[56:57], v[154:155], v[220:221]
	global_store_dwordx4 v[68:69], v[56:59], off offset:64
	s_waitcnt vmcnt(3)
	v_pk_fma_f32 v[54:55], v[54:55], v[148:149], v[238:239]
	v_pk_fma_f32 v[52:53], v[52:53], v[150:151], v[236:237]
	global_store_dwordx4 v[68:69], v[52:55], off offset:512
	s_waitcnt vmcnt(3)
	v_pk_fma_f32 v[50:51], v[50:51], v[146:147], v[242:243]
	v_pk_fma_f32 v[48:49], v[48:49], v[144:145], v[240:241]
	global_store_dwordx4 v[68:69], v[48:51], off offset:576
	s_nop 1
	v_lshl_add_u64 v[48:49], v[160:161], 0, s[22:23]
	s_mov_b32 s22, 0x90000
	v_add_co_u32_e32 v54, vcc, s22, v160
	s_mov_b64 s[22:23], 0xa0000
	s_nop 0
	v_addc_co_u32_e32 v55, vcc, 0, v161, vcc
	global_load_dwordx4 v[216:219], v[54:55], off
	global_load_dwordx4 v[220:223], v[48:49], off offset:64
	global_load_dwordx4 v[236:239], v[48:49], off offset:512
	global_load_dwordx4 v[240:243], v[48:49], off offset:576
	s_waitcnt vmcnt(3)
	v_pk_fma_f32 v[46:47], v[46:47], v[156:157], v[218:219]
	v_pk_fma_f32 v[44:45], v[44:45], v[158:159], v[216:217]
	global_store_dwordx4 v[54:55], v[44:47], off
	s_waitcnt vmcnt(3)
	v_pk_fma_f32 v[42:43], v[42:43], v[152:153], v[222:223]
	v_pk_fma_f32 v[40:41], v[40:41], v[154:155], v[220:221]
	global_store_dwordx4 v[48:49], v[40:43], off offset:64
	s_waitcnt vmcnt(3)
	v_pk_fma_f32 v[38:39], v[38:39], v[148:149], v[238:239]
	v_pk_fma_f32 v[36:37], v[36:37], v[150:151], v[236:237]
	global_store_dwordx4 v[48:49], v[36:39], off offset:512
	s_waitcnt vmcnt(3)
	v_pk_fma_f32 v[32:33], v[32:33], v[144:145], v[240:241]
	v_lshl_add_u64 v[36:37], v[160:161], 0, s[22:23]
	s_mov_b32 s22, 0xa0000
	v_pk_fma_f32 v[34:35], v[34:35], v[146:147], v[242:243]
	v_add_co_u32_e32 v38, vcc, s22, v160
	global_store_dwordx4 v[48:49], v[32:35], off offset:576
	s_nop 0
	v_addc_co_u32_e32 v39, vcc, 0, v161, vcc
	global_load_dwordx4 v[216:219], v[38:39], off
	global_load_dwordx4 v[220:223], v[36:37], off offset:64
	global_load_dwordx4 v[236:239], v[36:37], off offset:512
	global_load_dwordx4 v[240:243], v[36:37], off offset:576
	s_mov_b64 s[22:23], 0xb0000
	s_waitcnt vmcnt(3)
	v_pk_fma_f32 v[30:31], v[30:31], v[156:157], v[218:219]
	v_pk_fma_f32 v[28:29], v[28:29], v[158:159], v[216:217]
	global_store_dwordx4 v[38:39], v[28:31], off
	s_waitcnt vmcnt(3)
	v_pk_fma_f32 v[26:27], v[26:27], v[152:153], v[222:223]
	v_pk_fma_f32 v[24:25], v[24:25], v[154:155], v[220:221]
	global_store_dwordx4 v[36:37], v[24:27], off offset:64
	s_waitcnt vmcnt(3)
	v_pk_fma_f32 v[22:23], v[22:23], v[148:149], v[238:239]
	v_pk_fma_f32 v[20:21], v[20:21], v[150:151], v[236:237]
	global_store_dwordx4 v[36:37], v[20:23], off offset:512
	s_waitcnt vmcnt(3)
	v_pk_fma_f32 v[18:19], v[18:19], v[146:147], v[242:243]
	v_pk_fma_f32 v[16:17], v[16:17], v[144:145], v[240:241]
	global_store_dwordx4 v[36:37], v[16:19], off offset:576
	s_nop 1
	v_lshl_add_u64 v[16:17], v[160:161], 0, s[22:23]
	s_mov_b32 s22, 0xb0000
	v_add_co_u32_e32 v22, vcc, s22, v160
	s_mov_b64 s[22:23], -1
	s_nop 0
	v_addc_co_u32_e32 v23, vcc, 0, v161, vcc
	global_load_dwordx4 v[216:219], v[22:23], off
	global_load_dwordx4 v[220:223], v[16:17], off offset:64
	global_load_dwordx4 v[236:239], v[16:17], off offset:512
	global_load_dwordx4 v[240:243], v[16:17], off offset:576
	s_and_b64 vcc, exec, s[0:1]
	s_waitcnt vmcnt(3)
	v_pk_fma_f32 v[14:15], v[14:15], v[156:157], v[218:219]
	v_pk_fma_f32 v[12:13], v[12:13], v[158:159], v[216:217]
	global_store_dwordx4 v[22:23], v[12:15], off
	s_waitcnt vmcnt(3)
	v_pk_fma_f32 v[10:11], v[10:11], v[152:153], v[222:223]
	v_pk_fma_f32 v[8:9], v[8:9], v[154:155], v[220:221]
	global_store_dwordx4 v[16:17], v[8:11], off offset:64
	s_waitcnt vmcnt(3)
	v_pk_fma_f32 v[6:7], v[6:7], v[148:149], v[238:239]
	v_pk_fma_f32 v[4:5], v[4:5], v[150:151], v[236:237]
	global_store_dwordx4 v[16:17], v[4:7], off offset:512
	s_waitcnt vmcnt(3)
	v_pk_fma_f32 v[2:3], v[2:3], v[146:147], v[242:243]
	v_pk_fma_f32 v[0:1], v[0:1], v[144:145], v[240:241]
	global_store_dwordx4 v[16:17], v[0:3], off offset:576
	s_cbranch_vccnz .LBB0_2597
	s_andn2_b64 vcc, exec, s[10:11]
	s_cbranch_vccnz .LBB0_2596
	s_barrier
	s_branch .LBB0_2596
